# plus: useless tail staging loads of a workgroup's last unit collapsed to one cache line each
# baseline (speedup 1.0000x reference)
;   __device__ __forceinline__ bool next(int i,AttnUnit&u)const{ const int p=vcu+(i>>1)*grid; if(p>=BATCH*NHEAD*4)return false; const int q=(p&31)+32*(p>>8), s=(q<32)?(q&3):(3-(q&3)); u.bh=((p>>5)&7)*NHEAD+((q<32)?(q>>2):(NHEAD-1-((q-32)>>2)));     u.qb=(i&1)?s:(NQB-1-s); u.reuse=i&1; return true; }
;     __host__ __device__ __forceinline__ bool next(int i, Unit& u) const {
;         const long L = (long)i * G + c; if (L >= nwg) return false;
;         int wgid = (int)L; { const int q = nwg / NXCD, r = nwg % NXCD, xcd = wgid % NXCD, off = wgid / NXCD; wgid = (xcd < r ? xcd * (q + 1) : r * (q + 1) + (xcd - r) * q) + off; }
;         const int nig = WGM * nN, gid = wgid / nig, fm = gid * WGM, gsz = (nM - fm) < WGM ? (nM - fm) : WGM;
;         u.pm = fm + ((wgid % nig) % gsz); u.pn = (wgid % nig) / gsz; return true;
; template <class Epi, class Sched, bool ALIGN_EPI = false, bool SP2 = false>
; __device__ __forceinline__ void gemm_phase(PG8_LAS unsigned char* lds, const Gemm g, const Sched& S, const Epi& E, const int tid_in) {
;     ...
;         const bool has_next = S.next(ui + 1, nxt);
;         const char* nA = has_next ? (const char*)g.A + (size_t)nxt.pm * tstepA + (size_t)(nxt.pm >> 3) * g.abx : cA; const char* nB = has_next ? (const char*)g.Bt + (size_t)nxt.pn * tstepB : cB;
.LBB0_217:
	s_add_i32 s66, s66, 1
	v_readlane_b32 s4, v253, 16
	s_mul_i32 s4, s66, s4
	s_mul_hi_u32 s5, s66, s3
	s_add_i32 s5, s5, s4
	s_mul_i32 s4, s66, s3
	s_add_u32 s4, s4, s2
	s_addc_u32 s5, s5, s33
	v_mov_b64_e32 v[0:1], 0x400
	v_cmp_lt_i64_e64 s[40:41], s[4:5], v[0:1]
	s_nop 3
	s_mov_b32 s100, s40
	v_mov_b64_e32 v[0:1], 0x3ff
	v_cmp_gt_i64_e32 vcc, s[4:5], v[0:1]
	s_cbranch_vccnz .LBB0_223
	s_ashr_i32 s5, s4, 31
	s_lshr_b32 s5, s5, 29
	s_add_i32 s54, s4, s5
	s_and_b32 s5, s54, -8
	s_sub_i32 s55, s4, s5
	s_cmp_gt_i32 s55, -1
	s_mov_b64 s[4:5], -1
	s_cbranch_scc0 .LBB0_220
	s_lshl_b32 s56, s55, 7
	s_mov_b64 s[4:5], 0

; #define PG8_STAGE(bufoff, gbase, voff) do { _Pragma("unroll") for (int _i = 0; _i < 2; ++_i) \
;         __builtin_amdgcn_global_load_lds((const unsigned*)((const char*)(gbase) + (voff)[_i]), (PG8_LAS unsigned*)(lds + (bufoff) + ldsw + _i * 8192), 16, 0, 0); } while (0)
; #define PG8_LDA(dst, b, h) do { _Pragma("unroll") for (int m = 0; m < 4; ++m) _Pragma("unroll") for (int k = 0; k < 2; ++k) dst[m][k] = *(const PG8_LAS bf16x8*)(lds + PG8_SA(b, h) + aoff + m * 2048 + k * 1024); } while (0)
; #define PG8_LDB(dst, b, h) do { _Pragma("unroll") for (int n = 0; n < 2; ++n) _Pragma("unroll") for (int k = 0; k < 2; ++k) dst[n][k] = *(const PG8_LAS bf16x8*)(lds + PG8_SB(b, h) + boff + n * 2048 + k * 1024); } while (0)
; #define PG8_MMA(ai, bj, At, Bt) do { __builtin_amdgcn_s_setprio(1); _Pragma("unroll") for (int m = 0; m < 4; ++m) _Pragma("unroll") for (int n = 0; n < 2; ++n) _Pragma("unroll") for (int k = 0; k < 2; ++k) \
;         acc[ai][bj][m][n] = __builtin_amdgcn_mfma_f32_16x16x32_bf16(Bt[n][k], At[m][k], acc[ai][bj][m][n], 0, 0, 0); __builtin_amdgcn_s_setprio(0); } while (0)
; #define PG8_WAIT_V(n) asm volatile("s_waitcnt vmcnt(" #n ")" ::: "memory")
; #define PG8_WAIT_L(n) asm volatile("s_waitcnt lgkmcnt(" #n ")" ::: "memory")
; template <class Epi, class Sched, bool ALIGN_EPI = false, bool SP2 = false>
; __device__ __forceinline__ void gemm_phase(PG8_LAS unsigned char* lds, const Gemm g, const Sched& S, const Epi& E, const int tid_in) {
;     ...
;             const bool last = (t == nt - 2);
;             const char* a1 = cA + (size_t)(t + 1) * kstep;
;             const char* a2 = last ? nA : cA + (size_t)(t + 2) * kstep; const char* b2 = last ? nB : cB + (size_t)(t + 2) * kstep;
;             const char* a3 = a2 + kstep; const char* b3 = b2 + kstep;
;             if (last && has_next) S.a_ready(nxt);
;             if constexpr (SP2) {
;             PG8_LDB(B0, 0, 0); PG8_LDB(B1, 0, 1); PG8_SCHED; PG8_LDA(At, 0, 0); PG8_STAGE(PG8_SA(1, 1), a1 + hstepA, voffA);
;             PG8_WAIT_V(8); PG8_WAIT_L(0); PG8_BAR; PG8_MMA(0, 0, At, B0); PG8_MMA(0, 1, At, B1); PG8_BAR; PG8_SCHED;
;             PG8_LDA(At, 0, 1); PG8_STAGE(PG8_SB(0, 0), b2, voffB); PG8_STAGE(PG8_SB(0, 1), b2 + hstepB, voffB); PG8_STAGE(PG8_SA(0, 0), a2, voffA);
;             PG8_WAIT_V(8); PG8_WAIT_L(0); PG8_BAR; PG8_MMA(1, 0, At, B0); PG8_MMA(1, 1, At, B1); PG8_BAR; PG8_SCHED;
.LBB0_224:
	s_add_u32 s4, s0, 0xfffc0080
	s_addc_u32 s5, s1, -1
	s_add_i32 s76, 0, 0x10000
	s_cmp_eq_u32 s75, 12
	s_cselect_b32 s21, s57, s5
	s_cselect_b32 s20, s71, s4
	v_add_u32_e32 v114, s76, v171
	s_cselect_b32 s5, s55, s74
	s_cselect_b32 s4, s72, s73
	s_cmp_lg_u32 s75, 12
	s_cbranch_scc1 .Ltail_keep_foxin
	s_cmp_lg_u32 s100, 0
	s_cbranch_scc1 .Ltail_keep_foxin
	v_mov_b32_e32 v144, 0
	v_mov_b32_e32 v148, 0
	v_mov_b32_e32 v146, 0
	v_mov_b32_e32 v112, 0
.Ltail_keep_foxin:
	s_add_i32 s78, 0, 0x14000
	ds_read_b128 v[132:135], v114
	ds_read_b128 v[136:139], v114 offset:1024
	ds_read_b128 v[140:143], v114 offset:2048
	s_waitcnt lgkmcnt(0)
	ds_read_b128 v[154:157], v114 offset:3072
	v_add_u32_e32 v114, s78, v171
	ds_read_b128 v[158:161], v114
	ds_read_b128 v[162:165], v114 offset:1024
	ds_read_b128 v[166:169], v114 offset:2048
	ds_read_b128 v[200:203], v114 offset:3072
	v_lshl_add_u64 v[230:231], s[0:1], 0, v[150:151]
	s_add_i32 m0, s28, 0xc000
	ds_read_b128 v[204:207], v197
	ds_read_b128 v[208:211], v197 offset:1024
	ds_read_b128 v[212:215], v197 offset:2048
	ds_read_b128 v[216:219], v197 offset:3072
	ds_read_b128 v[220:223], v197 offset:4096
	ds_read_b128 v[224:227], v197 offset:5120
	ds_read_b128 v[238:241], v197 offset:6144
	ds_read_b128 v[242:245], v197 offset:7168
	global_load_lds_dwordx4 v[230:231], off
	v_lshl_add_u64 v[230:231], s[0:1], 0, v[152:153]
	s_add_i32 m0, s28, 0xe000
	s_nop 0
	global_load_lds_dwordx4 v[230:231], off
	s_waitcnt vmcnt(8)
	s_waitcnt lgkmcnt(0)
	s_barrier
	s_setprio 1
	s_waitcnt lgkmcnt(0)
	v_mfma_f32_16x16x32_bf16 v[128:131], v[132:135], v[204:207], v[128:131]
	v_mfma_f32_16x16x32_bf16 v[124:127], v[140:143], v[204:207], v[124:127]
	v_mfma_f32_16x16x32_bf16 v[108:111], v[132:135], v[212:215], v[108:111]
	v_mfma_f32_16x16x32_bf16 v[104:107], v[140:143], v[212:215], v[104:107]
	v_mfma_f32_16x16x32_bf16 v[92:95], v[132:135], v[220:223], v[92:95]
	v_mfma_f32_16x16x32_bf16 v[88:91], v[140:143], v[220:223], v[88:91]
	v_mfma_f32_16x16x32_bf16 v[76:79], v[132:135], v[238:241], v[76:79]
	v_mfma_f32_16x16x32_bf16 v[72:75], v[140:143], v[238:241], v[72:75]
	v_mfma_f32_16x16x32_bf16 v[128:131], v[136:139], v[208:211], v[128:131]
	v_mfma_f32_16x16x32_bf16 v[124:127], v[154:157], v[208:211], v[124:127]
	v_mfma_f32_16x16x32_bf16 v[108:111], v[136:139], v[216:219], v[108:111]
	v_mfma_f32_16x16x32_bf16 v[104:107], v[154:157], v[216:219], v[104:107]
	v_mfma_f32_16x16x32_bf16 v[92:95], v[136:139], v[224:227], v[92:95]
	v_mfma_f32_16x16x32_bf16 v[88:91], v[154:157], v[224:227], v[88:91]
	v_mfma_f32_16x16x32_bf16 v[76:79], v[136:139], v[242:245], v[76:79]
	v_mfma_f32_16x16x32_bf16 v[72:75], v[154:157], v[242:245], v[72:75]
	s_setprio 0
	s_setprio 1
	v_mfma_f32_16x16x32_bf16 v[120:123], v[158:161], v[204:207], v[120:123]
	v_mfma_f32_16x16x32_bf16 v[116:119], v[166:169], v[204:207], v[116:119]
	v_mfma_f32_16x16x32_bf16 v[100:103], v[158:161], v[212:215], v[100:103]
	v_mfma_f32_16x16x32_bf16 v[96:99], v[166:169], v[212:215], v[96:99]
	v_mfma_f32_16x16x32_bf16 v[84:87], v[158:161], v[220:223], v[84:87]
	v_mfma_f32_16x16x32_bf16 v[80:83], v[166:169], v[220:223], v[80:83]
	v_mfma_f32_16x16x32_bf16 v[68:71], v[158:161], v[238:241], v[68:71]
	v_mfma_f32_16x16x32_bf16 v[64:67], v[166:169], v[238:241], v[64:67]
	v_mfma_f32_16x16x32_bf16 v[120:123], v[162:165], v[208:211], v[120:123]
	v_mfma_f32_16x16x32_bf16 v[116:119], v[200:203], v[208:211], v[116:119]
	v_mfma_f32_16x16x32_bf16 v[100:103], v[162:165], v[216:219], v[100:103]
	v_mfma_f32_16x16x32_bf16 v[96:99], v[200:203], v[216:219], v[96:99]
	v_mfma_f32_16x16x32_bf16 v[84:87], v[162:165], v[224:227], v[84:87]
	v_mfma_f32_16x16x32_bf16 v[80:83], v[200:203], v[224:227], v[80:83]
	v_mfma_f32_16x16x32_bf16 v[68:71], v[162:165], v[242:245], v[68:71]
	v_mfma_f32_16x16x32_bf16 v[64:67], v[200:203], v[242:245], v[64:67]
	s_setprio 0
	s_barrier
	s_add_i32 s76, s76, s19
	v_lshl_add_u64 v[230:231], s[4:5], 0, v[144:145]
	s_mov_b32 m0, s76
	ds_read_b128 v[204:207], v197 offset:16384
	ds_read_b128 v[208:211], v197 offset:17408
	ds_read_b128 v[212:215], v197 offset:18432
	ds_read_b128 v[216:219], v197 offset:19456
	ds_read_b128 v[220:223], v197 offset:20480
	ds_read_b128 v[224:227], v197 offset:21504
	ds_read_b128 v[238:241], v197 offset:22528
	ds_read_b128 v[242:245], v197 offset:23552
	global_load_lds_dwordx4 v[230:231], off
	s_add_i32 m0, s76, 0x2000
	s_add_u32 s76, s4, 0x40000
	v_lshl_add_u64 v[234:235], s[4:5], 0, v[148:149]
	s_addc_u32 s77, s5, 0
	s_add_i32 s78, s78, s19
	global_load_lds_dwordx4 v[234:235], off
	v_lshl_add_u64 v[246:247], s[76:77], 0, v[144:145]
	s_mov_b32 m0, s78
	v_lshl_add_u64 v[248:249], s[20:21], 0, v[146:147]
	global_load_lds_dwordx4 v[246:247], off
	v_lshl_add_u64 v[246:247], s[76:77], 0, v[148:149]
	s_add_i32 m0, s78, 0x2000
	s_nop 0
	global_load_lds_dwordx4 v[246:247], off
	v_lshl_add_u64 v[246:247], s[20:21], 0, v[112:113]
	s_mov_b32 m0, s28
	s_nop 0
	global_load_lds_dwordx4 v[246:247], off
	s_mov_b32 m0, s29
	s_nop 0
	global_load_lds_dwordx4 v[248:249], off
	s_waitcnt vmcnt(8)
	s_waitcnt lgkmcnt(0)
	s_barrier
; #define PG8_STAGE(bufoff, gbase, voff) do { _Pragma("unroll") for (int _i = 0; _i < 2; ++_i) \
;         __builtin_amdgcn_global_load_lds((const unsigned*)((const char*)(gbase) + (voff)[_i]), (PG8_LAS unsigned*)(lds + (bufoff) + ldsw + _i * 8192), 16, 0, 0); } while (0)
; #define PG8_LDA(dst, b, h) do { _Pragma("unroll") for (int m = 0; m < 4; ++m) _Pragma("unroll") for (int k = 0; k < 2; ++k) dst[m][k] = *(const PG8_LAS bf16x8*)(lds + PG8_SA(b, h) + aoff + m * 2048 + k * 1024); } while (0)
; #define PG8_LDB(dst, b, h) do { _Pragma("unroll") for (int n = 0; n < 2; ++n) _Pragma("unroll") for (int k = 0; k < 2; ++k) dst[n][k] = *(const PG8_LAS bf16x8*)(lds + PG8_SB(b, h) + boff + n * 2048 + k * 1024); } while (0)
; #define PG8_MMA(ai, bj, At, Bt) do { __builtin_amdgcn_s_setprio(1); _Pragma("unroll") for (int m = 0; m < 4; ++m) _Pragma("unroll") for (int n = 0; n < 2; ++n) _Pragma("unroll") for (int k = 0; k < 2; ++k) \
;         acc[ai][bj][m][n] = __builtin_amdgcn_mfma_f32_16x16x32_bf16(Bt[n][k], At[m][k], acc[ai][bj][m][n], 0, 0, 0); __builtin_amdgcn_s_setprio(0); } while (0)
; #define PG8_WAIT_V(n) asm volatile("s_waitcnt vmcnt(" #n ")" ::: "memory")
; #define PG8_WAIT_L(n) asm volatile("s_waitcnt lgkmcnt(" #n ")" ::: "memory")
; #define PG8_BAR __builtin_amdgcn_s_barrier()
; #define PG8_SCHED __builtin_amdgcn_sched_barrier(0)
; template <class Epi, class Sched, bool ALIGN_EPI = false, bool SP2 = false>
; __device__ __forceinline__ void gemm_phase(PG8_LAS unsigned char* lds, const Gemm g, const Sched& S, const Epi& E, const int tid_in) {
;     ...
;             PG8_WAIT_V(8); PG8_WAIT_L(0); PG8_BAR; PG8_MMA(1, 0, At, B0); PG8_MMA(1, 1, At, B1); PG8_BAR; PG8_SCHED;
;             PG8_LDB(B0, 1, 0); PG8_LDB(B1, 1, 1); PG8_SCHED; PG8_LDA(At, 1, 0); PG8_STAGE(PG8_SA(0, 1), a2 + hstepA, voffA);
;             PG8_WAIT_V(8); PG8_WAIT_L(0); PG8_BAR; PG8_MMA(0, 0, At, B0); PG8_MMA(0, 1, At, B1); PG8_BAR; PG8_SCHED;
	s_setprio 1
	s_waitcnt lgkmcnt(0)
	v_mfma_f32_16x16x32_bf16 v[60:63], v[132:135], v[204:207], v[60:63]
	v_mfma_f32_16x16x32_bf16 v[56:59], v[140:143], v[204:207], v[56:59]
	v_mfma_f32_16x16x32_bf16 v[44:47], v[132:135], v[212:215], v[44:47]
	v_mfma_f32_16x16x32_bf16 v[40:43], v[140:143], v[212:215], v[40:43]
	v_mfma_f32_16x16x32_bf16 v[28:31], v[132:135], v[220:223], v[28:31]
	v_mfma_f32_16x16x32_bf16 v[24:27], v[140:143], v[220:223], v[24:27]
	v_mfma_f32_16x16x32_bf16 v[12:15], v[132:135], v[238:241], v[12:15]
	v_mfma_f32_16x16x32_bf16 v[8:11], v[140:143], v[238:241], v[8:11]
	v_mfma_f32_16x16x32_bf16 v[60:63], v[136:139], v[208:211], v[60:63]
	v_mfma_f32_16x16x32_bf16 v[56:59], v[154:157], v[208:211], v[56:59]
	v_mfma_f32_16x16x32_bf16 v[44:47], v[136:139], v[216:219], v[44:47]
	v_mfma_f32_16x16x32_bf16 v[40:43], v[154:157], v[216:219], v[40:43]
	v_mfma_f32_16x16x32_bf16 v[28:31], v[136:139], v[224:227], v[28:31]
	v_mfma_f32_16x16x32_bf16 v[24:27], v[154:157], v[224:227], v[24:27]
	v_mfma_f32_16x16x32_bf16 v[12:15], v[136:139], v[242:245], v[12:15]
	v_mfma_f32_16x16x32_bf16 v[8:11], v[154:157], v[242:245], v[8:11]
	s_setprio 0
	s_setprio 1
	v_mfma_f32_16x16x32_bf16 v[52:55], v[158:161], v[204:207], v[52:55]
	v_mfma_f32_16x16x32_bf16 v[48:51], v[166:169], v[204:207], v[48:51]
	v_mfma_f32_16x16x32_bf16 v[36:39], v[158:161], v[212:215], v[36:39]
	v_mfma_f32_16x16x32_bf16 v[32:35], v[166:169], v[212:215], v[32:35]
	v_mfma_f32_16x16x32_bf16 v[20:23], v[158:161], v[220:223], v[20:23]
	v_mfma_f32_16x16x32_bf16 v[16:19], v[166:169], v[220:223], v[16:19]
	v_mfma_f32_16x16x32_bf16 v[4:7], v[158:161], v[238:241], v[4:7]
	v_mfma_f32_16x16x32_bf16 v[0:3], v[166:169], v[238:241], v[0:3]
	v_mfma_f32_16x16x32_bf16 v[52:55], v[162:165], v[208:211], v[52:55]
	v_mfma_f32_16x16x32_bf16 v[48:51], v[200:203], v[208:211], v[48:51]
	v_mfma_f32_16x16x32_bf16 v[36:39], v[162:165], v[216:219], v[36:39]
	v_mfma_f32_16x16x32_bf16 v[32:35], v[200:203], v[216:219], v[32:35]
	v_mfma_f32_16x16x32_bf16 v[20:23], v[162:165], v[224:227], v[20:23]
	v_mfma_f32_16x16x32_bf16 v[16:19], v[200:203], v[224:227], v[16:19]
	v_mfma_f32_16x16x32_bf16 v[4:7], v[162:165], v[242:245], v[4:7]
	v_mfma_f32_16x16x32_bf16 v[0:3], v[200:203], v[242:245], v[0:3]
	s_setprio 0
	s_barrier
	s_add_i32 s76, 0, 0x18000
	v_add_u32_e32 v114, s76, v171
	s_add_i32 s77, 0, 0x1c000
	ds_read_b128 v[132:135], v114
	ds_read_b128 v[136:139], v114 offset:1024
	ds_read_b128 v[140:143], v114 offset:2048
	ds_read_b128 v[154:157], v114 offset:3072
	v_add_u32_e32 v114, s77, v171
	ds_read_b128 v[158:161], v114
	ds_read_b128 v[162:165], v114 offset:1024
	ds_read_b128 v[166:169], v114 offset:2048
	ds_read_b128 v[200:203], v114 offset:3072
	s_add_u32 s20, s20, 0x40000
	s_addc_u32 s21, s21, 0
	s_mov_b32 m0, s62
	v_lshl_add_u64 v[250:251], s[20:21], 0, v[112:113]
	ds_read_b128 v[204:207], v197 offset:32768
	ds_read_b128 v[208:211], v197 offset:33792
	ds_read_b128 v[212:215], v197 offset:34816
	ds_read_b128 v[216:219], v197 offset:35840
	ds_read_b128 v[220:223], v197 offset:36864
	ds_read_b128 v[224:227], v197 offset:37888
	ds_read_b128 v[238:241], v197 offset:38912
	ds_read_b128 v[242:245], v197 offset:39936
	global_load_lds_dwordx4 v[250:251], off
	v_lshl_add_u64 v[250:251], s[20:21], 0, v[146:147]
	s_mov_b32 m0, s63
	s_nop 0
	global_load_lds_dwordx4 v[250:251], off
	s_waitcnt vmcnt(8)
	s_waitcnt lgkmcnt(0)
	s_barrier
	s_setprio 1
	s_waitcnt lgkmcnt(0)
	v_mfma_f32_16x16x32_bf16 v[128:131], v[132:135], v[204:207], v[128:131]
	v_mfma_f32_16x16x32_bf16 v[124:127], v[140:143], v[204:207], v[124:127]
	v_mfma_f32_16x16x32_bf16 v[108:111], v[132:135], v[212:215], v[108:111]
	v_mfma_f32_16x16x32_bf16 v[104:107], v[140:143], v[212:215], v[104:107]
	v_mfma_f32_16x16x32_bf16 v[92:95], v[132:135], v[220:223], v[92:95]
	v_mfma_f32_16x16x32_bf16 v[88:91], v[140:143], v[220:223], v[88:91]
	v_mfma_f32_16x16x32_bf16 v[76:79], v[132:135], v[238:241], v[76:79]
	v_mfma_f32_16x16x32_bf16 v[72:75], v[140:143], v[238:241], v[72:75]
	v_mfma_f32_16x16x32_bf16 v[128:131], v[136:139], v[208:211], v[128:131]
	v_mfma_f32_16x16x32_bf16 v[124:127], v[154:157], v[208:211], v[124:127]
	v_mfma_f32_16x16x32_bf16 v[108:111], v[136:139], v[216:219], v[108:111]
	v_mfma_f32_16x16x32_bf16 v[104:107], v[154:157], v[216:219], v[104:107]
	v_mfma_f32_16x16x32_bf16 v[92:95], v[136:139], v[224:227], v[92:95]
	v_mfma_f32_16x16x32_bf16 v[88:91], v[154:157], v[224:227], v[88:91]
	v_mfma_f32_16x16x32_bf16 v[76:79], v[136:139], v[242:245], v[76:79]
	v_mfma_f32_16x16x32_bf16 v[72:75], v[154:157], v[242:245], v[72:75]
	s_setprio 0
	s_setprio 1
	v_mfma_f32_16x16x32_bf16 v[120:123], v[158:161], v[204:207], v[120:123]
	v_mfma_f32_16x16x32_bf16 v[116:119], v[166:169], v[204:207], v[116:119]
	v_mfma_f32_16x16x32_bf16 v[100:103], v[158:161], v[212:215], v[100:103]
	v_mfma_f32_16x16x32_bf16 v[96:99], v[166:169], v[212:215], v[96:99]
	v_mfma_f32_16x16x32_bf16 v[84:87], v[158:161], v[220:223], v[84:87]
	v_mfma_f32_16x16x32_bf16 v[80:83], v[166:169], v[220:223], v[80:83]
	v_mfma_f32_16x16x32_bf16 v[68:71], v[158:161], v[238:241], v[68:71]
	v_mfma_f32_16x16x32_bf16 v[64:67], v[166:169], v[238:241], v[64:67]
	v_mfma_f32_16x16x32_bf16 v[120:123], v[162:165], v[208:211], v[120:123]
	v_mfma_f32_16x16x32_bf16 v[116:119], v[200:203], v[208:211], v[116:119]
	v_mfma_f32_16x16x32_bf16 v[100:103], v[162:165], v[216:219], v[100:103]
	v_mfma_f32_16x16x32_bf16 v[96:99], v[200:203], v[216:219], v[96:99]
	v_mfma_f32_16x16x32_bf16 v[84:87], v[162:165], v[224:227], v[84:87]
	v_mfma_f32_16x16x32_bf16 v[80:83], v[200:203], v[224:227], v[80:83]
	v_mfma_f32_16x16x32_bf16 v[68:71], v[162:165], v[242:245], v[68:71]
	v_mfma_f32_16x16x32_bf16 v[64:67], v[200:203], v[242:245], v[64:67]
	s_setprio 0
	s_barrier
; #define PG8_STAGE(bufoff, gbase, voff) do { _Pragma("unroll") for (int _i = 0; _i < 2; ++_i) \
;         __builtin_amdgcn_global_load_lds((const unsigned*)((const char*)(gbase) + (voff)[_i]), (PG8_LAS unsigned*)(lds + (bufoff) + ldsw + _i * 8192), 16, 0, 0); } while (0)
; #define PG8_LDA(dst, b, h) do { _Pragma("unroll") for (int m = 0; m < 4; ++m) _Pragma("unroll") for (int k = 0; k < 2; ++k) dst[m][k] = *(const PG8_LAS bf16x8*)(lds + PG8_SA(b, h) + aoff + m * 2048 + k * 1024); } while (0)
; #define PG8_MMA(ai, bj, At, Bt) do { __builtin_amdgcn_s_setprio(1); _Pragma("unroll") for (int m = 0; m < 4; ++m) _Pragma("unroll") for (int n = 0; n < 2; ++n) _Pragma("unroll") for (int k = 0; k < 2; ++k) \
;         acc[ai][bj][m][n] = __builtin_amdgcn_mfma_f32_16x16x32_bf16(Bt[n][k], At[m][k], acc[ai][bj][m][n], 0, 0, 0); __builtin_amdgcn_s_setprio(0); } while (0)
; #define PG8_WAIT_V(n) asm volatile("s_waitcnt vmcnt(" #n ")" ::: "memory")
; #define PG8_WAIT_L(n) asm volatile("s_waitcnt lgkmcnt(" #n ")" ::: "memory")
; #define PG8_BAR __builtin_amdgcn_s_barrier()
; #define PG8_SCHED __builtin_amdgcn_sched_barrier(0)
; template <class Epi, class Sched, bool ALIGN_EPI = false, bool SP2 = false>
; __device__ __forceinline__ void gemm_phase(PG8_LAS unsigned char* lds, const Gemm g, const Sched& S, const Epi& E, const int tid_in) {
;     ...
;             PG8_LDA(At, 1, 1); PG8_STAGE(PG8_SB(1, 0), b3, voffB); PG8_STAGE(PG8_SB(1, 1), b3 + hstepB, voffB); PG8_STAGE(PG8_SA(1, 0), a3, voffA);
;             PG8_WAIT_V(8); PG8_WAIT_L(0); PG8_BAR; PG8_MMA(1, 0, At, B0); PG8_MMA(1, 1, At, B1); PG8_BAR; PG8_SCHED;
;     ...
;         if constexpr (ALIGN_EPI) { if (wr == 0) PG8_BAR; }
	s_add_i32 s20, s76, s19
	v_lshl_add_u64 v[230:231], v[230:231], 0, s[10:11]
	s_mov_b32 m0, s20
	ds_read_b128 v[204:207], v197 offset:49152
	ds_read_b128 v[208:211], v197 offset:50176
	ds_read_b128 v[212:215], v197 offset:51200
	ds_read_b128 v[216:219], v197 offset:52224
	ds_read_b128 v[220:223], v197 offset:53248
	ds_read_b128 v[224:227], v197 offset:54272
	ds_read_b128 v[238:241], v197 offset:55296
	ds_read_b128 v[242:245], v197 offset:56320
	global_load_lds_dwordx4 v[230:231], off
	s_add_i32 m0, s20, 0x2000
	s_add_u32 s4, s4, 0x40080
	v_lshl_add_u64 v[230:231], v[234:235], 0, s[10:11]
	s_addc_u32 s5, s5, 0
	s_add_i32 s20, s77, s19
	global_load_lds_dwordx4 v[230:231], off
	v_lshl_add_u64 v[230:231], s[4:5], 0, v[144:145]
	s_mov_b32 m0, s20
	s_nop 0
	global_load_lds_dwordx4 v[230:231], off
	v_lshl_add_u64 v[230:231], s[4:5], 0, v[148:149]
	s_add_i32 m0, s20, 0x2000
	s_nop 0
	global_load_lds_dwordx4 v[230:231], off
	v_lshl_add_u64 v[230:231], v[246:247], 0, s[10:11]
	s_mov_b32 m0, s64
	s_nop 0
	global_load_lds_dwordx4 v[230:231], off
	v_lshl_add_u64 v[230:231], v[248:249], 0, s[10:11]
	s_mov_b32 m0, s65
	s_nop 0
	global_load_lds_dwordx4 v[230:231], off
	s_waitcnt vmcnt(8)
	s_waitcnt lgkmcnt(0)
	s_barrier
	s_setprio 1
	s_waitcnt lgkmcnt(0)
	v_mfma_f32_16x16x32_bf16 v[60:63], v[132:135], v[204:207], v[60:63]
	v_mfma_f32_16x16x32_bf16 v[56:59], v[140:143], v[204:207], v[56:59]
	v_mfma_f32_16x16x32_bf16 v[44:47], v[132:135], v[212:215], v[44:47]
	v_mfma_f32_16x16x32_bf16 v[40:43], v[140:143], v[212:215], v[40:43]
	v_mfma_f32_16x16x32_bf16 v[28:31], v[132:135], v[220:223], v[28:31]
	v_mfma_f32_16x16x32_bf16 v[24:27], v[140:143], v[220:223], v[24:27]
	v_mfma_f32_16x16x32_bf16 v[12:15], v[132:135], v[238:241], v[12:15]
	v_mfma_f32_16x16x32_bf16 v[8:11], v[140:143], v[238:241], v[8:11]
	v_mfma_f32_16x16x32_bf16 v[60:63], v[136:139], v[208:211], v[60:63]
	v_mfma_f32_16x16x32_bf16 v[56:59], v[154:157], v[208:211], v[56:59]
	v_mfma_f32_16x16x32_bf16 v[44:47], v[136:139], v[216:219], v[44:47]
	v_mfma_f32_16x16x32_bf16 v[40:43], v[154:157], v[216:219], v[40:43]
	v_mfma_f32_16x16x32_bf16 v[28:31], v[136:139], v[224:227], v[28:31]
	v_mfma_f32_16x16x32_bf16 v[24:27], v[154:157], v[224:227], v[24:27]
	v_mfma_f32_16x16x32_bf16 v[12:15], v[136:139], v[242:245], v[12:15]
	v_mfma_f32_16x16x32_bf16 v[8:11], v[154:157], v[242:245], v[8:11]
	s_setprio 0
	s_setprio 1
	v_mfma_f32_16x16x32_bf16 v[52:55], v[158:161], v[204:207], v[52:55]
	v_mfma_f32_16x16x32_bf16 v[48:51], v[166:169], v[204:207], v[48:51]
	v_mfma_f32_16x16x32_bf16 v[36:39], v[158:161], v[212:215], v[36:39]
	v_mfma_f32_16x16x32_bf16 v[32:35], v[166:169], v[212:215], v[32:35]
	v_mfma_f32_16x16x32_bf16 v[20:23], v[158:161], v[220:223], v[20:23]
	v_mfma_f32_16x16x32_bf16 v[16:19], v[166:169], v[220:223], v[16:19]
	v_mfma_f32_16x16x32_bf16 v[4:7], v[158:161], v[238:241], v[4:7]
	v_mfma_f32_16x16x32_bf16 v[0:3], v[166:169], v[238:241], v[0:3]
	v_mfma_f32_16x16x32_bf16 v[52:55], v[162:165], v[208:211], v[52:55]
	v_mfma_f32_16x16x32_bf16 v[48:51], v[200:203], v[208:211], v[48:51]
	v_mfma_f32_16x16x32_bf16 v[36:39], v[162:165], v[216:219], v[36:39]
	v_mfma_f32_16x16x32_bf16 v[32:35], v[200:203], v[216:219], v[32:35]
	v_mfma_f32_16x16x32_bf16 v[20:23], v[162:165], v[224:227], v[20:23]
	v_mfma_f32_16x16x32_bf16 v[16:19], v[200:203], v[224:227], v[16:19]
	v_mfma_f32_16x16x32_bf16 v[4:7], v[162:165], v[242:245], v[4:7]
	v_mfma_f32_16x16x32_bf16 v[0:3], v[200:203], v[242:245], v[0:3]
	s_setprio 0
	s_barrier
	s_add_i32 s75, s75, 2
	s_add_u32 s0, s0, 0x100
	s_addc_u32 s1, s1, 0
	s_add_u32 s73, s73, 0x100
	s_addc_u32 s74, s74, 0
	s_cmp_gt_u32 s75, 13
	s_cbranch_scc0 .LBB0_224
	s_and_b64 vcc, exec, s[50:51]
	s_cbranch_vccz .LBB0_227
	s_barrier

;   __device__ __forceinline__ bool next(int i,AttnUnit&u)const{ const int p=vcu+(i>>1)*grid; if(p>=BATCH*NHEAD*4)return false; const int q=(p&31)+32*(p>>8), s=(q<32)?(q&3):(3-(q&3)); u.bh=((p>>5)&7)*NHEAD+((q<32)?(q>>2):(NHEAD-1-((q-32)>>2)));     u.qb=(i&1)?s:(NQB-1-s); u.reuse=i&1; return true; }
;     __host__ __device__ __forceinline__ bool next(int i, Unit& u) const {
;         const long L = (long)i * G + c; if (L >= nwg) return false;
;         int wgid = (int)L; { const int q = nwg / NXCD, r = nwg % NXCD, xcd = wgid % NXCD, off = wgid / NXCD; wgid = (xcd < r ? xcd * (q + 1) : r * (q + 1) + (xcd - r) * q) + off; }
;         const int nig = WGM * nN, gid = wgid / nig, fm = gid * WGM, gsz = (nM - fm) < WGM ? (nM - fm) : WGM;
;         u.pm = fm + ((wgid % nig) % gsz); u.pn = (wgid % nig) / gsz; return true;
; template <class Epi, class Sched, bool ALIGN_EPI = false, bool SP2 = false>
; __device__ __forceinline__ void gemm_phase(PG8_LAS unsigned char* lds, const Gemm g, const Sched& S, const Epi& E, const int tid_in) {
;     ...
;         const bool has_next = S.next(ui + 1, nxt);
.LBB0_499:
	s_add_i32 s70, s71, 1
	s_mul_i32 s9, s70, s3
	s_mul_hi_i32 s8, s70, s3
	s_add_u32 s14, s9, s2
	s_addc_u32 s15, s8, s33
	v_mov_b64_e32 v[140:141], 0x100
	v_cmp_lt_i64_e64 s[40:41], s[14:15], v[140:141]
	s_nop 3
	s_mov_b32 s100, s40
	v_mov_b64_e32 v[140:141], 0xff
	v_cmp_gt_i64_e64 s[8:9], s[14:15], v[140:141]
	s_and_b64 vcc, exec, s[8:9]
	s_cbranch_vccnz .LBB0_505
	s_ashr_i32 s15, s14, 31
	s_lshr_b32 s15, s15, 29
	s_add_i32 s28, s14, s15
	s_and_b32 s15, s28, -8
	s_sub_i32 s29, s14, s15
	s_cmp_gt_i32 s29, -1
	s_mov_b64 s[14:15], -1
	s_cbranch_scc0 .LBB0_502
	s_lshl_b32 s38, s29, 5
	s_mov_b64 s[14:15], 0

; #define PG8_STAGE(bufoff, gbase, voff) do { _Pragma("unroll") for (int _i = 0; _i < 2; ++_i) \
;         __builtin_amdgcn_global_load_lds((const unsigned*)((const char*)(gbase) + (voff)[_i]), (PG8_LAS unsigned*)(lds + (bufoff) + ldsw + _i * 8192), 16, 0, 0); } while (0)
; #define PG8_LDA(dst, b, h) do { _Pragma("unroll") for (int m = 0; m < 4; ++m) _Pragma("unroll") for (int k = 0; k < 2; ++k) dst[m][k] = *(const PG8_LAS bf16x8*)(lds + PG8_SA(b, h) + aoff + m * 2048 + k * 1024); } while (0)
; #define PG8_LDB(dst, b, h) do { _Pragma("unroll") for (int n = 0; n < 2; ++n) _Pragma("unroll") for (int k = 0; k < 2; ++k) dst[n][k] = *(const PG8_LAS bf16x8*)(lds + PG8_SB(b, h) + boff + n * 2048 + k * 1024); } while (0)
; #define PG8_MMA(ai, bj, At, Bt) do { __builtin_amdgcn_s_setprio(1); _Pragma("unroll") for (int m = 0; m < 4; ++m) _Pragma("unroll") for (int n = 0; n < 2; ++n) _Pragma("unroll") for (int k = 0; k < 2; ++k) \
;         acc[ai][bj][m][n] = __builtin_amdgcn_mfma_f32_16x16x32_bf16(Bt[n][k], At[m][k], acc[ai][bj][m][n], 0, 0, 0); __builtin_amdgcn_s_setprio(0); } while (0)
; #define PG8_WAIT_V(n) asm volatile("s_waitcnt vmcnt(" #n ")" ::: "memory")
; #define PG8_WAIT_L(n) asm volatile("s_waitcnt lgkmcnt(" #n ")" ::: "memory")
; #define PG8_BAR __builtin_amdgcn_s_barrier()
; #define PG8_SCHED __builtin_amdgcn_sched_barrier(0)
; template <class Epi, class Sched, bool ALIGN_EPI = false, bool SP2 = false>
; __device__ __forceinline__ void gemm_phase(PG8_LAS unsigned char* lds, const Gemm g, const Sched& S, const Epi& E, const int tid_in) {
;     ...
;             const bool last = (t == nt - 2);
;             const char* a1 = cA + (size_t)(t + 1) * kstep;
;             const char* a2 = last ? nA : cA + (size_t)(t + 2) * kstep; const char* b2 = last ? nB : cB + (size_t)(t + 2) * kstep;
;             const char* a3 = a2 + kstep; const char* b3 = b2 + kstep;
;             if (last && has_next) S.a_ready(nxt);
;             if constexpr (SP2) {
;             PG8_LDB(B0, 0, 0); PG8_LDB(B1, 0, 1); PG8_SCHED; PG8_LDA(At, 0, 0); PG8_STAGE(PG8_SA(1, 1), a1 + hstepA, voffA);
;             PG8_WAIT_V(8); PG8_WAIT_L(0); PG8_BAR; PG8_MMA(0, 0, At, B0); PG8_MMA(0, 1, At, B1); PG8_BAR; PG8_SCHED;
;             PG8_LDA(At, 0, 1); PG8_STAGE(PG8_SB(0, 0), b2, voffB); PG8_STAGE(PG8_SB(0, 1), b2 + hstepB, voffB); PG8_STAGE(PG8_SA(0, 0), a2, voffA);
.LBB0_508:
	s_add_u32 s53, s50, s40
	s_addc_u32 s54, s51, s41
	s_add_u32 s53, s53, 0x100
	s_addc_u32 s54, s54, 0
	s_add_u32 s74, s43, s40
	s_addc_u32 s55, s73, s41
	s_add_i32 s75, 0, 0x10000
	s_cmpk_eq_i32 s40, 0x700
	s_cselect_b32 s57, s47, s54
	s_cselect_b32 s56, s46, s53
	v_add_u32_e32 v151, s75, v145
	s_cselect_b32 s55, s14, s55
	s_cselect_b32 s54, s15, s74
	s_cmpk_lg_i32 s40, 0x700
	s_cbranch_scc1 .Ltail_keep_foxout
	s_cmp_lg_u32 s100, 0
	s_cbranch_scc1 .Ltail_keep_foxout
	v_mov_b32_e32 v114, 0
	v_mov_b32_e32 v112, 0
	v_mov_b32_e32 v132, 0
	v_mov_b32_e32 v134, 0
.Ltail_keep_foxout:
	s_add_i32 s53, 0, 0x14000
	ds_read_b128 v[152:155], v151
	ds_read_b128 v[156:159], v151 offset:1024
	ds_read_b128 v[160:163], v151 offset:2048
	ds_read_b128 v[164:167], v151 offset:3072
	v_add_u32_e32 v151, s53, v145
	ds_read_b128 v[168:171], v151
	ds_read_b128 v[172:175], v151 offset:1024
	ds_read_b128 v[176:179], v151 offset:2048
	ds_read_b128 v[180:183], v151 offset:3072
	v_lshl_add_u64 v[216:217], v[140:141], 0, s[40:41]
	s_add_i32 m0, s60, 0xc000
	ds_read_b128 v[184:187], v149
	ds_read_b128 v[188:191], v149 offset:1024
	ds_read_b128 v[192:195], v149 offset:2048
	ds_read_b128 v[196:199], v149 offset:3072
	ds_read_b128 v[200:203], v149 offset:4096
	ds_read_b128 v[204:207], v149 offset:5120
	ds_read_b128 v[208:211], v149 offset:6144
	ds_read_b128 v[212:215], v149 offset:7168
	global_load_lds_dwordx4 v[216:217], off
	v_lshl_add_u64 v[216:217], v[142:143], 0, s[40:41]
	s_add_i32 m0, s60, 0xe000
	s_nop 0
	global_load_lds_dwordx4 v[216:217], off
	s_waitcnt vmcnt(8)
	s_waitcnt lgkmcnt(0)
	s_barrier
	s_setprio 1
	s_waitcnt lgkmcnt(0)
	v_mfma_f32_16x16x32_bf16 v[0:3], v[152:155], v[184:187], v[0:3]
	v_mfma_f32_16x16x32_bf16 v[4:7], v[160:163], v[184:187], v[4:7]
	v_mfma_f32_16x16x32_bf16 v[16:19], v[152:155], v[192:195], v[16:19]
	v_mfma_f32_16x16x32_bf16 v[20:23], v[160:163], v[192:195], v[20:23]
	v_mfma_f32_16x16x32_bf16 v[32:35], v[152:155], v[200:203], v[32:35]
	v_mfma_f32_16x16x32_bf16 v[36:39], v[160:163], v[200:203], v[36:39]
	v_mfma_f32_16x16x32_bf16 v[48:51], v[152:155], v[208:211], v[48:51]
	v_mfma_f32_16x16x32_bf16 v[52:55], v[160:163], v[208:211], v[52:55]
	v_mfma_f32_16x16x32_bf16 v[0:3], v[156:159], v[188:191], v[0:3]
	v_mfma_f32_16x16x32_bf16 v[4:7], v[164:167], v[188:191], v[4:7]
	v_mfma_f32_16x16x32_bf16 v[16:19], v[156:159], v[196:199], v[16:19]
	v_mfma_f32_16x16x32_bf16 v[20:23], v[164:167], v[196:199], v[20:23]
	v_mfma_f32_16x16x32_bf16 v[32:35], v[156:159], v[204:207], v[32:35]
	v_mfma_f32_16x16x32_bf16 v[36:39], v[164:167], v[204:207], v[36:39]
	v_mfma_f32_16x16x32_bf16 v[48:51], v[156:159], v[212:215], v[48:51]
	v_mfma_f32_16x16x32_bf16 v[52:55], v[164:167], v[212:215], v[52:55]
	s_setprio 0
	s_setprio 1
	v_mfma_f32_16x16x32_bf16 v[8:11], v[168:171], v[184:187], v[8:11]
	v_mfma_f32_16x16x32_bf16 v[12:15], v[176:179], v[184:187], v[12:15]
	v_mfma_f32_16x16x32_bf16 v[24:27], v[168:171], v[192:195], v[24:27]
	v_mfma_f32_16x16x32_bf16 v[28:31], v[176:179], v[192:195], v[28:31]
	v_mfma_f32_16x16x32_bf16 v[40:43], v[168:171], v[200:203], v[40:43]
	v_mfma_f32_16x16x32_bf16 v[44:47], v[176:179], v[200:203], v[44:47]
	v_mfma_f32_16x16x32_bf16 v[56:59], v[168:171], v[208:211], v[56:59]
	v_mfma_f32_16x16x32_bf16 v[60:63], v[176:179], v[208:211], v[60:63]
	v_mfma_f32_16x16x32_bf16 v[8:11], v[172:175], v[188:191], v[8:11]
	v_mfma_f32_16x16x32_bf16 v[12:15], v[180:183], v[188:191], v[12:15]
	v_mfma_f32_16x16x32_bf16 v[24:27], v[172:175], v[196:199], v[24:27]
	v_mfma_f32_16x16x32_bf16 v[28:31], v[180:183], v[196:199], v[28:31]
	v_mfma_f32_16x16x32_bf16 v[40:43], v[172:175], v[204:207], v[40:43]
	v_mfma_f32_16x16x32_bf16 v[44:47], v[180:183], v[204:207], v[44:47]
	v_mfma_f32_16x16x32_bf16 v[56:59], v[172:175], v[212:215], v[56:59]
	v_mfma_f32_16x16x32_bf16 v[60:63], v[180:183], v[212:215], v[60:63]
	s_setprio 0
	s_barrier
	s_add_i32 s74, s75, s59
	v_lshl_add_u64 v[216:217], s[54:55], 0, v[114:115]
	s_mov_b32 m0, s74
	ds_read_b128 v[184:187], v149 offset:16384
	ds_read_b128 v[188:191], v149 offset:17408
	ds_read_b128 v[192:195], v149 offset:18432
	ds_read_b128 v[196:199], v149 offset:19456
	ds_read_b128 v[200:203], v149 offset:20480
	ds_read_b128 v[204:207], v149 offset:21504
	ds_read_b128 v[208:211], v149 offset:22528
	ds_read_b128 v[212:215], v149 offset:23552
	global_load_lds_dwordx4 v[216:217], off
	s_add_i32 m0, s74, 0x2000
	s_add_u32 s74, s54, 0x40000
	v_lshl_add_u64 v[218:219], s[54:55], 0, v[112:113]
	s_addc_u32 s75, s55, 0
	s_add_i32 s53, s53, s59
	global_load_lds_dwordx4 v[218:219], off
	v_lshl_add_u64 v[220:221], s[74:75], 0, v[114:115]
	s_mov_b32 m0, s53
	v_lshl_add_u64 v[222:223], s[56:57], 0, v[132:133]
	global_load_lds_dwordx4 v[220:221], off
	v_lshl_add_u64 v[220:221], s[74:75], 0, v[112:113]
	s_add_i32 m0, s53, 0x2000
	s_nop 0
	global_load_lds_dwordx4 v[220:221], off
	v_lshl_add_u64 v[220:221], s[56:57], 0, v[134:135]
	s_mov_b32 m0, s60
	s_nop 0
	global_load_lds_dwordx4 v[220:221], off
	s_mov_b32 m0, s61
	s_nop 0
	global_load_lds_dwordx4 v[222:223], off
	s_waitcnt vmcnt(8)
	s_waitcnt lgkmcnt(0)
	s_barrier
; #define PG8_STAGE(bufoff, gbase, voff) do { _Pragma("unroll") for (int _i = 0; _i < 2; ++_i) \
;         __builtin_amdgcn_global_load_lds((const unsigned*)((const char*)(gbase) + (voff)[_i]), (PG8_LAS unsigned*)(lds + (bufoff) + ldsw + _i * 8192), 16, 0, 0); } while (0)
; #define PG8_LDA(dst, b, h) do { _Pragma("unroll") for (int m = 0; m < 4; ++m) _Pragma("unroll") for (int k = 0; k < 2; ++k) dst[m][k] = *(const PG8_LAS bf16x8*)(lds + PG8_SA(b, h) + aoff + m * 2048 + k * 1024); } while (0)
; #define PG8_LDB(dst, b, h) do { _Pragma("unroll") for (int n = 0; n < 2; ++n) _Pragma("unroll") for (int k = 0; k < 2; ++k) dst[n][k] = *(const PG8_LAS bf16x8*)(lds + PG8_SB(b, h) + boff + n * 2048 + k * 1024); } while (0)
; #define PG8_MMA(ai, bj, At, Bt) do { __builtin_amdgcn_s_setprio(1); _Pragma("unroll") for (int m = 0; m < 4; ++m) _Pragma("unroll") for (int n = 0; n < 2; ++n) _Pragma("unroll") for (int k = 0; k < 2; ++k) \
;         acc[ai][bj][m][n] = __builtin_amdgcn_mfma_f32_16x16x32_bf16(Bt[n][k], At[m][k], acc[ai][bj][m][n], 0, 0, 0); __builtin_amdgcn_s_setprio(0); } while (0)
; #define PG8_WAIT_V(n) asm volatile("s_waitcnt vmcnt(" #n ")" ::: "memory")
; #define PG8_WAIT_L(n) asm volatile("s_waitcnt lgkmcnt(" #n ")" ::: "memory")
; #define PG8_BAR __builtin_amdgcn_s_barrier()
; #define PG8_SCHED __builtin_amdgcn_sched_barrier(0)
; template <class Epi, class Sched, bool ALIGN_EPI = false, bool SP2 = false>
; __device__ __forceinline__ void gemm_phase(PG8_LAS unsigned char* lds, const Gemm g, const Sched& S, const Epi& E, const int tid_in) {
;     ...
;             PG8_WAIT_V(8); PG8_WAIT_L(0); PG8_BAR; PG8_MMA(1, 0, At, B0); PG8_MMA(1, 1, At, B1); PG8_BAR; PG8_SCHED;
;             PG8_LDB(B0, 1, 0); PG8_LDB(B1, 1, 1); PG8_SCHED; PG8_LDA(At, 1, 0); PG8_STAGE(PG8_SA(0, 1), a2 + hstepA, voffA);
;             PG8_WAIT_V(8); PG8_WAIT_L(0); PG8_BAR; PG8_MMA(0, 0, At, B0); PG8_MMA(0, 1, At, B1); PG8_BAR; PG8_SCHED;
	s_setprio 1
	s_waitcnt lgkmcnt(0)
	v_mfma_f32_16x16x32_bf16 v[64:67], v[152:155], v[184:187], v[64:67]
	v_mfma_f32_16x16x32_bf16 v[68:71], v[160:163], v[184:187], v[68:71]
	v_mfma_f32_16x16x32_bf16 v[80:83], v[152:155], v[192:195], v[80:83]
	v_mfma_f32_16x16x32_bf16 v[84:87], v[160:163], v[192:195], v[84:87]
	v_mfma_f32_16x16x32_bf16 v[96:99], v[152:155], v[200:203], v[96:99]
	v_mfma_f32_16x16x32_bf16 v[100:103], v[160:163], v[200:203], v[100:103]
	v_mfma_f32_16x16x32_bf16 v[116:119], v[152:155], v[208:211], v[116:119]
	v_mfma_f32_16x16x32_bf16 v[120:123], v[160:163], v[208:211], v[120:123]
	v_mfma_f32_16x16x32_bf16 v[64:67], v[156:159], v[188:191], v[64:67]
	v_mfma_f32_16x16x32_bf16 v[68:71], v[164:167], v[188:191], v[68:71]
	v_mfma_f32_16x16x32_bf16 v[80:83], v[156:159], v[196:199], v[80:83]
	v_mfma_f32_16x16x32_bf16 v[84:87], v[164:167], v[196:199], v[84:87]
	v_mfma_f32_16x16x32_bf16 v[96:99], v[156:159], v[204:207], v[96:99]
	v_mfma_f32_16x16x32_bf16 v[100:103], v[164:167], v[204:207], v[100:103]
	v_mfma_f32_16x16x32_bf16 v[116:119], v[156:159], v[212:215], v[116:119]
	v_mfma_f32_16x16x32_bf16 v[120:123], v[164:167], v[212:215], v[120:123]
	s_setprio 0
	s_setprio 1
	v_mfma_f32_16x16x32_bf16 v[72:75], v[168:171], v[184:187], v[72:75]
	v_mfma_f32_16x16x32_bf16 v[76:79], v[176:179], v[184:187], v[76:79]
	v_mfma_f32_16x16x32_bf16 v[88:91], v[168:171], v[192:195], v[88:91]
	v_mfma_f32_16x16x32_bf16 v[92:95], v[176:179], v[192:195], v[92:95]
	v_mfma_f32_16x16x32_bf16 v[104:107], v[168:171], v[200:203], v[104:107]
	v_mfma_f32_16x16x32_bf16 v[108:111], v[176:179], v[200:203], v[108:111]
	v_mfma_f32_16x16x32_bf16 v[124:127], v[168:171], v[208:211], v[124:127]
	v_mfma_f32_16x16x32_bf16 v[128:131], v[176:179], v[208:211], v[128:131]
	v_mfma_f32_16x16x32_bf16 v[72:75], v[172:175], v[188:191], v[72:75]
	v_mfma_f32_16x16x32_bf16 v[76:79], v[180:183], v[188:191], v[76:79]
	v_mfma_f32_16x16x32_bf16 v[88:91], v[172:175], v[196:199], v[88:91]
	v_mfma_f32_16x16x32_bf16 v[92:95], v[180:183], v[196:199], v[92:95]
	v_mfma_f32_16x16x32_bf16 v[104:107], v[172:175], v[204:207], v[104:107]
	v_mfma_f32_16x16x32_bf16 v[108:111], v[180:183], v[204:207], v[108:111]
	v_mfma_f32_16x16x32_bf16 v[124:127], v[172:175], v[212:215], v[124:127]
	v_mfma_f32_16x16x32_bf16 v[128:131], v[180:183], v[212:215], v[128:131]
	s_setprio 0
	s_barrier
	s_add_i32 s53, 0, 0x18000
	v_add_u32_e32 v151, s53, v145
	s_add_i32 s74, 0, 0x1c000
	ds_read_b128 v[152:155], v151
	ds_read_b128 v[156:159], v151 offset:1024
	ds_read_b128 v[160:163], v151 offset:2048
	ds_read_b128 v[164:167], v151 offset:3072
	v_add_u32_e32 v151, s74, v145
	ds_read_b128 v[168:171], v151
	ds_read_b128 v[172:175], v151 offset:1024
	ds_read_b128 v[176:179], v151 offset:2048
	ds_read_b128 v[180:183], v151 offset:3072
	s_add_u32 s56, s56, 0x40000
	s_addc_u32 s57, s57, 0
	s_mov_b32 m0, s62
	v_lshl_add_u64 v[224:225], s[56:57], 0, v[134:135]
	ds_read_b128 v[184:187], v149 offset:32768
	ds_read_b128 v[188:191], v149 offset:33792
	ds_read_b128 v[192:195], v149 offset:34816
	ds_read_b128 v[196:199], v149 offset:35840
	ds_read_b128 v[200:203], v149 offset:36864
	ds_read_b128 v[204:207], v149 offset:37888
	ds_read_b128 v[208:211], v149 offset:38912
	ds_read_b128 v[212:215], v149 offset:39936
	global_load_lds_dwordx4 v[224:225], off
	v_lshl_add_u64 v[224:225], s[56:57], 0, v[132:133]
	s_mov_b32 m0, s63
	s_nop 0
	global_load_lds_dwordx4 v[224:225], off
	s_waitcnt vmcnt(8)
	s_waitcnt lgkmcnt(0)
	s_barrier
	s_setprio 1
	s_waitcnt lgkmcnt(0)
	v_mfma_f32_16x16x32_bf16 v[0:3], v[152:155], v[184:187], v[0:3]
	v_mfma_f32_16x16x32_bf16 v[4:7], v[160:163], v[184:187], v[4:7]
	v_mfma_f32_16x16x32_bf16 v[16:19], v[152:155], v[192:195], v[16:19]
	v_mfma_f32_16x16x32_bf16 v[20:23], v[160:163], v[192:195], v[20:23]
	v_mfma_f32_16x16x32_bf16 v[32:35], v[152:155], v[200:203], v[32:35]
	v_mfma_f32_16x16x32_bf16 v[36:39], v[160:163], v[200:203], v[36:39]
	v_mfma_f32_16x16x32_bf16 v[48:51], v[152:155], v[208:211], v[48:51]
	v_mfma_f32_16x16x32_bf16 v[52:55], v[160:163], v[208:211], v[52:55]
	v_mfma_f32_16x16x32_bf16 v[0:3], v[156:159], v[188:191], v[0:3]
	v_mfma_f32_16x16x32_bf16 v[4:7], v[164:167], v[188:191], v[4:7]
	v_mfma_f32_16x16x32_bf16 v[16:19], v[156:159], v[196:199], v[16:19]
	v_mfma_f32_16x16x32_bf16 v[20:23], v[164:167], v[196:199], v[20:23]
	v_mfma_f32_16x16x32_bf16 v[32:35], v[156:159], v[204:207], v[32:35]
	v_mfma_f32_16x16x32_bf16 v[36:39], v[164:167], v[204:207], v[36:39]
	v_mfma_f32_16x16x32_bf16 v[48:51], v[156:159], v[212:215], v[48:51]
	v_mfma_f32_16x16x32_bf16 v[52:55], v[164:167], v[212:215], v[52:55]
	s_setprio 0
	s_setprio 1
	v_mfma_f32_16x16x32_bf16 v[8:11], v[168:171], v[184:187], v[8:11]
	v_mfma_f32_16x16x32_bf16 v[12:15], v[176:179], v[184:187], v[12:15]
	v_mfma_f32_16x16x32_bf16 v[24:27], v[168:171], v[192:195], v[24:27]
	v_mfma_f32_16x16x32_bf16 v[28:31], v[176:179], v[192:195], v[28:31]
	v_mfma_f32_16x16x32_bf16 v[40:43], v[168:171], v[200:203], v[40:43]
	v_mfma_f32_16x16x32_bf16 v[44:47], v[176:179], v[200:203], v[44:47]
	v_mfma_f32_16x16x32_bf16 v[56:59], v[168:171], v[208:211], v[56:59]
	v_mfma_f32_16x16x32_bf16 v[60:63], v[176:179], v[208:211], v[60:63]
	v_mfma_f32_16x16x32_bf16 v[8:11], v[172:175], v[188:191], v[8:11]
	v_mfma_f32_16x16x32_bf16 v[12:15], v[180:183], v[188:191], v[12:15]
	v_mfma_f32_16x16x32_bf16 v[24:27], v[172:175], v[196:199], v[24:27]
	v_mfma_f32_16x16x32_bf16 v[28:31], v[180:183], v[196:199], v[28:31]
	v_mfma_f32_16x16x32_bf16 v[40:43], v[172:175], v[204:207], v[40:43]
	v_mfma_f32_16x16x32_bf16 v[44:47], v[180:183], v[204:207], v[44:47]
	v_mfma_f32_16x16x32_bf16 v[56:59], v[172:175], v[212:215], v[56:59]
	v_mfma_f32_16x16x32_bf16 v[60:63], v[180:183], v[212:215], v[60:63]
	s_setprio 0
	s_barrier
; #define PG8_STAGE(bufoff, gbase, voff) do { _Pragma("unroll") for (int _i = 0; _i < 2; ++_i) \
;         __builtin_amdgcn_global_load_lds((const unsigned*)((const char*)(gbase) + (voff)[_i]), (PG8_LAS unsigned*)(lds + (bufoff) + ldsw + _i * 8192), 16, 0, 0); } while (0)
; #define PG8_LDA(dst, b, h) do { _Pragma("unroll") for (int m = 0; m < 4; ++m) _Pragma("unroll") for (int k = 0; k < 2; ++k) dst[m][k] = *(const PG8_LAS bf16x8*)(lds + PG8_SA(b, h) + aoff + m * 2048 + k * 1024); } while (0)
; #define PG8_MMA(ai, bj, At, Bt) do { __builtin_amdgcn_s_setprio(1); _Pragma("unroll") for (int m = 0; m < 4; ++m) _Pragma("unroll") for (int n = 0; n < 2; ++n) _Pragma("unroll") for (int k = 0; k < 2; ++k) \
;         acc[ai][bj][m][n] = __builtin_amdgcn_mfma_f32_16x16x32_bf16(Bt[n][k], At[m][k], acc[ai][bj][m][n], 0, 0, 0); __builtin_amdgcn_s_setprio(0); } while (0)
; #define PG8_WAIT_V(n) asm volatile("s_waitcnt vmcnt(" #n ")" ::: "memory")
; #define PG8_WAIT_L(n) asm volatile("s_waitcnt lgkmcnt(" #n ")" ::: "memory")
; #define PG8_BAR __builtin_amdgcn_s_barrier()
; #define PG8_SCHED __builtin_amdgcn_sched_barrier(0)
; template <class Epi, class Sched, bool ALIGN_EPI = false, bool SP2 = false>
; __device__ __forceinline__ void gemm_phase(PG8_LAS unsigned char* lds, const Gemm g, const Sched& S, const Epi& E, const int tid_in) {
;     ...
;             PG8_LDA(At, 1, 1); PG8_STAGE(PG8_SB(1, 0), b3, voffB); PG8_STAGE(PG8_SB(1, 1), b3 + hstepB, voffB); PG8_STAGE(PG8_SA(1, 0), a3, voffA);
;             PG8_WAIT_V(8); PG8_WAIT_L(0); PG8_BAR; PG8_MMA(1, 0, At, B0); PG8_MMA(1, 1, At, B1); PG8_BAR; PG8_SCHED;
	s_add_i32 s53, s53, s59
	v_lshl_add_u64 v[216:217], v[216:217], 0, s[10:11]
	s_mov_b32 m0, s53
	ds_read_b128 v[184:187], v149 offset:49152
	ds_read_b128 v[188:191], v149 offset:50176
	ds_read_b128 v[192:195], v149 offset:51200
	ds_read_b128 v[196:199], v149 offset:52224
	ds_read_b128 v[200:203], v149 offset:53248
	ds_read_b128 v[204:207], v149 offset:54272
	ds_read_b128 v[208:211], v149 offset:55296
	ds_read_b128 v[212:215], v149 offset:56320
	global_load_lds_dwordx4 v[216:217], off
	s_add_i32 m0, s53, 0x2000
	s_add_u32 s54, s54, 0x40080
	v_lshl_add_u64 v[216:217], v[218:219], 0, s[10:11]
	s_addc_u32 s55, s55, 0
	s_add_i32 s53, s74, s59
	global_load_lds_dwordx4 v[216:217], off
	v_lshl_add_u64 v[216:217], s[54:55], 0, v[114:115]
	s_mov_b32 m0, s53
	s_nop 0
	global_load_lds_dwordx4 v[216:217], off
	v_lshl_add_u64 v[216:217], s[54:55], 0, v[112:113]
	s_add_i32 m0, s53, 0x2000
	s_nop 0
	global_load_lds_dwordx4 v[216:217], off
	v_lshl_add_u64 v[216:217], v[220:221], 0, s[10:11]
	s_mov_b32 m0, s66
	s_nop 0
	global_load_lds_dwordx4 v[216:217], off
	v_lshl_add_u64 v[216:217], v[222:223], 0, s[10:11]
	s_mov_b32 m0, s67
	s_nop 0
	global_load_lds_dwordx4 v[216:217], off
	s_waitcnt vmcnt(8)
	s_waitcnt lgkmcnt(0)
	s_barrier
	s_setprio 1
	s_waitcnt lgkmcnt(0)
	v_mfma_f32_16x16x32_bf16 v[64:67], v[152:155], v[184:187], v[64:67]
	v_mfma_f32_16x16x32_bf16 v[68:71], v[160:163], v[184:187], v[68:71]
	v_mfma_f32_16x16x32_bf16 v[80:83], v[152:155], v[192:195], v[80:83]
	v_mfma_f32_16x16x32_bf16 v[84:87], v[160:163], v[192:195], v[84:87]
	v_mfma_f32_16x16x32_bf16 v[96:99], v[152:155], v[200:203], v[96:99]
	v_mfma_f32_16x16x32_bf16 v[100:103], v[160:163], v[200:203], v[100:103]
	v_mfma_f32_16x16x32_bf16 v[116:119], v[152:155], v[208:211], v[116:119]
	v_mfma_f32_16x16x32_bf16 v[120:123], v[160:163], v[208:211], v[120:123]
	v_mfma_f32_16x16x32_bf16 v[64:67], v[156:159], v[188:191], v[64:67]
	v_mfma_f32_16x16x32_bf16 v[68:71], v[164:167], v[188:191], v[68:71]
	v_mfma_f32_16x16x32_bf16 v[80:83], v[156:159], v[196:199], v[80:83]
	v_mfma_f32_16x16x32_bf16 v[84:87], v[164:167], v[196:199], v[84:87]
	v_mfma_f32_16x16x32_bf16 v[96:99], v[156:159], v[204:207], v[96:99]
	v_mfma_f32_16x16x32_bf16 v[100:103], v[164:167], v[204:207], v[100:103]
	v_mfma_f32_16x16x32_bf16 v[116:119], v[156:159], v[212:215], v[116:119]
	v_mfma_f32_16x16x32_bf16 v[120:123], v[164:167], v[212:215], v[120:123]
	s_setprio 0
	s_setprio 1
	v_mfma_f32_16x16x32_bf16 v[72:75], v[168:171], v[184:187], v[72:75]
	v_mfma_f32_16x16x32_bf16 v[76:79], v[176:179], v[184:187], v[76:79]
	v_mfma_f32_16x16x32_bf16 v[88:91], v[168:171], v[192:195], v[88:91]
	v_mfma_f32_16x16x32_bf16 v[92:95], v[176:179], v[192:195], v[92:95]
	v_mfma_f32_16x16x32_bf16 v[104:107], v[168:171], v[200:203], v[104:107]
	v_mfma_f32_16x16x32_bf16 v[108:111], v[176:179], v[200:203], v[108:111]
	v_mfma_f32_16x16x32_bf16 v[124:127], v[168:171], v[208:211], v[124:127]
	v_mfma_f32_16x16x32_bf16 v[128:131], v[176:179], v[208:211], v[128:131]
	v_mfma_f32_16x16x32_bf16 v[72:75], v[172:175], v[188:191], v[72:75]
	v_mfma_f32_16x16x32_bf16 v[76:79], v[180:183], v[188:191], v[76:79]
	v_mfma_f32_16x16x32_bf16 v[88:91], v[172:175], v[196:199], v[88:91]
	v_mfma_f32_16x16x32_bf16 v[92:95], v[180:183], v[196:199], v[92:95]
	v_mfma_f32_16x16x32_bf16 v[104:107], v[172:175], v[204:207], v[104:107]
	v_mfma_f32_16x16x32_bf16 v[108:111], v[180:183], v[204:207], v[108:111]
	v_mfma_f32_16x16x32_bf16 v[124:127], v[172:175], v[212:215], v[124:127]
	v_mfma_f32_16x16x32_bf16 v[128:131], v[180:183], v[212:215], v[128:131]
	s_setprio 0
	s_barrier
	s_add_i32 s29, s29, 2
	s_add_u32 s40, s40, 0x100
	s_addc_u32 s41, s41, 0
	s_cmp_gt_u32 s29, 13
	s_cbranch_scc0 .LBB0_508
	s_and_b64 vcc, exec, s[26:27]
	s_cbranch_vccz .LBB0_511
	s_barrier

;   __device__ __forceinline__ bool next(int i,AttnUnit&u)const{ const int p=vcu+(i>>1)*grid; if(p>=BATCH*NHEAD*4)return false; const int q=(p&31)+32*(p>>8), s=(q<32)?(q&3):(3-(q&3)); u.bh=((p>>5)&7)*NHEAD+((q<32)?(q>>2):(NHEAD-1-((q-32)>>2)));     u.qb=(i&1)?s:(NQB-1-s); u.reuse=i&1; return true; }
;     __host__ __device__ __forceinline__ bool next(int i, Unit& u) const {
;         const long L = (long)i * G + c; if (L >= nwg) return false;
;         int wgid = (int)L; { const int q = nwg / NXCD, r = nwg % NXCD, xcd = wgid % NXCD, off = wgid / NXCD; wgid = (xcd < r ? xcd * (q + 1) : r * (q + 1) + (xcd - r) * q) + off; }
;         const int nig = WGM * nN, gid = wgid / nig, fm = gid * WGM, gsz = (nM - fm) < WGM ? (nM - fm) : WGM;
;         u.pm = fm + ((wgid % nig) % gsz); u.pn = (wgid % nig) / gsz; return true;
; template <class Epi, class Sched, bool ALIGN_EPI = false, bool SP2 = false>
; __device__ __forceinline__ void gemm_phase(PG8_LAS unsigned char* lds, const Gemm g, const Sched& S, const Epi& E, const int tid_in) {
;     ...
;         const bool has_next = S.next(ui + 1, nxt);
.LBB0_606:
	s_add_i32 s14, s14, 1
	v_readlane_b32 s4, v253, 16
	s_mul_i32 s4, s14, s4
	s_mul_hi_u32 s5, s14, s3
	s_add_i32 s5, s5, s4
	s_mul_i32 s4, s14, s3
	s_add_u32 s4, s4, s2
	s_addc_u32 s5, s5, s33
	v_mov_b64_e32 v[0:1], 0x400
	v_cmp_lt_i64_e64 s[40:41], s[4:5], v[0:1]
	s_nop 3
	s_mov_b32 s100, s40
	v_mov_b64_e32 v[0:1], 0x3ff
	v_cmp_gt_i64_e32 vcc, s[4:5], v[0:1]
	s_cbranch_vccnz .LBB0_612
	s_ashr_i32 s5, s4, 31
	s_lshr_b32 s5, s5, 29
	s_add_i32 s50, s4, s5
	s_and_b32 s5, s50, -8
	s_sub_i32 s51, s4, s5
	s_cmp_gt_i32 s51, -1
	s_mov_b64 s[4:5], -1
	s_cbranch_scc0 .LBB0_609
	s_lshl_b32 s52, s51, 7
	s_mov_b64 s[4:5], 0

; #define PG8_STAGE(bufoff, gbase, voff) do { _Pragma("unroll") for (int _i = 0; _i < 2; ++_i) \
;         __builtin_amdgcn_global_load_lds((const unsigned*)((const char*)(gbase) + (voff)[_i]), (PG8_LAS unsigned*)(lds + (bufoff) + ldsw + _i * 8192), 16, 0, 0); } while (0)
; #define PG8_LDA(dst, b, h) do { _Pragma("unroll") for (int m = 0; m < 4; ++m) _Pragma("unroll") for (int k = 0; k < 2; ++k) dst[m][k] = *(const PG8_LAS bf16x8*)(lds + PG8_SA(b, h) + aoff + m * 2048 + k * 1024); } while (0)
; #define PG8_LDB(dst, b, h) do { _Pragma("unroll") for (int n = 0; n < 2; ++n) _Pragma("unroll") for (int k = 0; k < 2; ++k) dst[n][k] = *(const PG8_LAS bf16x8*)(lds + PG8_SB(b, h) + boff + n * 2048 + k * 1024); } while (0)
; #define PG8_MMA(ai, bj, At, Bt) do { __builtin_amdgcn_s_setprio(1); _Pragma("unroll") for (int m = 0; m < 4; ++m) _Pragma("unroll") for (int n = 0; n < 2; ++n) _Pragma("unroll") for (int k = 0; k < 2; ++k) \
;         acc[ai][bj][m][n] = __builtin_amdgcn_mfma_f32_16x16x32_bf16(Bt[n][k], At[m][k], acc[ai][bj][m][n], 0, 0, 0); __builtin_amdgcn_s_setprio(0); } while (0)
; #define PG8_WAIT_V(n) asm volatile("s_waitcnt vmcnt(" #n ")" ::: "memory")
; #define PG8_WAIT_L(n) asm volatile("s_waitcnt lgkmcnt(" #n ")" ::: "memory")
; #define PG8_BAR __builtin_amdgcn_s_barrier()
; #define PG8_SCHED __builtin_amdgcn_sched_barrier(0)
; template <class Epi, class Sched, bool ALIGN_EPI = false, bool SP2 = false>
; __device__ __forceinline__ void gemm_phase(PG8_LAS unsigned char* lds, const Gemm g, const Sched& S, const Epi& E, const int tid_in) {
;     ...
;             const bool last = (t == nt - 2);
;             const char* a1 = cA + (size_t)(t + 1) * kstep;
;             const char* a2 = last ? nA : cA + (size_t)(t + 2) * kstep; const char* b2 = last ? nB : cB + (size_t)(t + 2) * kstep;
;             const char* a3 = a2 + kstep; const char* b3 = b2 + kstep;
;             if (last && has_next) S.a_ready(nxt);
;             if constexpr (SP2) {
;             PG8_LDB(B0, 0, 0); PG8_LDB(B1, 0, 1); PG8_SCHED; PG8_LDA(At, 0, 0); PG8_STAGE(PG8_SA(1, 1), a1 + hstepA, voffA);
;             PG8_WAIT_V(8); PG8_WAIT_L(0); PG8_BAR; PG8_MMA(0, 0, At, B0); PG8_MMA(0, 1, At, B1); PG8_BAR; PG8_SCHED;
;             PG8_LDA(At, 0, 1); PG8_STAGE(PG8_SB(0, 0), b2, voffB); PG8_STAGE(PG8_SB(0, 1), b2 + hstepB, voffB); PG8_STAGE(PG8_SA(0, 0), a2, voffA);
.LBB0_613:
	s_add_u32 s4, s0, 0xfffc0080
	s_addc_u32 s5, s1, -1
	s_add_i32 s66, 0, 0x10000
	s_cmp_eq_u32 s65, 12
	s_cselect_b32 s21, s53, s5
	s_cselect_b32 s20, s61, s4
	s_cselect_b32 s5, s51, s64
	s_cselect_b32 s4, s62, s63
	s_cmp_lg_u32 s65, 12
	s_cbranch_scc1 .Ltail_keep_gin
	s_cmp_lg_u32 s100, 0
	s_cbranch_scc1 .Ltail_keep_gin
	v_mov_b32_e32 v114, 0
	v_mov_b32_e32 v158, 0
	v_mov_b32_e32 v156, 0
	v_mov_b32_e32 v112, 0
.Ltail_keep_gin:
	s_add_i32 s70, 0, 0x14000
	v_add_u32_e32 v144, s66, v176
	v_add_u32_e32 v168, s70, v176
	ds_read_b128 v[132:135], v144
	ds_read_b128 v[136:139], v144 offset:1024
	ds_read_b128 v[140:143], v144 offset:2048
	ds_read_b128 v[144:147], v144 offset:3072
	ds_read_b128 v[148:151], v168
	ds_read_b128 v[152:155], v168 offset:1024
	ds_read_b128 v[164:167], v168 offset:2048
	ds_read_b128 v[168:171], v168 offset:3072
	v_lshl_add_u64 v[174:175], s[0:1], 0, v[160:161]
	s_add_i32 m0, s26, 0xc000
	ds_read_b128 v[180:183], v179
	ds_read_b128 v[184:187], v179 offset:1024
	ds_read_b128 v[188:191], v179 offset:2048
	ds_read_b128 v[192:195], v179 offset:3072
	ds_read_b128 v[196:199], v179 offset:4096
	ds_read_b128 v[204:207], v179 offset:5120
	ds_read_b128 v[208:211], v179 offset:6144
	ds_read_b128 v[212:215], v179 offset:7168
	global_load_lds_dwordx4 v[174:175], off
	v_lshl_add_u64 v[174:175], s[0:1], 0, v[162:163]
	s_add_i32 m0, s26, 0xe000
	s_nop 0
	global_load_lds_dwordx4 v[174:175], off
	s_waitcnt vmcnt(8)
	s_waitcnt lgkmcnt(0)
	s_barrier
	s_setprio 1
	s_waitcnt lgkmcnt(0)
	v_mfma_f32_16x16x32_bf16 v[128:131], v[132:135], v[180:183], v[128:131]
	v_mfma_f32_16x16x32_bf16 v[124:127], v[140:143], v[180:183], v[124:127]
	v_mfma_f32_16x16x32_bf16 v[108:111], v[132:135], v[188:191], v[108:111]
	v_mfma_f32_16x16x32_bf16 v[104:107], v[140:143], v[188:191], v[104:107]
	v_mfma_f32_16x16x32_bf16 v[92:95], v[132:135], v[196:199], v[92:95]
	v_mfma_f32_16x16x32_bf16 v[88:91], v[140:143], v[196:199], v[88:91]
	v_mfma_f32_16x16x32_bf16 v[76:79], v[132:135], v[208:211], v[76:79]
	v_mfma_f32_16x16x32_bf16 v[72:75], v[140:143], v[208:211], v[72:75]
	v_mfma_f32_16x16x32_bf16 v[128:131], v[136:139], v[184:187], v[128:131]
	v_mfma_f32_16x16x32_bf16 v[124:127], v[144:147], v[184:187], v[124:127]
	v_mfma_f32_16x16x32_bf16 v[108:111], v[136:139], v[192:195], v[108:111]
	v_mfma_f32_16x16x32_bf16 v[104:107], v[144:147], v[192:195], v[104:107]
	v_mfma_f32_16x16x32_bf16 v[92:95], v[136:139], v[204:207], v[92:95]
	v_mfma_f32_16x16x32_bf16 v[88:91], v[144:147], v[204:207], v[88:91]
	v_mfma_f32_16x16x32_bf16 v[76:79], v[136:139], v[212:215], v[76:79]
	v_mfma_f32_16x16x32_bf16 v[72:75], v[144:147], v[212:215], v[72:75]
	s_setprio 0
	s_setprio 1
	v_mfma_f32_16x16x32_bf16 v[120:123], v[148:151], v[180:183], v[120:123]
	v_mfma_f32_16x16x32_bf16 v[116:119], v[164:167], v[180:183], v[116:119]
	v_mfma_f32_16x16x32_bf16 v[100:103], v[148:151], v[188:191], v[100:103]
	v_mfma_f32_16x16x32_bf16 v[96:99], v[164:167], v[188:191], v[96:99]
	v_mfma_f32_16x16x32_bf16 v[84:87], v[148:151], v[196:199], v[84:87]
	v_mfma_f32_16x16x32_bf16 v[80:83], v[164:167], v[196:199], v[80:83]
	v_mfma_f32_16x16x32_bf16 v[68:71], v[148:151], v[208:211], v[68:71]
	v_mfma_f32_16x16x32_bf16 v[64:67], v[164:167], v[208:211], v[64:67]
	v_mfma_f32_16x16x32_bf16 v[120:123], v[152:155], v[184:187], v[120:123]
	v_mfma_f32_16x16x32_bf16 v[116:119], v[168:171], v[184:187], v[116:119]
	v_mfma_f32_16x16x32_bf16 v[100:103], v[152:155], v[192:195], v[100:103]
	v_mfma_f32_16x16x32_bf16 v[96:99], v[168:171], v[192:195], v[96:99]
	v_mfma_f32_16x16x32_bf16 v[84:87], v[152:155], v[204:207], v[84:87]
	v_mfma_f32_16x16x32_bf16 v[80:83], v[168:171], v[204:207], v[80:83]
	v_mfma_f32_16x16x32_bf16 v[68:71], v[152:155], v[212:215], v[68:71]
	v_mfma_f32_16x16x32_bf16 v[64:67], v[168:171], v[212:215], v[64:67]
	s_setprio 0
	s_barrier
	s_add_i32 s66, s66, s13
	v_lshl_add_u64 v[174:175], s[4:5], 0, v[114:115]
	s_mov_b32 m0, s66
	ds_read_b128 v[180:183], v179 offset:16384
	ds_read_b128 v[184:187], v179 offset:17408
	ds_read_b128 v[188:191], v179 offset:18432
	ds_read_b128 v[192:195], v179 offset:19456
	ds_read_b128 v[196:199], v179 offset:20480
	ds_read_b128 v[204:207], v179 offset:21504
	ds_read_b128 v[208:211], v179 offset:22528
	ds_read_b128 v[212:215], v179 offset:23552
	global_load_lds_dwordx4 v[174:175], off
	s_add_i32 m0, s66, 0x2000
	s_add_u32 s66, s4, 0x40000
	v_lshl_add_u64 v[200:201], s[4:5], 0, v[158:159]
	s_addc_u32 s67, s5, 0
	s_add_i32 s70, s70, s13
	global_load_lds_dwordx4 v[200:201], off
	v_lshl_add_u64 v[202:203], s[66:67], 0, v[114:115]
	s_mov_b32 m0, s70
	v_lshl_add_u64 v[216:217], s[20:21], 0, v[156:157]
	global_load_lds_dwordx4 v[202:203], off
	v_lshl_add_u64 v[202:203], s[66:67], 0, v[158:159]
	s_add_i32 m0, s70, 0x2000
	s_nop 0
	global_load_lds_dwordx4 v[202:203], off
	v_lshl_add_u64 v[202:203], s[20:21], 0, v[112:113]
	s_mov_b32 m0, s26
	s_nop 0
	global_load_lds_dwordx4 v[202:203], off
	s_mov_b32 m0, s27
	s_nop 0
	global_load_lds_dwordx4 v[216:217], off
	s_waitcnt vmcnt(8)
	s_waitcnt lgkmcnt(0)
	s_barrier
; #define PG8_STAGE(bufoff, gbase, voff) do { _Pragma("unroll") for (int _i = 0; _i < 2; ++_i) \
;         __builtin_amdgcn_global_load_lds((const unsigned*)((const char*)(gbase) + (voff)[_i]), (PG8_LAS unsigned*)(lds + (bufoff) + ldsw + _i * 8192), 16, 0, 0); } while (0)
; #define PG8_LDA(dst, b, h) do { _Pragma("unroll") for (int m = 0; m < 4; ++m) _Pragma("unroll") for (int k = 0; k < 2; ++k) dst[m][k] = *(const PG8_LAS bf16x8*)(lds + PG8_SA(b, h) + aoff + m * 2048 + k * 1024); } while (0)
; #define PG8_LDB(dst, b, h) do { _Pragma("unroll") for (int n = 0; n < 2; ++n) _Pragma("unroll") for (int k = 0; k < 2; ++k) dst[n][k] = *(const PG8_LAS bf16x8*)(lds + PG8_SB(b, h) + boff + n * 2048 + k * 1024); } while (0)
; #define PG8_MMA(ai, bj, At, Bt) do { __builtin_amdgcn_s_setprio(1); _Pragma("unroll") for (int m = 0; m < 4; ++m) _Pragma("unroll") for (int n = 0; n < 2; ++n) _Pragma("unroll") for (int k = 0; k < 2; ++k) \
;         acc[ai][bj][m][n] = __builtin_amdgcn_mfma_f32_16x16x32_bf16(Bt[n][k], At[m][k], acc[ai][bj][m][n], 0, 0, 0); __builtin_amdgcn_s_setprio(0); } while (0)
; #define PG8_WAIT_V(n) asm volatile("s_waitcnt vmcnt(" #n ")" ::: "memory")
; #define PG8_WAIT_L(n) asm volatile("s_waitcnt lgkmcnt(" #n ")" ::: "memory")
; #define PG8_BAR __builtin_amdgcn_s_barrier()
; #define PG8_SCHED __builtin_amdgcn_sched_barrier(0)
; template <class Epi, class Sched, bool ALIGN_EPI = false, bool SP2 = false>
; __device__ __forceinline__ void gemm_phase(PG8_LAS unsigned char* lds, const Gemm g, const Sched& S, const Epi& E, const int tid_in) {
;     ...
;             PG8_WAIT_V(8); PG8_WAIT_L(0); PG8_BAR; PG8_MMA(1, 0, At, B0); PG8_MMA(1, 1, At, B1); PG8_BAR; PG8_SCHED;
;             PG8_LDB(B0, 1, 0); PG8_LDB(B1, 1, 1); PG8_SCHED; PG8_LDA(At, 1, 0); PG8_STAGE(PG8_SA(0, 1), a2 + hstepA, voffA);
;             PG8_WAIT_V(8); PG8_WAIT_L(0); PG8_BAR; PG8_MMA(0, 0, At, B0); PG8_MMA(0, 1, At, B1); PG8_BAR; PG8_SCHED;
	s_setprio 1
	s_waitcnt lgkmcnt(0)
	v_mfma_f32_16x16x32_bf16 v[60:63], v[132:135], v[180:183], v[60:63]
	v_mfma_f32_16x16x32_bf16 v[56:59], v[140:143], v[180:183], v[56:59]
	v_mfma_f32_16x16x32_bf16 v[44:47], v[132:135], v[188:191], v[44:47]
	v_mfma_f32_16x16x32_bf16 v[40:43], v[140:143], v[188:191], v[40:43]
	v_mfma_f32_16x16x32_bf16 v[28:31], v[132:135], v[196:199], v[28:31]
	v_mfma_f32_16x16x32_bf16 v[24:27], v[140:143], v[196:199], v[24:27]
	v_mfma_f32_16x16x32_bf16 v[12:15], v[132:135], v[208:211], v[12:15]
	v_mfma_f32_16x16x32_bf16 v[8:11], v[140:143], v[208:211], v[8:11]
	v_mfma_f32_16x16x32_bf16 v[60:63], v[136:139], v[184:187], v[60:63]
	v_mfma_f32_16x16x32_bf16 v[56:59], v[144:147], v[184:187], v[56:59]
	v_mfma_f32_16x16x32_bf16 v[44:47], v[136:139], v[192:195], v[44:47]
	v_mfma_f32_16x16x32_bf16 v[40:43], v[144:147], v[192:195], v[40:43]
	v_mfma_f32_16x16x32_bf16 v[28:31], v[136:139], v[204:207], v[28:31]
	v_mfma_f32_16x16x32_bf16 v[24:27], v[144:147], v[204:207], v[24:27]
	v_mfma_f32_16x16x32_bf16 v[12:15], v[136:139], v[212:215], v[12:15]
	v_mfma_f32_16x16x32_bf16 v[8:11], v[144:147], v[212:215], v[8:11]
	s_setprio 0
	s_setprio 1
	v_mfma_f32_16x16x32_bf16 v[52:55], v[148:151], v[180:183], v[52:55]
	v_mfma_f32_16x16x32_bf16 v[48:51], v[164:167], v[180:183], v[48:51]
	v_mfma_f32_16x16x32_bf16 v[36:39], v[148:151], v[188:191], v[36:39]
	v_mfma_f32_16x16x32_bf16 v[32:35], v[164:167], v[188:191], v[32:35]
	v_mfma_f32_16x16x32_bf16 v[20:23], v[148:151], v[196:199], v[20:23]
	v_mfma_f32_16x16x32_bf16 v[16:19], v[164:167], v[196:199], v[16:19]
	v_mfma_f32_16x16x32_bf16 v[4:7], v[148:151], v[208:211], v[4:7]
	v_mfma_f32_16x16x32_bf16 v[0:3], v[164:167], v[208:211], v[0:3]
	v_mfma_f32_16x16x32_bf16 v[52:55], v[152:155], v[184:187], v[52:55]
	v_mfma_f32_16x16x32_bf16 v[48:51], v[168:171], v[184:187], v[48:51]
	v_mfma_f32_16x16x32_bf16 v[36:39], v[152:155], v[192:195], v[36:39]
	v_mfma_f32_16x16x32_bf16 v[32:35], v[168:171], v[192:195], v[32:35]
	v_mfma_f32_16x16x32_bf16 v[20:23], v[152:155], v[204:207], v[20:23]
	v_mfma_f32_16x16x32_bf16 v[16:19], v[168:171], v[204:207], v[16:19]
	v_mfma_f32_16x16x32_bf16 v[4:7], v[152:155], v[212:215], v[4:7]
	v_mfma_f32_16x16x32_bf16 v[0:3], v[168:171], v[212:215], v[0:3]
	s_setprio 0
	s_barrier
	s_add_i32 s66, 0, 0x18000
	s_add_i32 s67, 0, 0x1c000
	v_add_u32_e32 v144, s66, v176
	v_add_u32_e32 v168, s67, v176
	ds_read_b128 v[132:135], v144
	ds_read_b128 v[136:139], v144 offset:1024
	ds_read_b128 v[140:143], v144 offset:2048
	ds_read_b128 v[144:147], v144 offset:3072
	ds_read_b128 v[148:151], v168
	ds_read_b128 v[152:155], v168 offset:1024
	ds_read_b128 v[164:167], v168 offset:2048
	ds_read_b128 v[168:171], v168 offset:3072
	s_add_u32 s20, s20, 0x40000
	s_addc_u32 s21, s21, 0
	s_mov_b32 m0, s28
	v_lshl_add_u64 v[218:219], s[20:21], 0, v[112:113]
	ds_read_b128 v[180:183], v179 offset:32768
	ds_read_b128 v[184:187], v179 offset:33792
	ds_read_b128 v[188:191], v179 offset:34816
	ds_read_b128 v[192:195], v179 offset:35840
	ds_read_b128 v[196:199], v179 offset:36864
	ds_read_b128 v[204:207], v179 offset:37888
	ds_read_b128 v[208:211], v179 offset:38912
	ds_read_b128 v[212:215], v179 offset:39936
	global_load_lds_dwordx4 v[218:219], off
	v_lshl_add_u64 v[218:219], s[20:21], 0, v[156:157]
	s_mov_b32 m0, s29
	s_nop 0
	global_load_lds_dwordx4 v[218:219], off
	s_waitcnt vmcnt(8)
	s_waitcnt lgkmcnt(0)
	s_barrier
	s_setprio 1
	s_waitcnt lgkmcnt(0)
	v_mfma_f32_16x16x32_bf16 v[128:131], v[132:135], v[180:183], v[128:131]
	v_mfma_f32_16x16x32_bf16 v[124:127], v[140:143], v[180:183], v[124:127]
	v_mfma_f32_16x16x32_bf16 v[108:111], v[132:135], v[188:191], v[108:111]
	v_mfma_f32_16x16x32_bf16 v[104:107], v[140:143], v[188:191], v[104:107]
	v_mfma_f32_16x16x32_bf16 v[92:95], v[132:135], v[196:199], v[92:95]
	v_mfma_f32_16x16x32_bf16 v[88:91], v[140:143], v[196:199], v[88:91]
	v_mfma_f32_16x16x32_bf16 v[76:79], v[132:135], v[208:211], v[76:79]
	v_mfma_f32_16x16x32_bf16 v[72:75], v[140:143], v[208:211], v[72:75]
	v_mfma_f32_16x16x32_bf16 v[128:131], v[136:139], v[184:187], v[128:131]
	v_mfma_f32_16x16x32_bf16 v[124:127], v[144:147], v[184:187], v[124:127]
	v_mfma_f32_16x16x32_bf16 v[108:111], v[136:139], v[192:195], v[108:111]
	v_mfma_f32_16x16x32_bf16 v[104:107], v[144:147], v[192:195], v[104:107]
	v_mfma_f32_16x16x32_bf16 v[92:95], v[136:139], v[204:207], v[92:95]
	v_mfma_f32_16x16x32_bf16 v[88:91], v[144:147], v[204:207], v[88:91]
	v_mfma_f32_16x16x32_bf16 v[76:79], v[136:139], v[212:215], v[76:79]
	v_mfma_f32_16x16x32_bf16 v[72:75], v[144:147], v[212:215], v[72:75]
	s_setprio 0
	s_setprio 1
	v_mfma_f32_16x16x32_bf16 v[120:123], v[148:151], v[180:183], v[120:123]
	v_mfma_f32_16x16x32_bf16 v[116:119], v[164:167], v[180:183], v[116:119]
	v_mfma_f32_16x16x32_bf16 v[100:103], v[148:151], v[188:191], v[100:103]
	v_mfma_f32_16x16x32_bf16 v[96:99], v[164:167], v[188:191], v[96:99]
	v_mfma_f32_16x16x32_bf16 v[84:87], v[148:151], v[196:199], v[84:87]
	v_mfma_f32_16x16x32_bf16 v[80:83], v[164:167], v[196:199], v[80:83]
	v_mfma_f32_16x16x32_bf16 v[68:71], v[148:151], v[208:211], v[68:71]
	v_mfma_f32_16x16x32_bf16 v[64:67], v[164:167], v[208:211], v[64:67]
	v_mfma_f32_16x16x32_bf16 v[120:123], v[152:155], v[184:187], v[120:123]
	v_mfma_f32_16x16x32_bf16 v[116:119], v[168:171], v[184:187], v[116:119]
	v_mfma_f32_16x16x32_bf16 v[100:103], v[152:155], v[192:195], v[100:103]
	v_mfma_f32_16x16x32_bf16 v[96:99], v[168:171], v[192:195], v[96:99]
	v_mfma_f32_16x16x32_bf16 v[84:87], v[152:155], v[204:207], v[84:87]
	v_mfma_f32_16x16x32_bf16 v[80:83], v[168:171], v[204:207], v[80:83]
	v_mfma_f32_16x16x32_bf16 v[68:71], v[152:155], v[212:215], v[68:71]
	v_mfma_f32_16x16x32_bf16 v[64:67], v[168:171], v[212:215], v[64:67]
	s_setprio 0
	s_barrier
; #define PG8_STAGE(bufoff, gbase, voff) do { _Pragma("unroll") for (int _i = 0; _i < 2; ++_i) \
;         __builtin_amdgcn_global_load_lds((const unsigned*)((const char*)(gbase) + (voff)[_i]), (PG8_LAS unsigned*)(lds + (bufoff) + ldsw + _i * 8192), 16, 0, 0); } while (0)
; #define PG8_LDA(dst, b, h) do { _Pragma("unroll") for (int m = 0; m < 4; ++m) _Pragma("unroll") for (int k = 0; k < 2; ++k) dst[m][k] = *(const PG8_LAS bf16x8*)(lds + PG8_SA(b, h) + aoff + m * 2048 + k * 1024); } while (0)
; #define PG8_MMA(ai, bj, At, Bt) do { __builtin_amdgcn_s_setprio(1); _Pragma("unroll") for (int m = 0; m < 4; ++m) _Pragma("unroll") for (int n = 0; n < 2; ++n) _Pragma("unroll") for (int k = 0; k < 2; ++k) \
;         acc[ai][bj][m][n] = __builtin_amdgcn_mfma_f32_16x16x32_bf16(Bt[n][k], At[m][k], acc[ai][bj][m][n], 0, 0, 0); __builtin_amdgcn_s_setprio(0); } while (0)
; #define PG8_WAIT_V(n) asm volatile("s_waitcnt vmcnt(" #n ")" ::: "memory")
; #define PG8_WAIT_L(n) asm volatile("s_waitcnt lgkmcnt(" #n ")" ::: "memory")
; #define PG8_BAR __builtin_amdgcn_s_barrier()
; #define PG8_SCHED __builtin_amdgcn_sched_barrier(0)
; template <class Epi, class Sched, bool ALIGN_EPI = false, bool SP2 = false>
; __device__ __forceinline__ void gemm_phase(PG8_LAS unsigned char* lds, const Gemm g, const Sched& S, const Epi& E, const int tid_in) {
;     ...
;             PG8_LDA(At, 1, 1); PG8_STAGE(PG8_SB(1, 0), b3, voffB); PG8_STAGE(PG8_SB(1, 1), b3 + hstepB, voffB); PG8_STAGE(PG8_SA(1, 0), a3, voffA);
;             PG8_WAIT_V(8); PG8_WAIT_L(0); PG8_BAR; PG8_MMA(1, 0, At, B0); PG8_MMA(1, 1, At, B1); PG8_BAR; PG8_SCHED;
	s_add_i32 s20, s66, s13
	v_lshl_add_u64 v[174:175], v[174:175], 0, s[10:11]
	s_mov_b32 m0, s20
	ds_read_b128 v[180:183], v179 offset:49152
	ds_read_b128 v[184:187], v179 offset:50176
	ds_read_b128 v[188:191], v179 offset:51200
	ds_read_b128 v[192:195], v179 offset:52224
	ds_read_b128 v[196:199], v179 offset:53248
	ds_read_b128 v[204:207], v179 offset:54272
	ds_read_b128 v[208:211], v179 offset:55296
	ds_read_b128 v[212:215], v179 offset:56320
	global_load_lds_dwordx4 v[174:175], off
	s_add_i32 m0, s20, 0x2000
	s_add_u32 s4, s4, 0x40080
	v_lshl_add_u64 v[174:175], v[200:201], 0, s[10:11]
	s_addc_u32 s5, s5, 0
	s_add_i32 s20, s67, s13
	global_load_lds_dwordx4 v[174:175], off
	v_lshl_add_u64 v[174:175], s[4:5], 0, v[114:115]
	s_mov_b32 m0, s20
	s_nop 0
	global_load_lds_dwordx4 v[174:175], off
	v_lshl_add_u64 v[174:175], s[4:5], 0, v[158:159]
	s_add_i32 m0, s20, 0x2000
	s_nop 0
	global_load_lds_dwordx4 v[174:175], off
	v_lshl_add_u64 v[174:175], v[202:203], 0, s[10:11]
	s_mov_b32 m0, s58
	s_nop 0
	global_load_lds_dwordx4 v[174:175], off
	v_lshl_add_u64 v[174:175], v[216:217], 0, s[10:11]
	s_mov_b32 m0, s59
	s_nop 0
	global_load_lds_dwordx4 v[174:175], off
	s_waitcnt vmcnt(8)
	s_waitcnt lgkmcnt(0)
	s_barrier
	s_setprio 1
	s_waitcnt lgkmcnt(0)
	v_mfma_f32_16x16x32_bf16 v[60:63], v[132:135], v[180:183], v[60:63]
	v_mfma_f32_16x16x32_bf16 v[56:59], v[140:143], v[180:183], v[56:59]
	v_mfma_f32_16x16x32_bf16 v[44:47], v[132:135], v[188:191], v[44:47]
	v_mfma_f32_16x16x32_bf16 v[40:43], v[140:143], v[188:191], v[40:43]
	v_mfma_f32_16x16x32_bf16 v[28:31], v[132:135], v[196:199], v[28:31]
	v_mfma_f32_16x16x32_bf16 v[24:27], v[140:143], v[196:199], v[24:27]
	v_mfma_f32_16x16x32_bf16 v[12:15], v[132:135], v[208:211], v[12:15]
	v_mfma_f32_16x16x32_bf16 v[8:11], v[140:143], v[208:211], v[8:11]
	v_mfma_f32_16x16x32_bf16 v[60:63], v[136:139], v[184:187], v[60:63]
	v_mfma_f32_16x16x32_bf16 v[56:59], v[144:147], v[184:187], v[56:59]
	v_mfma_f32_16x16x32_bf16 v[44:47], v[136:139], v[192:195], v[44:47]
	v_mfma_f32_16x16x32_bf16 v[40:43], v[144:147], v[192:195], v[40:43]
	v_mfma_f32_16x16x32_bf16 v[28:31], v[136:139], v[204:207], v[28:31]
	v_mfma_f32_16x16x32_bf16 v[24:27], v[144:147], v[204:207], v[24:27]
	v_mfma_f32_16x16x32_bf16 v[12:15], v[136:139], v[212:215], v[12:15]
	v_mfma_f32_16x16x32_bf16 v[8:11], v[144:147], v[212:215], v[8:11]
	s_setprio 0
	s_setprio 1
	v_mfma_f32_16x16x32_bf16 v[52:55], v[148:151], v[180:183], v[52:55]
	v_mfma_f32_16x16x32_bf16 v[48:51], v[164:167], v[180:183], v[48:51]
	v_mfma_f32_16x16x32_bf16 v[36:39], v[148:151], v[188:191], v[36:39]
	v_mfma_f32_16x16x32_bf16 v[32:35], v[164:167], v[188:191], v[32:35]
	v_mfma_f32_16x16x32_bf16 v[20:23], v[148:151], v[196:199], v[20:23]
	v_mfma_f32_16x16x32_bf16 v[16:19], v[164:167], v[196:199], v[16:19]
	v_mfma_f32_16x16x32_bf16 v[4:7], v[148:151], v[208:211], v[4:7]
	v_mfma_f32_16x16x32_bf16 v[0:3], v[164:167], v[208:211], v[0:3]
	v_mfma_f32_16x16x32_bf16 v[52:55], v[152:155], v[184:187], v[52:55]
	v_mfma_f32_16x16x32_bf16 v[48:51], v[168:171], v[184:187], v[48:51]
	v_mfma_f32_16x16x32_bf16 v[36:39], v[152:155], v[192:195], v[36:39]
	v_mfma_f32_16x16x32_bf16 v[32:35], v[168:171], v[192:195], v[32:35]
	v_mfma_f32_16x16x32_bf16 v[20:23], v[152:155], v[204:207], v[20:23]
	v_mfma_f32_16x16x32_bf16 v[16:19], v[168:171], v[204:207], v[16:19]
	v_mfma_f32_16x16x32_bf16 v[4:7], v[152:155], v[212:215], v[4:7]
	v_mfma_f32_16x16x32_bf16 v[0:3], v[168:171], v[212:215], v[0:3]
	s_setprio 0
	s_barrier
	s_add_i32 s65, s65, 2
	s_add_u32 s0, s0, 0x100
	s_addc_u32 s1, s1, 0
	s_add_u32 s63, s63, 0x100
	s_addc_u32 s64, s64, 0
	s_cmp_gt_u32 s65, 13
	s_cbranch_scc0 .LBB0_613
	s_and_b64 vcc, exec, s[18:19]
	s_cbranch_vccz .LBB0_616
	s_barrier

;   __device__ __forceinline__ bool next(int i,AttnUnit&u)const{ const int p=vcu+(i>>1)*grid; if(p>=BATCH*NHEAD*4)return false; const int q=(p&31)+32*(p>>8), s=(q<32)?(q&3):(3-(q&3)); u.bh=((p>>5)&7)*NHEAD+((q<32)?(q>>2):(NHEAD-1-((q-32)>>2)));     u.qb=(i&1)?s:(NQB-1-s); u.reuse=i&1; return true; }
;     __host__ __device__ __forceinline__ bool next(int i, Unit& u) const {
;         const long L = (long)i * G + c; if (L >= nwg) return false;
;         int wgid = (int)L; { const int q = nwg / NXCD, r = nwg % NXCD, xcd = wgid % NXCD, off = wgid / NXCD; wgid = (xcd < r ? xcd * (q + 1) : r * (q + 1) + (xcd - r) * q) + off; }
;         const int nig = WGM * nN, gid = wgid / nig, fm = gid * WGM, gsz = (nM - fm) < WGM ? (nM - fm) : WGM;
;         u.pm = fm + ((wgid % nig) % gsz); u.pn = (wgid % nig) / gsz; return true;
; template <class Epi, class Sched, bool ALIGN_EPI = false, bool SP2 = false>
; __device__ __forceinline__ void gemm_phase(PG8_LAS unsigned char* lds, const Gemm g, const Sched& S, const Epi& E, const int tid_in) {
;     ...
;         const bool has_next = S.next(ui + 1, nxt);
.LBB0_787:
	s_add_i32 s64, s65, 1
	s_mul_i32 s9, s64, s3
	s_mul_hi_i32 s8, s64, s3
	s_add_u32 s14, s9, s2
	s_addc_u32 s15, s8, s33
	v_mov_b64_e32 v[140:141], 0x100
	v_cmp_lt_i64_e64 s[38:39], s[14:15], v[140:141]
	s_nop 3
	s_mov_b32 s100, s38
	v_mov_b64_e32 v[140:141], 0xff
	v_cmp_gt_i64_e64 s[8:9], s[14:15], v[140:141]
	s_and_b64 vcc, exec, s[8:9]
	s_cbranch_vccnz .LBB0_793
	s_ashr_i32 s15, s14, 31
	s_lshr_b32 s15, s15, 29
	s_add_i32 s24, s14, s15
	s_and_b32 s15, s24, -8
	s_sub_i32 s25, s14, s15
	s_cmp_gt_i32 s25, -1
	s_mov_b64 s[14:15], -1
	s_cbranch_scc0 .LBB0_790
	s_lshl_b32 s26, s25, 5
	s_mov_b64 s[14:15], 0

; #define PG8_STAGE(bufoff, gbase, voff) do { _Pragma("unroll") for (int _i = 0; _i < 2; ++_i) \
;         __builtin_amdgcn_global_load_lds((const unsigned*)((const char*)(gbase) + (voff)[_i]), (PG8_LAS unsigned*)(lds + (bufoff) + ldsw + _i * 8192), 16, 0, 0); } while (0)
; #define PG8_LDA(dst, b, h) do { _Pragma("unroll") for (int m = 0; m < 4; ++m) _Pragma("unroll") for (int k = 0; k < 2; ++k) dst[m][k] = *(const PG8_LAS bf16x8*)(lds + PG8_SA(b, h) + aoff + m * 2048 + k * 1024); } while (0)
; #define PG8_LDB(dst, b, h) do { _Pragma("unroll") for (int n = 0; n < 2; ++n) _Pragma("unroll") for (int k = 0; k < 2; ++k) dst[n][k] = *(const PG8_LAS bf16x8*)(lds + PG8_SB(b, h) + boff + n * 2048 + k * 1024); } while (0)
; #define PG8_MMA(ai, bj, At, Bt) do { __builtin_amdgcn_s_setprio(1); _Pragma("unroll") for (int m = 0; m < 4; ++m) _Pragma("unroll") for (int n = 0; n < 2; ++n) _Pragma("unroll") for (int k = 0; k < 2; ++k) \
;         acc[ai][bj][m][n] = __builtin_amdgcn_mfma_f32_16x16x32_bf16(Bt[n][k], At[m][k], acc[ai][bj][m][n], 0, 0, 0); __builtin_amdgcn_s_setprio(0); } while (0)
; #define PG8_WAIT_V(n) asm volatile("s_waitcnt vmcnt(" #n ")" ::: "memory")
; #define PG8_WAIT_L(n) asm volatile("s_waitcnt lgkmcnt(" #n ")" ::: "memory")
; #define PG8_BAR __builtin_amdgcn_s_barrier()
; #define PG8_SCHED __builtin_amdgcn_sched_barrier(0)
; template <class Epi, class Sched, bool ALIGN_EPI = false, bool SP2 = false>
; __device__ __forceinline__ void gemm_phase(PG8_LAS unsigned char* lds, const Gemm g, const Sched& S, const Epi& E, const int tid_in) {
;     ...
;             const bool last = (t == nt - 2);
;             const char* a1 = cA + (size_t)(t + 1) * kstep;
;             const char* a2 = last ? nA : cA + (size_t)(t + 2) * kstep; const char* b2 = last ? nB : cB + (size_t)(t + 2) * kstep;
;             const char* a3 = a2 + kstep; const char* b3 = b2 + kstep;
;             if (last && has_next) S.a_ready(nxt);
;             if constexpr (SP2) {
;             PG8_LDB(B0, 0, 0); PG8_LDB(B1, 0, 1); PG8_SCHED; PG8_LDA(At, 0, 0); PG8_STAGE(PG8_SA(1, 1), a1 + hstepA, voffA);
;             PG8_WAIT_V(8); PG8_WAIT_L(0); PG8_BAR; PG8_MMA(0, 0, At, B0); PG8_MMA(0, 1, At, B1); PG8_BAR; PG8_SCHED;
;             PG8_LDA(At, 0, 1); PG8_STAGE(PG8_SB(0, 0), b2, voffB); PG8_STAGE(PG8_SB(0, 1), b2 + hstepB, voffB); PG8_STAGE(PG8_SA(0, 0), a2, voffA);
.LBB0_794:
	s_add_u32 s50, s42, s46
	s_addc_u32 s51, s43, s47
	s_add_u32 s50, s50, 0x100
	s_addc_u32 s51, s51, 0
	s_add_u32 s71, s67, s46
	s_addc_u32 s72, s70, s47
	s_add_i32 s73, 0, 0x10000
	s_cmpk_eq_i32 s46, 0xf00
	s_cselect_b32 s53, s14, s51
	s_cselect_b32 s52, s15, s50
	v_add_u32_e32 v151, s73, v145
	s_cselect_b32 s51, s25, s72
	s_cselect_b32 s50, s27, s71
	s_cmpk_lg_i32 s46, 0xf00
	s_cbranch_scc1 .Ltail_keep_gout
	s_cmp_lg_u32 s100, 0
	s_cbranch_scc1 .Ltail_keep_gout
	v_mov_b32_e32 v114, 0
	v_mov_b32_e32 v112, 0
	v_mov_b32_e32 v132, 0
	v_mov_b32_e32 v134, 0
.Ltail_keep_gout:
	s_add_i32 s71, 0, 0x14000
	ds_read_b128 v[152:155], v151
	ds_read_b128 v[156:159], v151 offset:1024
	ds_read_b128 v[160:163], v151 offset:2048
	ds_read_b128 v[164:167], v151 offset:3072
	v_add_u32_e32 v151, s71, v145
	ds_read_b128 v[168:171], v151
	ds_read_b128 v[172:175], v151 offset:1024
	ds_read_b128 v[176:179], v151 offset:2048
	ds_read_b128 v[180:183], v151 offset:3072
	v_lshl_add_u64 v[216:217], v[140:141], 0, s[46:47]
	s_add_i32 m0, s58, 0xc000
	ds_read_b128 v[184:187], v149
	ds_read_b128 v[188:191], v149 offset:1024
	ds_read_b128 v[192:195], v149 offset:2048
	ds_read_b128 v[196:199], v149 offset:3072
	ds_read_b128 v[200:203], v149 offset:4096
	ds_read_b128 v[204:207], v149 offset:5120
	ds_read_b128 v[208:211], v149 offset:6144
	ds_read_b128 v[212:215], v149 offset:7168
	global_load_lds_dwordx4 v[216:217], off
	v_lshl_add_u64 v[216:217], v[142:143], 0, s[46:47]
	s_add_i32 m0, s58, 0xe000
	s_nop 0
	global_load_lds_dwordx4 v[216:217], off
	s_waitcnt vmcnt(8)
	s_waitcnt lgkmcnt(0)
	s_barrier
	s_setprio 1
	s_waitcnt lgkmcnt(0)
	v_mfma_f32_16x16x32_bf16 v[0:3], v[152:155], v[184:187], v[0:3]
	v_mfma_f32_16x16x32_bf16 v[4:7], v[160:163], v[184:187], v[4:7]
	v_mfma_f32_16x16x32_bf16 v[16:19], v[152:155], v[192:195], v[16:19]
	v_mfma_f32_16x16x32_bf16 v[20:23], v[160:163], v[192:195], v[20:23]
	v_mfma_f32_16x16x32_bf16 v[32:35], v[152:155], v[200:203], v[32:35]
	v_mfma_f32_16x16x32_bf16 v[36:39], v[160:163], v[200:203], v[36:39]
	v_mfma_f32_16x16x32_bf16 v[48:51], v[152:155], v[208:211], v[48:51]
	v_mfma_f32_16x16x32_bf16 v[52:55], v[160:163], v[208:211], v[52:55]
	v_mfma_f32_16x16x32_bf16 v[0:3], v[156:159], v[188:191], v[0:3]
	v_mfma_f32_16x16x32_bf16 v[4:7], v[164:167], v[188:191], v[4:7]
	v_mfma_f32_16x16x32_bf16 v[16:19], v[156:159], v[196:199], v[16:19]
	v_mfma_f32_16x16x32_bf16 v[20:23], v[164:167], v[196:199], v[20:23]
	v_mfma_f32_16x16x32_bf16 v[32:35], v[156:159], v[204:207], v[32:35]
	v_mfma_f32_16x16x32_bf16 v[36:39], v[164:167], v[204:207], v[36:39]
	v_mfma_f32_16x16x32_bf16 v[48:51], v[156:159], v[212:215], v[48:51]
	v_mfma_f32_16x16x32_bf16 v[52:55], v[164:167], v[212:215], v[52:55]
	s_setprio 0
	s_setprio 1
	v_mfma_f32_16x16x32_bf16 v[8:11], v[168:171], v[184:187], v[8:11]
	v_mfma_f32_16x16x32_bf16 v[12:15], v[176:179], v[184:187], v[12:15]
	v_mfma_f32_16x16x32_bf16 v[24:27], v[168:171], v[192:195], v[24:27]
	v_mfma_f32_16x16x32_bf16 v[28:31], v[176:179], v[192:195], v[28:31]
	v_mfma_f32_16x16x32_bf16 v[40:43], v[168:171], v[200:203], v[40:43]
	v_mfma_f32_16x16x32_bf16 v[44:47], v[176:179], v[200:203], v[44:47]
	v_mfma_f32_16x16x32_bf16 v[56:59], v[168:171], v[208:211], v[56:59]
	v_mfma_f32_16x16x32_bf16 v[60:63], v[176:179], v[208:211], v[60:63]
	v_mfma_f32_16x16x32_bf16 v[8:11], v[172:175], v[188:191], v[8:11]
	v_mfma_f32_16x16x32_bf16 v[12:15], v[180:183], v[188:191], v[12:15]
	v_mfma_f32_16x16x32_bf16 v[24:27], v[172:175], v[196:199], v[24:27]
	v_mfma_f32_16x16x32_bf16 v[28:31], v[180:183], v[196:199], v[28:31]
	v_mfma_f32_16x16x32_bf16 v[40:43], v[172:175], v[204:207], v[40:43]
	v_mfma_f32_16x16x32_bf16 v[44:47], v[180:183], v[204:207], v[44:47]
	v_mfma_f32_16x16x32_bf16 v[56:59], v[172:175], v[212:215], v[56:59]
	v_mfma_f32_16x16x32_bf16 v[60:63], v[180:183], v[212:215], v[60:63]
	s_setprio 0
	s_barrier
	s_add_i32 s72, s73, s57
	v_lshl_add_u64 v[216:217], s[50:51], 0, v[114:115]
	s_mov_b32 m0, s72
	ds_read_b128 v[184:187], v149 offset:16384
	ds_read_b128 v[188:191], v149 offset:17408
	ds_read_b128 v[192:195], v149 offset:18432
	ds_read_b128 v[196:199], v149 offset:19456
	ds_read_b128 v[200:203], v149 offset:20480
	ds_read_b128 v[204:207], v149 offset:21504
	ds_read_b128 v[208:211], v149 offset:22528
	ds_read_b128 v[212:215], v149 offset:23552
	global_load_lds_dwordx4 v[216:217], off
	s_add_i32 m0, s72, 0x2000
	s_add_u32 s72, s50, 0x80000
	v_lshl_add_u64 v[218:219], s[50:51], 0, v[112:113]
	s_addc_u32 s73, s51, 0
	s_add_i32 s71, s71, s57
	global_load_lds_dwordx4 v[218:219], off
	v_lshl_add_u64 v[220:221], s[72:73], 0, v[114:115]
	s_mov_b32 m0, s71
	v_lshl_add_u64 v[222:223], s[52:53], 0, v[132:133]
	global_load_lds_dwordx4 v[220:221], off
	v_lshl_add_u64 v[220:221], s[72:73], 0, v[112:113]
	s_add_i32 m0, s71, 0x2000
	s_nop 0
	global_load_lds_dwordx4 v[220:221], off
	v_lshl_add_u64 v[220:221], s[52:53], 0, v[134:135]
	s_mov_b32 m0, s58
	s_nop 0
	global_load_lds_dwordx4 v[220:221], off
	s_mov_b32 m0, s59
	s_nop 0
	global_load_lds_dwordx4 v[222:223], off
	s_waitcnt vmcnt(8)
	s_waitcnt lgkmcnt(0)
	s_barrier
; #define PG8_STAGE(bufoff, gbase, voff) do { _Pragma("unroll") for (int _i = 0; _i < 2; ++_i) \
;         __builtin_amdgcn_global_load_lds((const unsigned*)((const char*)(gbase) + (voff)[_i]), (PG8_LAS unsigned*)(lds + (bufoff) + ldsw + _i * 8192), 16, 0, 0); } while (0)
; #define PG8_LDA(dst, b, h) do { _Pragma("unroll") for (int m = 0; m < 4; ++m) _Pragma("unroll") for (int k = 0; k < 2; ++k) dst[m][k] = *(const PG8_LAS bf16x8*)(lds + PG8_SA(b, h) + aoff + m * 2048 + k * 1024); } while (0)
; #define PG8_LDB(dst, b, h) do { _Pragma("unroll") for (int n = 0; n < 2; ++n) _Pragma("unroll") for (int k = 0; k < 2; ++k) dst[n][k] = *(const PG8_LAS bf16x8*)(lds + PG8_SB(b, h) + boff + n * 2048 + k * 1024); } while (0)
; #define PG8_MMA(ai, bj, At, Bt) do { __builtin_amdgcn_s_setprio(1); _Pragma("unroll") for (int m = 0; m < 4; ++m) _Pragma("unroll") for (int n = 0; n < 2; ++n) _Pragma("unroll") for (int k = 0; k < 2; ++k) \
;         acc[ai][bj][m][n] = __builtin_amdgcn_mfma_f32_16x16x32_bf16(Bt[n][k], At[m][k], acc[ai][bj][m][n], 0, 0, 0); __builtin_amdgcn_s_setprio(0); } while (0)
; #define PG8_WAIT_V(n) asm volatile("s_waitcnt vmcnt(" #n ")" ::: "memory")
; #define PG8_WAIT_L(n) asm volatile("s_waitcnt lgkmcnt(" #n ")" ::: "memory")
; #define PG8_BAR __builtin_amdgcn_s_barrier()
; #define PG8_SCHED __builtin_amdgcn_sched_barrier(0)
; template <class Epi, class Sched, bool ALIGN_EPI = false, bool SP2 = false>
; __device__ __forceinline__ void gemm_phase(PG8_LAS unsigned char* lds, const Gemm g, const Sched& S, const Epi& E, const int tid_in) {
;     ...
;             PG8_WAIT_V(8); PG8_WAIT_L(0); PG8_BAR; PG8_MMA(1, 0, At, B0); PG8_MMA(1, 1, At, B1); PG8_BAR; PG8_SCHED;
;             PG8_LDB(B0, 1, 0); PG8_LDB(B1, 1, 1); PG8_SCHED; PG8_LDA(At, 1, 0); PG8_STAGE(PG8_SA(0, 1), a2 + hstepA, voffA);
;             PG8_WAIT_V(8); PG8_WAIT_L(0); PG8_BAR; PG8_MMA(0, 0, At, B0); PG8_MMA(0, 1, At, B1); PG8_BAR; PG8_SCHED;
	s_setprio 1
	s_waitcnt lgkmcnt(0)
	v_mfma_f32_16x16x32_bf16 v[64:67], v[152:155], v[184:187], v[64:67]
	v_mfma_f32_16x16x32_bf16 v[68:71], v[160:163], v[184:187], v[68:71]
	v_mfma_f32_16x16x32_bf16 v[80:83], v[152:155], v[192:195], v[80:83]
	v_mfma_f32_16x16x32_bf16 v[84:87], v[160:163], v[192:195], v[84:87]
	v_mfma_f32_16x16x32_bf16 v[96:99], v[152:155], v[200:203], v[96:99]
	v_mfma_f32_16x16x32_bf16 v[100:103], v[160:163], v[200:203], v[100:103]
	v_mfma_f32_16x16x32_bf16 v[116:119], v[152:155], v[208:211], v[116:119]
	v_mfma_f32_16x16x32_bf16 v[120:123], v[160:163], v[208:211], v[120:123]
	v_mfma_f32_16x16x32_bf16 v[64:67], v[156:159], v[188:191], v[64:67]
	v_mfma_f32_16x16x32_bf16 v[68:71], v[164:167], v[188:191], v[68:71]
	v_mfma_f32_16x16x32_bf16 v[80:83], v[156:159], v[196:199], v[80:83]
	v_mfma_f32_16x16x32_bf16 v[84:87], v[164:167], v[196:199], v[84:87]
	v_mfma_f32_16x16x32_bf16 v[96:99], v[156:159], v[204:207], v[96:99]
	v_mfma_f32_16x16x32_bf16 v[100:103], v[164:167], v[204:207], v[100:103]
	v_mfma_f32_16x16x32_bf16 v[116:119], v[156:159], v[212:215], v[116:119]
	v_mfma_f32_16x16x32_bf16 v[120:123], v[164:167], v[212:215], v[120:123]
	s_setprio 0
	s_setprio 1
	v_mfma_f32_16x16x32_bf16 v[72:75], v[168:171], v[184:187], v[72:75]
	v_mfma_f32_16x16x32_bf16 v[76:79], v[176:179], v[184:187], v[76:79]
	v_mfma_f32_16x16x32_bf16 v[88:91], v[168:171], v[192:195], v[88:91]
	v_mfma_f32_16x16x32_bf16 v[92:95], v[176:179], v[192:195], v[92:95]
	v_mfma_f32_16x16x32_bf16 v[104:107], v[168:171], v[200:203], v[104:107]
	v_mfma_f32_16x16x32_bf16 v[108:111], v[176:179], v[200:203], v[108:111]
	v_mfma_f32_16x16x32_bf16 v[124:127], v[168:171], v[208:211], v[124:127]
	v_mfma_f32_16x16x32_bf16 v[128:131], v[176:179], v[208:211], v[128:131]
	v_mfma_f32_16x16x32_bf16 v[72:75], v[172:175], v[188:191], v[72:75]
	v_mfma_f32_16x16x32_bf16 v[76:79], v[180:183], v[188:191], v[76:79]
	v_mfma_f32_16x16x32_bf16 v[88:91], v[172:175], v[196:199], v[88:91]
	v_mfma_f32_16x16x32_bf16 v[92:95], v[180:183], v[196:199], v[92:95]
	v_mfma_f32_16x16x32_bf16 v[104:107], v[172:175], v[204:207], v[104:107]
	v_mfma_f32_16x16x32_bf16 v[108:111], v[180:183], v[204:207], v[108:111]
	v_mfma_f32_16x16x32_bf16 v[124:127], v[172:175], v[212:215], v[124:127]
	v_mfma_f32_16x16x32_bf16 v[128:131], v[180:183], v[212:215], v[128:131]
	s_setprio 0
	s_barrier
	s_add_i32 s71, 0, 0x18000
	v_add_u32_e32 v151, s71, v145
	s_add_i32 s72, 0, 0x1c000
	ds_read_b128 v[152:155], v151
	ds_read_b128 v[156:159], v151 offset:1024
	ds_read_b128 v[160:163], v151 offset:2048
	ds_read_b128 v[164:167], v151 offset:3072
	v_add_u32_e32 v151, s72, v145
	ds_read_b128 v[168:171], v151
	ds_read_b128 v[172:175], v151 offset:1024
	ds_read_b128 v[176:179], v151 offset:2048
	ds_read_b128 v[180:183], v151 offset:3072
	s_add_u32 s52, s52, 0x100000
	s_addc_u32 s53, s53, 0
	s_mov_b32 m0, s60
	v_lshl_add_u64 v[224:225], s[52:53], 0, v[134:135]
	ds_read_b128 v[184:187], v149 offset:32768
	ds_read_b128 v[188:191], v149 offset:33792
	ds_read_b128 v[192:195], v149 offset:34816
	ds_read_b128 v[196:199], v149 offset:35840
	ds_read_b128 v[200:203], v149 offset:36864
	ds_read_b128 v[204:207], v149 offset:37888
	ds_read_b128 v[208:211], v149 offset:38912
	ds_read_b128 v[212:215], v149 offset:39936
	global_load_lds_dwordx4 v[224:225], off
	v_lshl_add_u64 v[224:225], s[52:53], 0, v[132:133]
	s_mov_b32 m0, s61
	s_nop 0
	global_load_lds_dwordx4 v[224:225], off
	s_waitcnt vmcnt(8)
	s_waitcnt lgkmcnt(0)
	s_barrier
	s_setprio 1
	s_waitcnt lgkmcnt(0)
	v_mfma_f32_16x16x32_bf16 v[0:3], v[152:155], v[184:187], v[0:3]
	v_mfma_f32_16x16x32_bf16 v[4:7], v[160:163], v[184:187], v[4:7]
	v_mfma_f32_16x16x32_bf16 v[16:19], v[152:155], v[192:195], v[16:19]
	v_mfma_f32_16x16x32_bf16 v[20:23], v[160:163], v[192:195], v[20:23]
	v_mfma_f32_16x16x32_bf16 v[32:35], v[152:155], v[200:203], v[32:35]
	v_mfma_f32_16x16x32_bf16 v[36:39], v[160:163], v[200:203], v[36:39]
	v_mfma_f32_16x16x32_bf16 v[48:51], v[152:155], v[208:211], v[48:51]
	v_mfma_f32_16x16x32_bf16 v[52:55], v[160:163], v[208:211], v[52:55]
	v_mfma_f32_16x16x32_bf16 v[0:3], v[156:159], v[188:191], v[0:3]
	v_mfma_f32_16x16x32_bf16 v[4:7], v[164:167], v[188:191], v[4:7]
	v_mfma_f32_16x16x32_bf16 v[16:19], v[156:159], v[196:199], v[16:19]
	v_mfma_f32_16x16x32_bf16 v[20:23], v[164:167], v[196:199], v[20:23]
	v_mfma_f32_16x16x32_bf16 v[32:35], v[156:159], v[204:207], v[32:35]
	v_mfma_f32_16x16x32_bf16 v[36:39], v[164:167], v[204:207], v[36:39]
	v_mfma_f32_16x16x32_bf16 v[48:51], v[156:159], v[212:215], v[48:51]
	v_mfma_f32_16x16x32_bf16 v[52:55], v[164:167], v[212:215], v[52:55]
	s_setprio 0
	s_setprio 1
	v_mfma_f32_16x16x32_bf16 v[8:11], v[168:171], v[184:187], v[8:11]
	v_mfma_f32_16x16x32_bf16 v[12:15], v[176:179], v[184:187], v[12:15]
	v_mfma_f32_16x16x32_bf16 v[24:27], v[168:171], v[192:195], v[24:27]
	v_mfma_f32_16x16x32_bf16 v[28:31], v[176:179], v[192:195], v[28:31]
	v_mfma_f32_16x16x32_bf16 v[40:43], v[168:171], v[200:203], v[40:43]
	v_mfma_f32_16x16x32_bf16 v[44:47], v[176:179], v[200:203], v[44:47]
	v_mfma_f32_16x16x32_bf16 v[56:59], v[168:171], v[208:211], v[56:59]
	v_mfma_f32_16x16x32_bf16 v[60:63], v[176:179], v[208:211], v[60:63]
	v_mfma_f32_16x16x32_bf16 v[8:11], v[172:175], v[188:191], v[8:11]
	v_mfma_f32_16x16x32_bf16 v[12:15], v[180:183], v[188:191], v[12:15]
	v_mfma_f32_16x16x32_bf16 v[24:27], v[172:175], v[196:199], v[24:27]
	v_mfma_f32_16x16x32_bf16 v[28:31], v[180:183], v[196:199], v[28:31]
	v_mfma_f32_16x16x32_bf16 v[40:43], v[172:175], v[204:207], v[40:43]
	v_mfma_f32_16x16x32_bf16 v[44:47], v[180:183], v[204:207], v[44:47]
	v_mfma_f32_16x16x32_bf16 v[56:59], v[172:175], v[212:215], v[56:59]
	v_mfma_f32_16x16x32_bf16 v[60:63], v[180:183], v[212:215], v[60:63]
	s_setprio 0
	s_barrier
; #define PG8_STAGE(bufoff, gbase, voff) do { _Pragma("unroll") for (int _i = 0; _i < 2; ++_i) \
;         __builtin_amdgcn_global_load_lds((const unsigned*)((const char*)(gbase) + (voff)[_i]), (PG8_LAS unsigned*)(lds + (bufoff) + ldsw + _i * 8192), 16, 0, 0); } while (0)
; #define PG8_LDA(dst, b, h) do { _Pragma("unroll") for (int m = 0; m < 4; ++m) _Pragma("unroll") for (int k = 0; k < 2; ++k) dst[m][k] = *(const PG8_LAS bf16x8*)(lds + PG8_SA(b, h) + aoff + m * 2048 + k * 1024); } while (0)
; #define PG8_MMA(ai, bj, At, Bt) do { __builtin_amdgcn_s_setprio(1); _Pragma("unroll") for (int m = 0; m < 4; ++m) _Pragma("unroll") for (int n = 0; n < 2; ++n) _Pragma("unroll") for (int k = 0; k < 2; ++k) \
;         acc[ai][bj][m][n] = __builtin_amdgcn_mfma_f32_16x16x32_bf16(Bt[n][k], At[m][k], acc[ai][bj][m][n], 0, 0, 0); __builtin_amdgcn_s_setprio(0); } while (0)
; #define PG8_WAIT_V(n) asm volatile("s_waitcnt vmcnt(" #n ")" ::: "memory")
; #define PG8_WAIT_L(n) asm volatile("s_waitcnt lgkmcnt(" #n ")" ::: "memory")
; #define PG8_BAR __builtin_amdgcn_s_barrier()
; #define PG8_SCHED __builtin_amdgcn_sched_barrier(0)
; template <class Epi, class Sched, bool ALIGN_EPI = false, bool SP2 = false>
; __device__ __forceinline__ void gemm_phase(PG8_LAS unsigned char* lds, const Gemm g, const Sched& S, const Epi& E, const int tid_in) {
;     ...
;             PG8_LDA(At, 1, 1); PG8_STAGE(PG8_SB(1, 0), b3, voffB); PG8_STAGE(PG8_SB(1, 1), b3 + hstepB, voffB); PG8_STAGE(PG8_SA(1, 0), a3, voffA);
;             PG8_WAIT_V(8); PG8_WAIT_L(0); PG8_BAR; PG8_MMA(1, 0, At, B0); PG8_MMA(1, 1, At, B1); PG8_BAR; PG8_SCHED;
	s_add_i32 s52, s71, s57
	v_lshl_add_u64 v[216:217], v[216:217], 0, s[10:11]
	s_mov_b32 m0, s52
	ds_read_b128 v[184:187], v149 offset:49152
	ds_read_b128 v[188:191], v149 offset:50176
	ds_read_b128 v[192:195], v149 offset:51200
	ds_read_b128 v[196:199], v149 offset:52224
	ds_read_b128 v[200:203], v149 offset:53248
	ds_read_b128 v[204:207], v149 offset:54272
	ds_read_b128 v[208:211], v149 offset:55296
	ds_read_b128 v[212:215], v149 offset:56320
	global_load_lds_dwordx4 v[216:217], off
	s_add_i32 m0, s52, 0x2000
	s_add_u32 s50, s50, 0x80080
	v_lshl_add_u64 v[216:217], v[218:219], 0, s[10:11]
	s_addc_u32 s51, s51, 0
	s_add_i32 s52, s72, s57
	global_load_lds_dwordx4 v[216:217], off
	v_lshl_add_u64 v[216:217], s[50:51], 0, v[114:115]
	s_mov_b32 m0, s52
	s_nop 0
	global_load_lds_dwordx4 v[216:217], off
	v_lshl_add_u64 v[216:217], s[50:51], 0, v[112:113]
	s_add_i32 m0, s52, 0x2000
	s_nop 0
	global_load_lds_dwordx4 v[216:217], off
	v_lshl_add_u64 v[216:217], v[220:221], 0, s[10:11]
	s_mov_b32 m0, s62
	s_nop 0
	global_load_lds_dwordx4 v[216:217], off
	v_lshl_add_u64 v[216:217], v[222:223], 0, s[10:11]
	s_mov_b32 m0, s63
	s_nop 0
	global_load_lds_dwordx4 v[216:217], off
	s_waitcnt vmcnt(8)
	s_waitcnt lgkmcnt(0)
	s_barrier
	s_setprio 1
	s_waitcnt lgkmcnt(0)
	v_mfma_f32_16x16x32_bf16 v[64:67], v[152:155], v[184:187], v[64:67]
	v_mfma_f32_16x16x32_bf16 v[68:71], v[160:163], v[184:187], v[68:71]
	v_mfma_f32_16x16x32_bf16 v[80:83], v[152:155], v[192:195], v[80:83]
	v_mfma_f32_16x16x32_bf16 v[84:87], v[160:163], v[192:195], v[84:87]
	v_mfma_f32_16x16x32_bf16 v[96:99], v[152:155], v[200:203], v[96:99]
	v_mfma_f32_16x16x32_bf16 v[100:103], v[160:163], v[200:203], v[100:103]
	v_mfma_f32_16x16x32_bf16 v[116:119], v[152:155], v[208:211], v[116:119]
	v_mfma_f32_16x16x32_bf16 v[120:123], v[160:163], v[208:211], v[120:123]
	v_mfma_f32_16x16x32_bf16 v[64:67], v[156:159], v[188:191], v[64:67]
	v_mfma_f32_16x16x32_bf16 v[68:71], v[164:167], v[188:191], v[68:71]
	v_mfma_f32_16x16x32_bf16 v[80:83], v[156:159], v[196:199], v[80:83]
	v_mfma_f32_16x16x32_bf16 v[84:87], v[164:167], v[196:199], v[84:87]
	v_mfma_f32_16x16x32_bf16 v[96:99], v[156:159], v[204:207], v[96:99]
	v_mfma_f32_16x16x32_bf16 v[100:103], v[164:167], v[204:207], v[100:103]
	v_mfma_f32_16x16x32_bf16 v[116:119], v[156:159], v[212:215], v[116:119]
	v_mfma_f32_16x16x32_bf16 v[120:123], v[164:167], v[212:215], v[120:123]
	s_setprio 0
	s_setprio 1
	v_mfma_f32_16x16x32_bf16 v[72:75], v[168:171], v[184:187], v[72:75]
	v_mfma_f32_16x16x32_bf16 v[76:79], v[176:179], v[184:187], v[76:79]
	v_mfma_f32_16x16x32_bf16 v[88:91], v[168:171], v[192:195], v[88:91]
	v_mfma_f32_16x16x32_bf16 v[92:95], v[176:179], v[192:195], v[92:95]
	v_mfma_f32_16x16x32_bf16 v[104:107], v[168:171], v[200:203], v[104:107]
	v_mfma_f32_16x16x32_bf16 v[108:111], v[176:179], v[200:203], v[108:111]
	v_mfma_f32_16x16x32_bf16 v[124:127], v[168:171], v[208:211], v[124:127]
	v_mfma_f32_16x16x32_bf16 v[128:131], v[176:179], v[208:211], v[128:131]
	v_mfma_f32_16x16x32_bf16 v[72:75], v[172:175], v[188:191], v[72:75]
	v_mfma_f32_16x16x32_bf16 v[76:79], v[180:183], v[188:191], v[76:79]
	v_mfma_f32_16x16x32_bf16 v[88:91], v[172:175], v[196:199], v[88:91]
	v_mfma_f32_16x16x32_bf16 v[92:95], v[180:183], v[196:199], v[92:95]
	v_mfma_f32_16x16x32_bf16 v[104:107], v[172:175], v[204:207], v[104:107]
	v_mfma_f32_16x16x32_bf16 v[108:111], v[180:183], v[204:207], v[108:111]
	v_mfma_f32_16x16x32_bf16 v[124:127], v[172:175], v[212:215], v[124:127]
	v_mfma_f32_16x16x32_bf16 v[128:131], v[180:183], v[212:215], v[128:131]
	s_setprio 0
	s_barrier
	s_add_i32 s45, s45, 2
	s_add_u32 s46, s46, 0x100
	s_addc_u32 s47, s47, 0
	s_cmp_gt_u32 s45, 29
	s_cbranch_scc0 .LBB0_794
	s_and_b64 vcc, exec, s[22:23]
	s_cbranch_vccz .LBB0_797
	s_barrier

;   __device__ __forceinline__ bool next(int i,AttnUnit&u)const{ const int p=vcu+(i>>1)*grid; if(p>=BATCH*NHEAD*4)return false; const int q=(p&31)+32*(p>>8), s=(q<32)?(q&3):(3-(q&3)); u.bh=((p>>5)&7)*NHEAD+((q<32)?(q>>2):(NHEAD-1-((q-32)>>2)));     u.qb=(i&1)?s:(NQB-1-s); u.reuse=i&1; return true; }
;     __host__ __device__ __forceinline__ bool next(int i, Unit& u) const {
;         const long L = (long)i * G + c; if (L >= nwg) return false;
;         int wgid = (int)L; { const int q = nwg / NXCD, r = nwg % NXCD, xcd = wgid % NXCD, off = wgid / NXCD; wgid = (xcd < r ? xcd * (q + 1) : r * (q + 1) + (xcd - r) * q) + off; }
;         const int nig = WGM * nN, gid = wgid / nig, fm = gid * WGM, gsz = (nM - fm) < WGM ? (nM - fm) : WGM;
;         u.pm = fm + ((wgid % nig) % gsz); u.pn = (wgid % nig) / gsz; return true;
; template <class Epi, class Sched, bool ALIGN_EPI = false, bool SP2 = false>
; __device__ __forceinline__ void gemm_phase(PG8_LAS unsigned char* lds, const Gemm g, const Sched& S, const Epi& E, const int tid_in) {
;     ...
;         const bool has_next = S.next(ui + 1, nxt);
.LBB0_849:
	s_add_i32 s55, s55, 1
	v_readlane_b32 s4, v253, 16
	s_mul_i32 s4, s55, s4
	s_mul_hi_u32 s5, s55, s3
	s_add_i32 s5, s5, s4
	s_mul_i32 s4, s55, s3
	s_add_u32 s14, s4, s2
	s_addc_u32 s15, s5, s33
	v_mov_b64_e32 v[0:1], 0x400
	v_cmp_lt_i64_e64 s[4:5], s[14:15], v[0:1]
	s_nop 3
	s_mov_b32 s100, s4
	v_mov_b64_e32 v[0:1], 0x3ff
	v_cmp_gt_i64_e32 vcc, s[14:15], v[0:1]
	s_cbranch_vccnz .LBB0_855
	s_ashr_i32 s15, s14, 31
	s_lshr_b32 s15, s15, 29
	s_add_i32 s22, s14, s15
	s_and_b32 s15, s22, -8
	s_sub_i32 s23, s14, s15
	s_cmp_gt_i32 s23, -1
	s_mov_b64 s[14:15], -1
	s_cbranch_scc0 .LBB0_852
	s_lshl_b32 s24, s23, 7
	s_mov_b64 s[14:15], 0

; #define PG8_STAGE(bufoff, gbase, voff) do { _Pragma("unroll") for (int _i = 0; _i < 2; ++_i) \
;         __builtin_amdgcn_global_load_lds((const unsigned*)((const char*)(gbase) + (voff)[_i]), (PG8_LAS unsigned*)(lds + (bufoff) + ldsw + _i * 8192), 16, 0, 0); } while (0)
; #define PG8_LDA(dst, b, h) do { _Pragma("unroll") for (int m = 0; m < 4; ++m) _Pragma("unroll") for (int k = 0; k < 2; ++k) dst[m][k] = *(const PG8_LAS bf16x8*)(lds + PG8_SA(b, h) + aoff + m * 2048 + k * 1024); } while (0)
; #define PG8_LDB(dst, b, h) do { _Pragma("unroll") for (int n = 0; n < 2; ++n) _Pragma("unroll") for (int k = 0; k < 2; ++k) dst[n][k] = *(const PG8_LAS bf16x8*)(lds + PG8_SB(b, h) + boff + n * 2048 + k * 1024); } while (0)
; #define PG8_MMA(ai, bj, At, Bt) do { __builtin_amdgcn_s_setprio(1); _Pragma("unroll") for (int m = 0; m < 4; ++m) _Pragma("unroll") for (int n = 0; n < 2; ++n) _Pragma("unroll") for (int k = 0; k < 2; ++k) \
;         acc[ai][bj][m][n] = __builtin_amdgcn_mfma_f32_16x16x32_bf16(Bt[n][k], At[m][k], acc[ai][bj][m][n], 0, 0, 0); __builtin_amdgcn_s_setprio(0); } while (0)
; #define PG8_WAIT_V(n) asm volatile("s_waitcnt vmcnt(" #n ")" ::: "memory")
; #define PG8_WAIT_L(n) asm volatile("s_waitcnt lgkmcnt(" #n ")" ::: "memory")
; #define PG8_BAR __builtin_amdgcn_s_barrier()
; #define PG8_SCHED __builtin_amdgcn_sched_barrier(0)
; template <class Epi, class Sched, bool ALIGN_EPI = false, bool SP2 = false>
; __device__ __forceinline__ void gemm_phase(PG8_LAS unsigned char* lds, const Gemm g, const Sched& S, const Epi& E, const int tid_in) {
;     ...
;             const bool last = (t == nt - 2);
;             const char* a1 = cA + (size_t)(t + 1) * kstep;
;             const char* a2 = last ? nA : cA + (size_t)(t + 2) * kstep; const char* b2 = last ? nB : cB + (size_t)(t + 2) * kstep;
;             const char* a3 = a2 + kstep; const char* b3 = b2 + kstep;
;             if (last && has_next) S.a_ready(nxt);
;             if constexpr (SP2) {
;             PG8_LDB(B0, 0, 0); PG8_LDB(B1, 0, 1); PG8_SCHED; PG8_LDA(At, 0, 0); PG8_STAGE(PG8_SA(1, 1), a1 + hstepA, voffA);
;             PG8_WAIT_V(8); PG8_WAIT_L(0); PG8_BAR; PG8_MMA(0, 0, At, B0); PG8_MMA(0, 1, At, B1); PG8_BAR; PG8_SCHED;
;             PG8_LDA(At, 0, 1); PG8_STAGE(PG8_SB(0, 0), b2, voffB); PG8_STAGE(PG8_SB(0, 1), b2 + hstepB, voffB); PG8_STAGE(PG8_SA(0, 0), a2, voffA);
.LBB0_856:
	s_add_u32 s38, s6, 0xfffc0080
	s_addc_u32 s39, s7, -1
	s_add_i32 s61, 0, 0x10000
	s_cmp_eq_u32 s60, 12
	s_cselect_b32 s41, s14, s39
	s_cselect_b32 s40, s15, s38
	s_cselect_b32 s39, s23, s59
	s_cselect_b32 s38, s25, s58
	s_cmp_lg_u32 s60, 12
	s_cbranch_scc1 .Ltail_keep_up
	s_cmp_lg_u32 s100, 0
	s_cbranch_scc1 .Ltail_keep_up
	v_mov_b32_e32 v114, 0
	v_mov_b32_e32 v158, 0
	v_mov_b32_e32 v156, 0
	v_mov_b32_e32 v112, 0
.Ltail_keep_up:
	s_add_i32 s64, 0, 0x14000
	v_add_u32_e32 v144, s61, v184
	v_add_u32_e32 v168, s64, v184
	ds_read_b128 v[132:135], v144
	ds_read_b128 v[136:139], v144 offset:1024
	ds_read_b128 v[140:143], v144 offset:2048
	ds_read_b128 v[144:147], v144 offset:3072
	ds_read_b128 v[148:151], v168
	ds_read_b128 v[152:155], v168 offset:1024
	ds_read_b128 v[164:167], v168 offset:2048
	ds_read_b128 v[168:171], v168 offset:3072
	v_lshl_add_u64 v[180:181], s[6:7], 0, v[160:161]
	s_add_i32 m0, s47, 0xc000
	ds_read_b128 v[172:175], v187
	ds_read_b128 v[176:179], v187 offset:1024
	ds_read_b128 v[188:191], v187 offset:2048
	ds_read_b128 v[192:195], v187 offset:3072
	ds_read_b128 v[196:199], v187 offset:4096
	ds_read_b128 v[200:203], v187 offset:5120
	ds_read_b128 v[204:207], v187 offset:6144
	ds_read_b128 v[208:211], v187 offset:7168
	global_load_lds_dwordx4 v[180:181], off
	v_lshl_add_u64 v[180:181], s[6:7], 0, v[162:163]
	s_add_i32 m0, s47, 0xe000
	s_nop 0
	global_load_lds_dwordx4 v[180:181], off
	s_waitcnt vmcnt(8)
	s_waitcnt lgkmcnt(0)
	s_barrier
	s_setprio 1
	s_waitcnt lgkmcnt(0)
	v_mfma_f32_16x16x32_bf16 v[128:131], v[132:135], v[172:175], v[128:131]
	v_mfma_f32_16x16x32_bf16 v[124:127], v[140:143], v[172:175], v[124:127]
	v_mfma_f32_16x16x32_bf16 v[108:111], v[132:135], v[188:191], v[108:111]
	v_mfma_f32_16x16x32_bf16 v[104:107], v[140:143], v[188:191], v[104:107]
	v_mfma_f32_16x16x32_bf16 v[92:95], v[132:135], v[196:199], v[92:95]
	v_mfma_f32_16x16x32_bf16 v[88:91], v[140:143], v[196:199], v[88:91]
	v_mfma_f32_16x16x32_bf16 v[76:79], v[132:135], v[204:207], v[76:79]
	v_mfma_f32_16x16x32_bf16 v[72:75], v[140:143], v[204:207], v[72:75]
	v_mfma_f32_16x16x32_bf16 v[128:131], v[136:139], v[176:179], v[128:131]
	v_mfma_f32_16x16x32_bf16 v[124:127], v[144:147], v[176:179], v[124:127]
	v_mfma_f32_16x16x32_bf16 v[108:111], v[136:139], v[192:195], v[108:111]
	v_mfma_f32_16x16x32_bf16 v[104:107], v[144:147], v[192:195], v[104:107]
	v_mfma_f32_16x16x32_bf16 v[92:95], v[136:139], v[200:203], v[92:95]
	v_mfma_f32_16x16x32_bf16 v[88:91], v[144:147], v[200:203], v[88:91]
	v_mfma_f32_16x16x32_bf16 v[76:79], v[136:139], v[208:211], v[76:79]
	v_mfma_f32_16x16x32_bf16 v[72:75], v[144:147], v[208:211], v[72:75]
	s_setprio 0
	s_setprio 1
	v_mfma_f32_16x16x32_bf16 v[120:123], v[148:151], v[172:175], v[120:123]
	v_mfma_f32_16x16x32_bf16 v[116:119], v[164:167], v[172:175], v[116:119]
	v_mfma_f32_16x16x32_bf16 v[100:103], v[148:151], v[188:191], v[100:103]
	v_mfma_f32_16x16x32_bf16 v[96:99], v[164:167], v[188:191], v[96:99]
	v_mfma_f32_16x16x32_bf16 v[84:87], v[148:151], v[196:199], v[84:87]
	v_mfma_f32_16x16x32_bf16 v[80:83], v[164:167], v[196:199], v[80:83]
	v_mfma_f32_16x16x32_bf16 v[68:71], v[148:151], v[204:207], v[68:71]
	v_mfma_f32_16x16x32_bf16 v[64:67], v[164:167], v[204:207], v[64:67]
	v_mfma_f32_16x16x32_bf16 v[120:123], v[152:155], v[176:179], v[120:123]
	v_mfma_f32_16x16x32_bf16 v[116:119], v[168:171], v[176:179], v[116:119]
	v_mfma_f32_16x16x32_bf16 v[100:103], v[152:155], v[192:195], v[100:103]
	v_mfma_f32_16x16x32_bf16 v[96:99], v[168:171], v[192:195], v[96:99]
	v_mfma_f32_16x16x32_bf16 v[84:87], v[152:155], v[200:203], v[84:87]
	v_mfma_f32_16x16x32_bf16 v[80:83], v[168:171], v[200:203], v[80:83]
	v_mfma_f32_16x16x32_bf16 v[68:71], v[152:155], v[208:211], v[68:71]
	v_mfma_f32_16x16x32_bf16 v[64:67], v[168:171], v[208:211], v[64:67]
	s_setprio 0
	s_barrier
	s_add_i32 s61, s61, s42
	v_lshl_add_u64 v[180:181], s[38:39], 0, v[114:115]
	s_mov_b32 m0, s61
	ds_read_b128 v[172:175], v187 offset:16384
	ds_read_b128 v[176:179], v187 offset:17408
	ds_read_b128 v[188:191], v187 offset:18432
	ds_read_b128 v[192:195], v187 offset:19456
	ds_read_b128 v[196:199], v187 offset:20480
	ds_read_b128 v[200:203], v187 offset:21504
	ds_read_b128 v[204:207], v187 offset:22528
	ds_read_b128 v[208:211], v187 offset:23552
	global_load_lds_dwordx4 v[180:181], off
	s_add_i32 m0, s61, 0x2000
	s_add_u32 s62, s38, 0x40000
	v_lshl_add_u64 v[212:213], s[38:39], 0, v[158:159]
	s_addc_u32 s63, s39, 0
	s_add_i32 s61, s64, s42
	global_load_lds_dwordx4 v[212:213], off
	v_lshl_add_u64 v[214:215], s[62:63], 0, v[114:115]
	s_mov_b32 m0, s61
	v_lshl_add_u64 v[216:217], s[40:41], 0, v[156:157]
	global_load_lds_dwordx4 v[214:215], off
	v_lshl_add_u64 v[214:215], s[62:63], 0, v[158:159]
	s_add_i32 m0, s61, 0x2000
	s_nop 0
	global_load_lds_dwordx4 v[214:215], off
	v_lshl_add_u64 v[214:215], s[40:41], 0, v[112:113]
	s_mov_b32 m0, s47
	s_nop 0
	global_load_lds_dwordx4 v[214:215], off
	s_mov_b32 m0, s50
	s_nop 0
	global_load_lds_dwordx4 v[216:217], off
	s_waitcnt vmcnt(8)
	s_waitcnt lgkmcnt(0)
	s_barrier
; #define PG8_STAGE(bufoff, gbase, voff) do { _Pragma("unroll") for (int _i = 0; _i < 2; ++_i) \
;         __builtin_amdgcn_global_load_lds((const unsigned*)((const char*)(gbase) + (voff)[_i]), (PG8_LAS unsigned*)(lds + (bufoff) + ldsw + _i * 8192), 16, 0, 0); } while (0)
; #define PG8_LDA(dst, b, h) do { _Pragma("unroll") for (int m = 0; m < 4; ++m) _Pragma("unroll") for (int k = 0; k < 2; ++k) dst[m][k] = *(const PG8_LAS bf16x8*)(lds + PG8_SA(b, h) + aoff + m * 2048 + k * 1024); } while (0)
; #define PG8_LDB(dst, b, h) do { _Pragma("unroll") for (int n = 0; n < 2; ++n) _Pragma("unroll") for (int k = 0; k < 2; ++k) dst[n][k] = *(const PG8_LAS bf16x8*)(lds + PG8_SB(b, h) + boff + n * 2048 + k * 1024); } while (0)
; #define PG8_MMA(ai, bj, At, Bt) do { __builtin_amdgcn_s_setprio(1); _Pragma("unroll") for (int m = 0; m < 4; ++m) _Pragma("unroll") for (int n = 0; n < 2; ++n) _Pragma("unroll") for (int k = 0; k < 2; ++k) \
;         acc[ai][bj][m][n] = __builtin_amdgcn_mfma_f32_16x16x32_bf16(Bt[n][k], At[m][k], acc[ai][bj][m][n], 0, 0, 0); __builtin_amdgcn_s_setprio(0); } while (0)
; #define PG8_WAIT_V(n) asm volatile("s_waitcnt vmcnt(" #n ")" ::: "memory")
; #define PG8_WAIT_L(n) asm volatile("s_waitcnt lgkmcnt(" #n ")" ::: "memory")
; #define PG8_BAR __builtin_amdgcn_s_barrier()
; #define PG8_SCHED __builtin_amdgcn_sched_barrier(0)
; template <class Epi, class Sched, bool ALIGN_EPI = false, bool SP2 = false>
; __device__ __forceinline__ void gemm_phase(PG8_LAS unsigned char* lds, const Gemm g, const Sched& S, const Epi& E, const int tid_in) {
;     ...
;             PG8_WAIT_V(8); PG8_WAIT_L(0); PG8_BAR; PG8_MMA(1, 0, At, B0); PG8_MMA(1, 1, At, B1); PG8_BAR; PG8_SCHED;
;             PG8_LDB(B0, 1, 0); PG8_LDB(B1, 1, 1); PG8_SCHED; PG8_LDA(At, 1, 0); PG8_STAGE(PG8_SA(0, 1), a2 + hstepA, voffA);
;             PG8_WAIT_V(8); PG8_WAIT_L(0); PG8_BAR; PG8_MMA(0, 0, At, B0); PG8_MMA(0, 1, At, B1); PG8_BAR; PG8_SCHED;
	s_setprio 1
	s_waitcnt lgkmcnt(0)
	v_mfma_f32_16x16x32_bf16 v[60:63], v[132:135], v[172:175], v[60:63]
	v_mfma_f32_16x16x32_bf16 v[56:59], v[140:143], v[172:175], v[56:59]
	v_mfma_f32_16x16x32_bf16 v[44:47], v[132:135], v[188:191], v[44:47]
	v_mfma_f32_16x16x32_bf16 v[40:43], v[140:143], v[188:191], v[40:43]
	v_mfma_f32_16x16x32_bf16 v[28:31], v[132:135], v[196:199], v[28:31]
	v_mfma_f32_16x16x32_bf16 v[24:27], v[140:143], v[196:199], v[24:27]
	v_mfma_f32_16x16x32_bf16 v[12:15], v[132:135], v[204:207], v[12:15]
	v_mfma_f32_16x16x32_bf16 v[8:11], v[140:143], v[204:207], v[8:11]
	v_mfma_f32_16x16x32_bf16 v[60:63], v[136:139], v[176:179], v[60:63]
	v_mfma_f32_16x16x32_bf16 v[56:59], v[144:147], v[176:179], v[56:59]
	v_mfma_f32_16x16x32_bf16 v[44:47], v[136:139], v[192:195], v[44:47]
	v_mfma_f32_16x16x32_bf16 v[40:43], v[144:147], v[192:195], v[40:43]
	v_mfma_f32_16x16x32_bf16 v[28:31], v[136:139], v[200:203], v[28:31]
	v_mfma_f32_16x16x32_bf16 v[24:27], v[144:147], v[200:203], v[24:27]
	v_mfma_f32_16x16x32_bf16 v[12:15], v[136:139], v[208:211], v[12:15]
	v_mfma_f32_16x16x32_bf16 v[8:11], v[144:147], v[208:211], v[8:11]
	s_setprio 0
	s_setprio 1
	v_mfma_f32_16x16x32_bf16 v[52:55], v[148:151], v[172:175], v[52:55]
	v_mfma_f32_16x16x32_bf16 v[48:51], v[164:167], v[172:175], v[48:51]
	v_mfma_f32_16x16x32_bf16 v[36:39], v[148:151], v[188:191], v[36:39]
	v_mfma_f32_16x16x32_bf16 v[32:35], v[164:167], v[188:191], v[32:35]
	v_mfma_f32_16x16x32_bf16 v[20:23], v[148:151], v[196:199], v[20:23]
	v_mfma_f32_16x16x32_bf16 v[16:19], v[164:167], v[196:199], v[16:19]
	v_mfma_f32_16x16x32_bf16 v[4:7], v[148:151], v[204:207], v[4:7]
	v_mfma_f32_16x16x32_bf16 v[0:3], v[164:167], v[204:207], v[0:3]
	v_mfma_f32_16x16x32_bf16 v[52:55], v[152:155], v[176:179], v[52:55]
	v_mfma_f32_16x16x32_bf16 v[48:51], v[168:171], v[176:179], v[48:51]
	v_mfma_f32_16x16x32_bf16 v[36:39], v[152:155], v[192:195], v[36:39]
	v_mfma_f32_16x16x32_bf16 v[32:35], v[168:171], v[192:195], v[32:35]
	v_mfma_f32_16x16x32_bf16 v[20:23], v[152:155], v[200:203], v[20:23]
	v_mfma_f32_16x16x32_bf16 v[16:19], v[168:171], v[200:203], v[16:19]
	v_mfma_f32_16x16x32_bf16 v[4:7], v[152:155], v[208:211], v[4:7]
	v_mfma_f32_16x16x32_bf16 v[0:3], v[168:171], v[208:211], v[0:3]
	s_setprio 0
	s_barrier
	s_add_i32 s61, 0, 0x18000
	s_add_i32 s62, 0, 0x1c000
	v_add_u32_e32 v144, s61, v184
	v_add_u32_e32 v168, s62, v184
	ds_read_b128 v[132:135], v144
	ds_read_b128 v[136:139], v144 offset:1024
	ds_read_b128 v[140:143], v144 offset:2048
	ds_read_b128 v[144:147], v144 offset:3072
	ds_read_b128 v[148:151], v168
	ds_read_b128 v[152:155], v168 offset:1024
	ds_read_b128 v[164:167], v168 offset:2048
	ds_read_b128 v[168:171], v168 offset:3072
	s_add_u32 s40, s40, 0x40000
	s_addc_u32 s41, s41, 0
	s_mov_b32 m0, s51
	v_lshl_add_u64 v[218:219], s[40:41], 0, v[112:113]
	ds_read_b128 v[172:175], v187 offset:32768
	ds_read_b128 v[176:179], v187 offset:33792
	ds_read_b128 v[188:191], v187 offset:34816
	ds_read_b128 v[192:195], v187 offset:35840
	ds_read_b128 v[196:199], v187 offset:36864
	ds_read_b128 v[200:203], v187 offset:37888
	ds_read_b128 v[204:207], v187 offset:38912
	ds_read_b128 v[208:211], v187 offset:39936
	global_load_lds_dwordx4 v[218:219], off
	v_lshl_add_u64 v[218:219], s[40:41], 0, v[156:157]
	s_mov_b32 m0, s52
	s_nop 0
	global_load_lds_dwordx4 v[218:219], off
	s_waitcnt vmcnt(8)
	s_waitcnt lgkmcnt(0)
	s_barrier
	s_setprio 1
	s_waitcnt lgkmcnt(0)
	v_mfma_f32_16x16x32_bf16 v[128:131], v[132:135], v[172:175], v[128:131]
	v_mfma_f32_16x16x32_bf16 v[124:127], v[140:143], v[172:175], v[124:127]
	v_mfma_f32_16x16x32_bf16 v[108:111], v[132:135], v[188:191], v[108:111]
	v_mfma_f32_16x16x32_bf16 v[104:107], v[140:143], v[188:191], v[104:107]
	v_mfma_f32_16x16x32_bf16 v[92:95], v[132:135], v[196:199], v[92:95]
	v_mfma_f32_16x16x32_bf16 v[88:91], v[140:143], v[196:199], v[88:91]
	v_mfma_f32_16x16x32_bf16 v[76:79], v[132:135], v[204:207], v[76:79]
	v_mfma_f32_16x16x32_bf16 v[72:75], v[140:143], v[204:207], v[72:75]
	v_mfma_f32_16x16x32_bf16 v[128:131], v[136:139], v[176:179], v[128:131]
	v_mfma_f32_16x16x32_bf16 v[124:127], v[144:147], v[176:179], v[124:127]
	v_mfma_f32_16x16x32_bf16 v[108:111], v[136:139], v[192:195], v[108:111]
	v_mfma_f32_16x16x32_bf16 v[104:107], v[144:147], v[192:195], v[104:107]
	v_mfma_f32_16x16x32_bf16 v[92:95], v[136:139], v[200:203], v[92:95]
	v_mfma_f32_16x16x32_bf16 v[88:91], v[144:147], v[200:203], v[88:91]
	v_mfma_f32_16x16x32_bf16 v[76:79], v[136:139], v[208:211], v[76:79]
	v_mfma_f32_16x16x32_bf16 v[72:75], v[144:147], v[208:211], v[72:75]
	s_setprio 0
	s_setprio 1
	v_mfma_f32_16x16x32_bf16 v[120:123], v[148:151], v[172:175], v[120:123]
	v_mfma_f32_16x16x32_bf16 v[116:119], v[164:167], v[172:175], v[116:119]
	v_mfma_f32_16x16x32_bf16 v[100:103], v[148:151], v[188:191], v[100:103]
	v_mfma_f32_16x16x32_bf16 v[96:99], v[164:167], v[188:191], v[96:99]
	v_mfma_f32_16x16x32_bf16 v[84:87], v[148:151], v[196:199], v[84:87]
	v_mfma_f32_16x16x32_bf16 v[80:83], v[164:167], v[196:199], v[80:83]
	v_mfma_f32_16x16x32_bf16 v[68:71], v[148:151], v[204:207], v[68:71]
	v_mfma_f32_16x16x32_bf16 v[64:67], v[164:167], v[204:207], v[64:67]
	v_mfma_f32_16x16x32_bf16 v[120:123], v[152:155], v[176:179], v[120:123]
	v_mfma_f32_16x16x32_bf16 v[116:119], v[168:171], v[176:179], v[116:119]
	v_mfma_f32_16x16x32_bf16 v[100:103], v[152:155], v[192:195], v[100:103]
	v_mfma_f32_16x16x32_bf16 v[96:99], v[168:171], v[192:195], v[96:99]
	v_mfma_f32_16x16x32_bf16 v[84:87], v[152:155], v[200:203], v[84:87]
	v_mfma_f32_16x16x32_bf16 v[80:83], v[168:171], v[200:203], v[80:83]
	v_mfma_f32_16x16x32_bf16 v[68:71], v[152:155], v[208:211], v[68:71]
	v_mfma_f32_16x16x32_bf16 v[64:67], v[168:171], v[208:211], v[64:67]
	s_setprio 0
	s_barrier
; #define PG8_STAGE(bufoff, gbase, voff) do { _Pragma("unroll") for (int _i = 0; _i < 2; ++_i) \
;         __builtin_amdgcn_global_load_lds((const unsigned*)((const char*)(gbase) + (voff)[_i]), (PG8_LAS unsigned*)(lds + (bufoff) + ldsw + _i * 8192), 16, 0, 0); } while (0)
; #define PG8_LDA(dst, b, h) do { _Pragma("unroll") for (int m = 0; m < 4; ++m) _Pragma("unroll") for (int k = 0; k < 2; ++k) dst[m][k] = *(const PG8_LAS bf16x8*)(lds + PG8_SA(b, h) + aoff + m * 2048 + k * 1024); } while (0)
; #define PG8_MMA(ai, bj, At, Bt) do { __builtin_amdgcn_s_setprio(1); _Pragma("unroll") for (int m = 0; m < 4; ++m) _Pragma("unroll") for (int n = 0; n < 2; ++n) _Pragma("unroll") for (int k = 0; k < 2; ++k) \
;         acc[ai][bj][m][n] = __builtin_amdgcn_mfma_f32_16x16x32_bf16(Bt[n][k], At[m][k], acc[ai][bj][m][n], 0, 0, 0); __builtin_amdgcn_s_setprio(0); } while (0)
; #define PG8_WAIT_V(n) asm volatile("s_waitcnt vmcnt(" #n ")" ::: "memory")
; #define PG8_WAIT_L(n) asm volatile("s_waitcnt lgkmcnt(" #n ")" ::: "memory")
; #define PG8_BAR __builtin_amdgcn_s_barrier()
; #define PG8_SCHED __builtin_amdgcn_sched_barrier(0)
; template <class Epi, class Sched, bool ALIGN_EPI = false, bool SP2 = false>
; __device__ __forceinline__ void gemm_phase(PG8_LAS unsigned char* lds, const Gemm g, const Sched& S, const Epi& E, const int tid_in) {
;     ...
;             PG8_LDA(At, 1, 1); PG8_STAGE(PG8_SB(1, 0), b3, voffB); PG8_STAGE(PG8_SB(1, 1), b3 + hstepB, voffB); PG8_STAGE(PG8_SA(1, 0), a3, voffA);
;             PG8_WAIT_V(8); PG8_WAIT_L(0); PG8_BAR; PG8_MMA(1, 0, At, B0); PG8_MMA(1, 1, At, B1); PG8_BAR; PG8_SCHED;
	s_add_i32 s40, s61, s42
	v_lshl_add_u64 v[180:181], v[180:181], 0, s[10:11]
	s_mov_b32 m0, s40
	ds_read_b128 v[172:175], v187 offset:49152
	ds_read_b128 v[176:179], v187 offset:50176
	ds_read_b128 v[188:191], v187 offset:51200
	ds_read_b128 v[192:195], v187 offset:52224
	ds_read_b128 v[196:199], v187 offset:53248
	ds_read_b128 v[200:203], v187 offset:54272
	ds_read_b128 v[204:207], v187 offset:55296
	ds_read_b128 v[208:211], v187 offset:56320
	global_load_lds_dwordx4 v[180:181], off
	s_add_i32 m0, s40, 0x2000
	s_add_u32 s38, s38, 0x40080
	v_lshl_add_u64 v[180:181], v[212:213], 0, s[10:11]
	s_addc_u32 s39, s39, 0
	s_add_i32 s40, s62, s42
	global_load_lds_dwordx4 v[180:181], off
	v_lshl_add_u64 v[180:181], s[38:39], 0, v[114:115]
	s_mov_b32 m0, s40
	s_nop 0
	global_load_lds_dwordx4 v[180:181], off
	v_lshl_add_u64 v[180:181], s[38:39], 0, v[158:159]
	s_add_i32 m0, s40, 0x2000
	s_nop 0
	global_load_lds_dwordx4 v[180:181], off
	v_lshl_add_u64 v[180:181], v[214:215], 0, s[10:11]
	s_mov_b32 m0, s53
	s_nop 0
	global_load_lds_dwordx4 v[180:181], off
	v_lshl_add_u64 v[180:181], v[216:217], 0, s[10:11]
	s_mov_b32 m0, s54
	s_nop 0
	global_load_lds_dwordx4 v[180:181], off
	s_waitcnt vmcnt(8)
	s_waitcnt lgkmcnt(0)
	s_barrier
	s_setprio 1
	s_waitcnt lgkmcnt(0)
	v_mfma_f32_16x16x32_bf16 v[60:63], v[132:135], v[172:175], v[60:63]
	v_mfma_f32_16x16x32_bf16 v[56:59], v[140:143], v[172:175], v[56:59]
	v_mfma_f32_16x16x32_bf16 v[44:47], v[132:135], v[188:191], v[44:47]
	v_mfma_f32_16x16x32_bf16 v[40:43], v[140:143], v[188:191], v[40:43]
	v_mfma_f32_16x16x32_bf16 v[28:31], v[132:135], v[196:199], v[28:31]
	v_mfma_f32_16x16x32_bf16 v[24:27], v[140:143], v[196:199], v[24:27]
	v_mfma_f32_16x16x32_bf16 v[12:15], v[132:135], v[204:207], v[12:15]
	v_mfma_f32_16x16x32_bf16 v[8:11], v[140:143], v[204:207], v[8:11]
	v_mfma_f32_16x16x32_bf16 v[60:63], v[136:139], v[176:179], v[60:63]
	v_mfma_f32_16x16x32_bf16 v[56:59], v[144:147], v[176:179], v[56:59]
	v_mfma_f32_16x16x32_bf16 v[44:47], v[136:139], v[192:195], v[44:47]
	v_mfma_f32_16x16x32_bf16 v[40:43], v[144:147], v[192:195], v[40:43]
	v_mfma_f32_16x16x32_bf16 v[28:31], v[136:139], v[200:203], v[28:31]
	v_mfma_f32_16x16x32_bf16 v[24:27], v[144:147], v[200:203], v[24:27]
	v_mfma_f32_16x16x32_bf16 v[12:15], v[136:139], v[208:211], v[12:15]
	v_mfma_f32_16x16x32_bf16 v[8:11], v[144:147], v[208:211], v[8:11]
	s_setprio 0
	s_setprio 1
	v_mfma_f32_16x16x32_bf16 v[52:55], v[148:151], v[172:175], v[52:55]
	v_mfma_f32_16x16x32_bf16 v[48:51], v[164:167], v[172:175], v[48:51]
	v_mfma_f32_16x16x32_bf16 v[36:39], v[148:151], v[188:191], v[36:39]
	v_mfma_f32_16x16x32_bf16 v[32:35], v[164:167], v[188:191], v[32:35]
	v_mfma_f32_16x16x32_bf16 v[20:23], v[148:151], v[196:199], v[20:23]
	v_mfma_f32_16x16x32_bf16 v[16:19], v[164:167], v[196:199], v[16:19]
	v_mfma_f32_16x16x32_bf16 v[4:7], v[148:151], v[204:207], v[4:7]
	v_mfma_f32_16x16x32_bf16 v[0:3], v[164:167], v[204:207], v[0:3]
	v_mfma_f32_16x16x32_bf16 v[52:55], v[152:155], v[176:179], v[52:55]
	v_mfma_f32_16x16x32_bf16 v[48:51], v[168:171], v[176:179], v[48:51]
	v_mfma_f32_16x16x32_bf16 v[36:39], v[152:155], v[192:195], v[36:39]
	v_mfma_f32_16x16x32_bf16 v[32:35], v[168:171], v[192:195], v[32:35]
	v_mfma_f32_16x16x32_bf16 v[20:23], v[152:155], v[200:203], v[20:23]
	v_mfma_f32_16x16x32_bf16 v[16:19], v[168:171], v[200:203], v[16:19]
	v_mfma_f32_16x16x32_bf16 v[4:7], v[152:155], v[208:211], v[4:7]
	v_mfma_f32_16x16x32_bf16 v[0:3], v[168:171], v[208:211], v[0:3]
	s_setprio 0
	s_barrier
	s_add_i32 s60, s60, 2
	s_add_u32 s6, s6, 0x100
	s_addc_u32 s7, s7, 0
	s_add_u32 s58, s58, 0x100
	s_addc_u32 s59, s59, 0
	s_cmp_gt_u32 s60, 13
	s_cbranch_scc0 .LBB0_856
	s_and_b64 vcc, exec, s[20:21]
	s_cbranch_vccz .LBB0_859
	s_barrier

;   __device__ __forceinline__ bool next(int i,AttnUnit&u)const{ const int p=vcu+(i>>1)*grid; if(p>=BATCH*NHEAD*4)return false; const int q=(p&31)+32*(p>>8), s=(q<32)?(q&3):(3-(q&3)); u.bh=((p>>5)&7)*NHEAD+((q<32)?(q>>2):(NHEAD-1-((q-32)>>2)));     u.qb=(i&1)?s:(NQB-1-s); u.reuse=i&1; return true; }
;     __host__ __device__ __forceinline__ bool next(int i, Unit& u) const {
;         const long L = (long)i * G + c; if (L >= nwg) return false;
;         int wgid = (int)L; { const int q = nwg / NXCD, r = nwg % NXCD, xcd = wgid % NXCD, off = wgid / NXCD; wgid = (xcd < r ? xcd * (q + 1) : r * (q + 1) + (xcd - r) * q) + off; }
;         const int nig = WGM * nN, gid = wgid / nig, fm = gid * WGM, gsz = (nM - fm) < WGM ? (nM - fm) : WGM;
;         u.pm = fm + ((wgid % nig) % gsz); u.pn = (wgid % nig) / gsz; return true;
; template <class Epi, class Sched, bool ALIGN_EPI = false, bool SP2 = false>
; __device__ __forceinline__ void gemm_phase(PG8_LAS unsigned char* lds, const Gemm g, const Sched& S, const Epi& E, const int tid_in) {
;     ...
;         const bool has_next = S.next(ui + 1, nxt);
.LBB0_967:
	s_add_i32 s70, s71, 1
	s_mul_i32 s9, s70, s3
	s_mul_hi_i32 s8, s70, s3
	s_add_u32 s14, s9, s2
	s_addc_u32 s15, s8, s33
	v_mov_b64_e32 v[140:141], 0x100
	v_cmp_lt_i64_e64 s[38:39], s[14:15], v[140:141]
	s_nop 3
	s_mov_b32 s100, s38
	v_mov_b64_e32 v[140:141], 0xff
	v_cmp_gt_i64_e64 s[8:9], s[14:15], v[140:141]
	s_and_b64 vcc, exec, s[8:9]
	s_cbranch_vccnz .LBB0_973
	s_ashr_i32 s15, s14, 31
	s_lshr_b32 s15, s15, 29
	s_add_i32 s28, s14, s15
	s_and_b32 s15, s28, -8
	s_sub_i32 s29, s14, s15
	s_cmp_gt_i32 s29, -1
	s_mov_b64 s[14:15], -1
	s_cbranch_scc0 .LBB0_970
	s_lshl_b32 s42, s29, 5
	s_mov_b64 s[14:15], 0

; #define PG8_STAGE(bufoff, gbase, voff) do { _Pragma("unroll") for (int _i = 0; _i < 2; ++_i) \
;         __builtin_amdgcn_global_load_lds((const unsigned*)((const char*)(gbase) + (voff)[_i]), (PG8_LAS unsigned*)(lds + (bufoff) + ldsw + _i * 8192), 16, 0, 0); } while (0)
; #define PG8_LDA(dst, b, h) do { _Pragma("unroll") for (int m = 0; m < 4; ++m) _Pragma("unroll") for (int k = 0; k < 2; ++k) dst[m][k] = *(const PG8_LAS bf16x8*)(lds + PG8_SA(b, h) + aoff + m * 2048 + k * 1024); } while (0)
; #define PG8_LDB(dst, b, h) do { _Pragma("unroll") for (int n = 0; n < 2; ++n) _Pragma("unroll") for (int k = 0; k < 2; ++k) dst[n][k] = *(const PG8_LAS bf16x8*)(lds + PG8_SB(b, h) + boff + n * 2048 + k * 1024); } while (0)
; #define PG8_MMA(ai, bj, At, Bt) do { __builtin_amdgcn_s_setprio(1); _Pragma("unroll") for (int m = 0; m < 4; ++m) _Pragma("unroll") for (int n = 0; n < 2; ++n) _Pragma("unroll") for (int k = 0; k < 2; ++k) \
;         acc[ai][bj][m][n] = __builtin_amdgcn_mfma_f32_16x16x32_bf16(Bt[n][k], At[m][k], acc[ai][bj][m][n], 0, 0, 0); __builtin_amdgcn_s_setprio(0); } while (0)
; #define PG8_WAIT_V(n) asm volatile("s_waitcnt vmcnt(" #n ")" ::: "memory")
; #define PG8_WAIT_L(n) asm volatile("s_waitcnt lgkmcnt(" #n ")" ::: "memory")
; #define PG8_BAR __builtin_amdgcn_s_barrier()
; #define PG8_SCHED __builtin_amdgcn_sched_barrier(0)
; template <class Epi, class Sched, bool ALIGN_EPI = false, bool SP2 = false>
; __device__ __forceinline__ void gemm_phase(PG8_LAS unsigned char* lds, const Gemm g, const Sched& S, const Epi& E, const int tid_in) {
;     ...
;             const bool last = (t == nt - 2);
;             const char* a1 = cA + (size_t)(t + 1) * kstep;
;             const char* a2 = last ? nA : cA + (size_t)(t + 2) * kstep; const char* b2 = last ? nB : cB + (size_t)(t + 2) * kstep;
;             const char* a3 = a2 + kstep; const char* b3 = b2 + kstep;
;             if (last && has_next) S.a_ready(nxt);
;             if constexpr (SP2) {
;             PG8_LDB(B0, 0, 0); PG8_LDB(B1, 0, 1); PG8_SCHED; PG8_LDA(At, 0, 0); PG8_STAGE(PG8_SA(1, 1), a1 + hstepA, voffA);
;             PG8_WAIT_V(8); PG8_WAIT_L(0); PG8_BAR; PG8_MMA(0, 0, At, B0); PG8_MMA(0, 1, At, B1); PG8_BAR; PG8_SCHED;
;             PG8_LDA(At, 0, 1); PG8_STAGE(PG8_SB(0, 0), b2, voffB); PG8_STAGE(PG8_SB(0, 1), b2 + hstepB, voffB); PG8_STAGE(PG8_SA(0, 0), a2, voffA);
.LBB0_974:
	s_add_u32 s54, s50, s40
	s_addc_u32 s55, s51, s41
	s_add_u32 s54, s54, 0x100
	s_addc_u32 s55, s55, 0
	s_add_u32 s75, s73, s40
	s_addc_u32 s76, s74, s41
	s_add_i32 s77, 0, 0x10000
	s_cmpk_eq_i32 s40, 0x1f00
	s_cselect_b32 s57, s14, s55
	s_cselect_b32 s56, s15, s54
	v_add_u32_e32 v155, s77, v149
	s_cselect_b32 s55, s29, s76
	s_cselect_b32 s54, s43, s75
	s_cmpk_lg_i32 s40, 0x1f00
	s_cbranch_scc1 .Ltail_keep_down
	s_cmp_lg_u32 s100, 0
	s_cbranch_scc1 .Ltail_keep_down
	v_mov_b32_e32 v114, 0
	v_mov_b32_e32 v112, 0
	v_mov_b32_e32 v132, 0
	v_mov_b32_e32 v134, 0
.Ltail_keep_down:
	s_add_i32 s75, 0, 0x14000
	ds_read_b128 v[144:147], v155
	ds_read_b128 v[156:159], v155 offset:1024
	ds_read_b128 v[160:163], v155 offset:2048
	ds_read_b128 v[164:167], v155 offset:3072
	v_add_u32_e32 v155, s75, v149
	ds_read_b128 v[168:171], v155
	ds_read_b128 v[172:175], v155 offset:1024
	ds_read_b128 v[176:179], v155 offset:2048
	ds_read_b128 v[180:183], v155 offset:3072
	v_lshl_add_u64 v[216:217], v[140:141], 0, s[40:41]
	s_add_i32 m0, s62, 0xc000
	ds_read_b128 v[184:187], v153
	ds_read_b128 v[188:191], v153 offset:1024
	ds_read_b128 v[192:195], v153 offset:2048
	ds_read_b128 v[196:199], v153 offset:3072
	ds_read_b128 v[200:203], v153 offset:4096
	ds_read_b128 v[204:207], v153 offset:5120
	ds_read_b128 v[208:211], v153 offset:6144
	ds_read_b128 v[212:215], v153 offset:7168
	global_load_lds_dwordx4 v[216:217], off
	v_lshl_add_u64 v[216:217], v[142:143], 0, s[40:41]
	s_add_i32 m0, s62, 0xe000
	s_nop 0
	global_load_lds_dwordx4 v[216:217], off
	s_waitcnt vmcnt(8)
	s_waitcnt lgkmcnt(0)
	s_barrier
	s_setprio 1
	s_waitcnt lgkmcnt(0)
	v_mfma_f32_16x16x32_bf16 v[0:3], v[144:147], v[184:187], v[0:3]
	v_mfma_f32_16x16x32_bf16 v[4:7], v[160:163], v[184:187], v[4:7]
	v_mfma_f32_16x16x32_bf16 v[16:19], v[144:147], v[192:195], v[16:19]
	v_mfma_f32_16x16x32_bf16 v[20:23], v[160:163], v[192:195], v[20:23]
	v_mfma_f32_16x16x32_bf16 v[32:35], v[144:147], v[200:203], v[32:35]
	v_mfma_f32_16x16x32_bf16 v[36:39], v[160:163], v[200:203], v[36:39]
	v_mfma_f32_16x16x32_bf16 v[48:51], v[144:147], v[208:211], v[48:51]
	v_mfma_f32_16x16x32_bf16 v[52:55], v[160:163], v[208:211], v[52:55]
	v_mfma_f32_16x16x32_bf16 v[0:3], v[156:159], v[188:191], v[0:3]
	v_mfma_f32_16x16x32_bf16 v[4:7], v[164:167], v[188:191], v[4:7]
	v_mfma_f32_16x16x32_bf16 v[16:19], v[156:159], v[196:199], v[16:19]
	v_mfma_f32_16x16x32_bf16 v[20:23], v[164:167], v[196:199], v[20:23]
	v_mfma_f32_16x16x32_bf16 v[32:35], v[156:159], v[204:207], v[32:35]
	v_mfma_f32_16x16x32_bf16 v[36:39], v[164:167], v[204:207], v[36:39]
	v_mfma_f32_16x16x32_bf16 v[48:51], v[156:159], v[212:215], v[48:51]
	v_mfma_f32_16x16x32_bf16 v[52:55], v[164:167], v[212:215], v[52:55]
	s_setprio 0
	s_setprio 1
	v_mfma_f32_16x16x32_bf16 v[8:11], v[168:171], v[184:187], v[8:11]
	v_mfma_f32_16x16x32_bf16 v[12:15], v[176:179], v[184:187], v[12:15]
	v_mfma_f32_16x16x32_bf16 v[24:27], v[168:171], v[192:195], v[24:27]
	v_mfma_f32_16x16x32_bf16 v[28:31], v[176:179], v[192:195], v[28:31]
	v_mfma_f32_16x16x32_bf16 v[40:43], v[168:171], v[200:203], v[40:43]
	v_mfma_f32_16x16x32_bf16 v[44:47], v[176:179], v[200:203], v[44:47]
	v_mfma_f32_16x16x32_bf16 v[56:59], v[168:171], v[208:211], v[56:59]
	v_mfma_f32_16x16x32_bf16 v[60:63], v[176:179], v[208:211], v[60:63]
	v_mfma_f32_16x16x32_bf16 v[8:11], v[172:175], v[188:191], v[8:11]
	v_mfma_f32_16x16x32_bf16 v[12:15], v[180:183], v[188:191], v[12:15]
	v_mfma_f32_16x16x32_bf16 v[24:27], v[172:175], v[196:199], v[24:27]
	v_mfma_f32_16x16x32_bf16 v[28:31], v[180:183], v[196:199], v[28:31]
	v_mfma_f32_16x16x32_bf16 v[40:43], v[172:175], v[204:207], v[40:43]
	v_mfma_f32_16x16x32_bf16 v[44:47], v[180:183], v[204:207], v[44:47]
	v_mfma_f32_16x16x32_bf16 v[56:59], v[172:175], v[212:215], v[56:59]
	v_mfma_f32_16x16x32_bf16 v[60:63], v[180:183], v[212:215], v[60:63]
	s_setprio 0
	s_barrier
	s_add_i32 s76, s77, s48
	v_lshl_add_u64 v[216:217], s[54:55], 0, v[114:115]
	s_mov_b32 m0, s76
	ds_read_b128 v[184:187], v153 offset:16384
	ds_read_b128 v[188:191], v153 offset:17408
	ds_read_b128 v[192:195], v153 offset:18432
	ds_read_b128 v[196:199], v153 offset:19456
	ds_read_b128 v[200:203], v153 offset:20480
	ds_read_b128 v[204:207], v153 offset:21504
	ds_read_b128 v[208:211], v153 offset:22528
	ds_read_b128 v[212:215], v153 offset:23552
	global_load_lds_dwordx4 v[216:217], off
	s_add_i32 m0, s76, 0x2000
	s_add_u32 s76, s54, 0x100000
	v_lshl_add_u64 v[218:219], s[54:55], 0, v[112:113]
	s_addc_u32 s77, s55, 0
	s_add_i32 s75, s75, s48
	global_load_lds_dwordx4 v[218:219], off
	v_lshl_add_u64 v[220:221], s[76:77], 0, v[114:115]
	s_mov_b32 m0, s75
	v_lshl_add_u64 v[222:223], s[56:57], 0, v[132:133]
	global_load_lds_dwordx4 v[220:221], off
	v_lshl_add_u64 v[220:221], s[76:77], 0, v[112:113]
	s_add_i32 m0, s75, 0x2000
	s_nop 0
	global_load_lds_dwordx4 v[220:221], off
	v_lshl_add_u64 v[220:221], s[56:57], 0, v[134:135]
	s_mov_b32 m0, s62
	s_nop 0
	global_load_lds_dwordx4 v[220:221], off
	s_mov_b32 m0, s63
	s_nop 0
	global_load_lds_dwordx4 v[222:223], off
	s_waitcnt vmcnt(8)
	s_waitcnt lgkmcnt(0)
	s_barrier
; #define PG8_STAGE(bufoff, gbase, voff) do { _Pragma("unroll") for (int _i = 0; _i < 2; ++_i) \
;         __builtin_amdgcn_global_load_lds((const unsigned*)((const char*)(gbase) + (voff)[_i]), (PG8_LAS unsigned*)(lds + (bufoff) + ldsw + _i * 8192), 16, 0, 0); } while (0)
; #define PG8_LDA(dst, b, h) do { _Pragma("unroll") for (int m = 0; m < 4; ++m) _Pragma("unroll") for (int k = 0; k < 2; ++k) dst[m][k] = *(const PG8_LAS bf16x8*)(lds + PG8_SA(b, h) + aoff + m * 2048 + k * 1024); } while (0)
; #define PG8_LDB(dst, b, h) do { _Pragma("unroll") for (int n = 0; n < 2; ++n) _Pragma("unroll") for (int k = 0; k < 2; ++k) dst[n][k] = *(const PG8_LAS bf16x8*)(lds + PG8_SB(b, h) + boff + n * 2048 + k * 1024); } while (0)
; #define PG8_MMA(ai, bj, At, Bt) do { __builtin_amdgcn_s_setprio(1); _Pragma("unroll") for (int m = 0; m < 4; ++m) _Pragma("unroll") for (int n = 0; n < 2; ++n) _Pragma("unroll") for (int k = 0; k < 2; ++k) \
;         acc[ai][bj][m][n] = __builtin_amdgcn_mfma_f32_16x16x32_bf16(Bt[n][k], At[m][k], acc[ai][bj][m][n], 0, 0, 0); __builtin_amdgcn_s_setprio(0); } while (0)
; #define PG8_WAIT_V(n) asm volatile("s_waitcnt vmcnt(" #n ")" ::: "memory")
; #define PG8_WAIT_L(n) asm volatile("s_waitcnt lgkmcnt(" #n ")" ::: "memory")
; #define PG8_BAR __builtin_amdgcn_s_barrier()
; #define PG8_SCHED __builtin_amdgcn_sched_barrier(0)
; template <class Epi, class Sched, bool ALIGN_EPI = false, bool SP2 = false>
; __device__ __forceinline__ void gemm_phase(PG8_LAS unsigned char* lds, const Gemm g, const Sched& S, const Epi& E, const int tid_in) {
;     ...
;             PG8_WAIT_V(8); PG8_WAIT_L(0); PG8_BAR; PG8_MMA(1, 0, At, B0); PG8_MMA(1, 1, At, B1); PG8_BAR; PG8_SCHED;
;             PG8_LDB(B0, 1, 0); PG8_LDB(B1, 1, 1); PG8_SCHED; PG8_LDA(At, 1, 0); PG8_STAGE(PG8_SA(0, 1), a2 + hstepA, voffA);
;             PG8_WAIT_V(8); PG8_WAIT_L(0); PG8_BAR; PG8_MMA(0, 0, At, B0); PG8_MMA(0, 1, At, B1); PG8_BAR; PG8_SCHED;
	s_setprio 1
	s_waitcnt lgkmcnt(0)
	v_mfma_f32_16x16x32_bf16 v[64:67], v[144:147], v[184:187], v[64:67]
	v_mfma_f32_16x16x32_bf16 v[68:71], v[160:163], v[184:187], v[68:71]
	v_mfma_f32_16x16x32_bf16 v[80:83], v[144:147], v[192:195], v[80:83]
	v_mfma_f32_16x16x32_bf16 v[84:87], v[160:163], v[192:195], v[84:87]
	v_mfma_f32_16x16x32_bf16 v[96:99], v[144:147], v[200:203], v[96:99]
	v_mfma_f32_16x16x32_bf16 v[100:103], v[160:163], v[200:203], v[100:103]
	v_mfma_f32_16x16x32_bf16 v[116:119], v[144:147], v[208:211], v[116:119]
	v_mfma_f32_16x16x32_bf16 v[120:123], v[160:163], v[208:211], v[120:123]
	v_mfma_f32_16x16x32_bf16 v[64:67], v[156:159], v[188:191], v[64:67]
	v_mfma_f32_16x16x32_bf16 v[68:71], v[164:167], v[188:191], v[68:71]
	v_mfma_f32_16x16x32_bf16 v[80:83], v[156:159], v[196:199], v[80:83]
	v_mfma_f32_16x16x32_bf16 v[84:87], v[164:167], v[196:199], v[84:87]
	v_mfma_f32_16x16x32_bf16 v[96:99], v[156:159], v[204:207], v[96:99]
	v_mfma_f32_16x16x32_bf16 v[100:103], v[164:167], v[204:207], v[100:103]
	v_mfma_f32_16x16x32_bf16 v[116:119], v[156:159], v[212:215], v[116:119]
	v_mfma_f32_16x16x32_bf16 v[120:123], v[164:167], v[212:215], v[120:123]
	s_setprio 0
	s_setprio 1
	v_mfma_f32_16x16x32_bf16 v[72:75], v[168:171], v[184:187], v[72:75]
	v_mfma_f32_16x16x32_bf16 v[76:79], v[176:179], v[184:187], v[76:79]
	v_mfma_f32_16x16x32_bf16 v[88:91], v[168:171], v[192:195], v[88:91]
	v_mfma_f32_16x16x32_bf16 v[92:95], v[176:179], v[192:195], v[92:95]
	v_mfma_f32_16x16x32_bf16 v[104:107], v[168:171], v[200:203], v[104:107]
	v_mfma_f32_16x16x32_bf16 v[108:111], v[176:179], v[200:203], v[108:111]
	v_mfma_f32_16x16x32_bf16 v[124:127], v[168:171], v[208:211], v[124:127]
	v_mfma_f32_16x16x32_bf16 v[128:131], v[176:179], v[208:211], v[128:131]
	v_mfma_f32_16x16x32_bf16 v[72:75], v[172:175], v[188:191], v[72:75]
	v_mfma_f32_16x16x32_bf16 v[76:79], v[180:183], v[188:191], v[76:79]
	v_mfma_f32_16x16x32_bf16 v[88:91], v[172:175], v[196:199], v[88:91]
	v_mfma_f32_16x16x32_bf16 v[92:95], v[180:183], v[196:199], v[92:95]
	v_mfma_f32_16x16x32_bf16 v[104:107], v[172:175], v[204:207], v[104:107]
	v_mfma_f32_16x16x32_bf16 v[108:111], v[180:183], v[204:207], v[108:111]
	v_mfma_f32_16x16x32_bf16 v[124:127], v[172:175], v[212:215], v[124:127]
	v_mfma_f32_16x16x32_bf16 v[128:131], v[180:183], v[212:215], v[128:131]
	s_setprio 0
	s_barrier
	s_add_i32 s75, 0, 0x18000
	v_add_u32_e32 v155, s75, v149
	s_add_i32 s76, 0, 0x1c000
	ds_read_b128 v[144:147], v155
	ds_read_b128 v[156:159], v155 offset:1024
	ds_read_b128 v[160:163], v155 offset:2048
	ds_read_b128 v[164:167], v155 offset:3072
	v_add_u32_e32 v155, s76, v149
	ds_read_b128 v[168:171], v155
	ds_read_b128 v[172:175], v155 offset:1024
	ds_read_b128 v[176:179], v155 offset:2048
	ds_read_b128 v[180:183], v155 offset:3072
	s_add_u32 s56, s56, 0x100000
	s_addc_u32 s57, s57, 0
	s_mov_b32 m0, s64
	v_lshl_add_u64 v[224:225], s[56:57], 0, v[134:135]
	ds_read_b128 v[184:187], v153 offset:32768
	ds_read_b128 v[188:191], v153 offset:33792
	ds_read_b128 v[192:195], v153 offset:34816
	ds_read_b128 v[196:199], v153 offset:35840
	ds_read_b128 v[200:203], v153 offset:36864
	ds_read_b128 v[204:207], v153 offset:37888
	ds_read_b128 v[208:211], v153 offset:38912
	ds_read_b128 v[212:215], v153 offset:39936
	global_load_lds_dwordx4 v[224:225], off
	v_lshl_add_u64 v[224:225], s[56:57], 0, v[132:133]
	s_mov_b32 m0, s65
	s_nop 0
	global_load_lds_dwordx4 v[224:225], off
	s_waitcnt vmcnt(8)
	s_waitcnt lgkmcnt(0)
	s_barrier
	s_setprio 1
	s_waitcnt lgkmcnt(0)
	v_mfma_f32_16x16x32_bf16 v[0:3], v[144:147], v[184:187], v[0:3]
	v_mfma_f32_16x16x32_bf16 v[4:7], v[160:163], v[184:187], v[4:7]
	v_mfma_f32_16x16x32_bf16 v[16:19], v[144:147], v[192:195], v[16:19]
	v_mfma_f32_16x16x32_bf16 v[20:23], v[160:163], v[192:195], v[20:23]
	v_mfma_f32_16x16x32_bf16 v[32:35], v[144:147], v[200:203], v[32:35]
	v_mfma_f32_16x16x32_bf16 v[36:39], v[160:163], v[200:203], v[36:39]
	v_mfma_f32_16x16x32_bf16 v[48:51], v[144:147], v[208:211], v[48:51]
	v_mfma_f32_16x16x32_bf16 v[52:55], v[160:163], v[208:211], v[52:55]
	v_mfma_f32_16x16x32_bf16 v[0:3], v[156:159], v[188:191], v[0:3]
	v_mfma_f32_16x16x32_bf16 v[4:7], v[164:167], v[188:191], v[4:7]
	v_mfma_f32_16x16x32_bf16 v[16:19], v[156:159], v[196:199], v[16:19]
	v_mfma_f32_16x16x32_bf16 v[20:23], v[164:167], v[196:199], v[20:23]
	v_mfma_f32_16x16x32_bf16 v[32:35], v[156:159], v[204:207], v[32:35]
	v_mfma_f32_16x16x32_bf16 v[36:39], v[164:167], v[204:207], v[36:39]
	v_mfma_f32_16x16x32_bf16 v[48:51], v[156:159], v[212:215], v[48:51]
	v_mfma_f32_16x16x32_bf16 v[52:55], v[164:167], v[212:215], v[52:55]
	s_setprio 0
	s_setprio 1
	v_mfma_f32_16x16x32_bf16 v[8:11], v[168:171], v[184:187], v[8:11]
	v_mfma_f32_16x16x32_bf16 v[12:15], v[176:179], v[184:187], v[12:15]
	v_mfma_f32_16x16x32_bf16 v[24:27], v[168:171], v[192:195], v[24:27]
	v_mfma_f32_16x16x32_bf16 v[28:31], v[176:179], v[192:195], v[28:31]
	v_mfma_f32_16x16x32_bf16 v[40:43], v[168:171], v[200:203], v[40:43]
	v_mfma_f32_16x16x32_bf16 v[44:47], v[176:179], v[200:203], v[44:47]
	v_mfma_f32_16x16x32_bf16 v[56:59], v[168:171], v[208:211], v[56:59]
	v_mfma_f32_16x16x32_bf16 v[60:63], v[176:179], v[208:211], v[60:63]
	v_mfma_f32_16x16x32_bf16 v[8:11], v[172:175], v[188:191], v[8:11]
	v_mfma_f32_16x16x32_bf16 v[12:15], v[180:183], v[188:191], v[12:15]
	v_mfma_f32_16x16x32_bf16 v[24:27], v[172:175], v[196:199], v[24:27]
	v_mfma_f32_16x16x32_bf16 v[28:31], v[180:183], v[196:199], v[28:31]
	v_mfma_f32_16x16x32_bf16 v[40:43], v[172:175], v[204:207], v[40:43]
	v_mfma_f32_16x16x32_bf16 v[44:47], v[180:183], v[204:207], v[44:47]
	v_mfma_f32_16x16x32_bf16 v[56:59], v[172:175], v[212:215], v[56:59]
	v_mfma_f32_16x16x32_bf16 v[60:63], v[180:183], v[212:215], v[60:63]
	s_setprio 0
	s_barrier
; #define PG8_STAGE(bufoff, gbase, voff) do { _Pragma("unroll") for (int _i = 0; _i < 2; ++_i) \
;         __builtin_amdgcn_global_load_lds((const unsigned*)((const char*)(gbase) + (voff)[_i]), (PG8_LAS unsigned*)(lds + (bufoff) + ldsw + _i * 8192), 16, 0, 0); } while (0)
; #define PG8_LDA(dst, b, h) do { _Pragma("unroll") for (int m = 0; m < 4; ++m) _Pragma("unroll") for (int k = 0; k < 2; ++k) dst[m][k] = *(const PG8_LAS bf16x8*)(lds + PG8_SA(b, h) + aoff + m * 2048 + k * 1024); } while (0)
; #define PG8_MMA(ai, bj, At, Bt) do { __builtin_amdgcn_s_setprio(1); _Pragma("unroll") for (int m = 0; m < 4; ++m) _Pragma("unroll") for (int n = 0; n < 2; ++n) _Pragma("unroll") for (int k = 0; k < 2; ++k) \
;         acc[ai][bj][m][n] = __builtin_amdgcn_mfma_f32_16x16x32_bf16(Bt[n][k], At[m][k], acc[ai][bj][m][n], 0, 0, 0); __builtin_amdgcn_s_setprio(0); } while (0)
; #define PG8_WAIT_V(n) asm volatile("s_waitcnt vmcnt(" #n ")" ::: "memory")
; #define PG8_WAIT_L(n) asm volatile("s_waitcnt lgkmcnt(" #n ")" ::: "memory")
; #define PG8_BAR __builtin_amdgcn_s_barrier()
; #define PG8_SCHED __builtin_amdgcn_sched_barrier(0)
; template <class Epi, class Sched, bool ALIGN_EPI = false, bool SP2 = false>
; __device__ __forceinline__ void gemm_phase(PG8_LAS unsigned char* lds, const Gemm g, const Sched& S, const Epi& E, const int tid_in) {
;     ...
;             PG8_LDA(At, 1, 1); PG8_STAGE(PG8_SB(1, 0), b3, voffB); PG8_STAGE(PG8_SB(1, 1), b3 + hstepB, voffB); PG8_STAGE(PG8_SA(1, 0), a3, voffA);
;             PG8_WAIT_V(8); PG8_WAIT_L(0); PG8_BAR; PG8_MMA(1, 0, At, B0); PG8_MMA(1, 1, At, B1); PG8_BAR; PG8_SCHED;
	s_add_i32 s56, s75, s48
	v_lshl_add_u64 v[216:217], v[216:217], 0, s[10:11]
	s_mov_b32 m0, s56
	ds_read_b128 v[184:187], v153 offset:49152
	ds_read_b128 v[188:191], v153 offset:50176
	ds_read_b128 v[192:195], v153 offset:51200
	ds_read_b128 v[196:199], v153 offset:52224
	ds_read_b128 v[200:203], v153 offset:53248
	ds_read_b128 v[204:207], v153 offset:54272
	ds_read_b128 v[208:211], v153 offset:55296
	ds_read_b128 v[212:215], v153 offset:56320
	global_load_lds_dwordx4 v[216:217], off
	s_add_i32 m0, s56, 0x2000
	s_add_u32 s54, s54, 0x100080
	v_lshl_add_u64 v[216:217], v[218:219], 0, s[10:11]
	s_addc_u32 s55, s55, 0
	s_add_i32 s56, s76, s48
	global_load_lds_dwordx4 v[216:217], off
	v_lshl_add_u64 v[216:217], s[54:55], 0, v[114:115]
	s_mov_b32 m0, s56
	s_nop 0
	global_load_lds_dwordx4 v[216:217], off
	v_lshl_add_u64 v[216:217], s[54:55], 0, v[112:113]
	s_add_i32 m0, s56, 0x2000
	s_nop 0
	global_load_lds_dwordx4 v[216:217], off
	v_lshl_add_u64 v[216:217], v[220:221], 0, s[10:11]
	s_mov_b32 m0, s66
	s_nop 0
	global_load_lds_dwordx4 v[216:217], off
	v_lshl_add_u64 v[216:217], v[222:223], 0, s[10:11]
	s_mov_b32 m0, s67
	s_nop 0
	global_load_lds_dwordx4 v[216:217], off
	s_waitcnt vmcnt(8)
	s_waitcnt lgkmcnt(0)
	s_barrier
	s_setprio 1
	s_waitcnt lgkmcnt(0)
	v_mfma_f32_16x16x32_bf16 v[64:67], v[144:147], v[184:187], v[64:67]
	v_mfma_f32_16x16x32_bf16 v[68:71], v[160:163], v[184:187], v[68:71]
	v_mfma_f32_16x16x32_bf16 v[80:83], v[144:147], v[192:195], v[80:83]
	v_mfma_f32_16x16x32_bf16 v[84:87], v[160:163], v[192:195], v[84:87]
	v_mfma_f32_16x16x32_bf16 v[96:99], v[144:147], v[200:203], v[96:99]
	v_mfma_f32_16x16x32_bf16 v[100:103], v[160:163], v[200:203], v[100:103]
	v_mfma_f32_16x16x32_bf16 v[116:119], v[144:147], v[208:211], v[116:119]
	v_mfma_f32_16x16x32_bf16 v[120:123], v[160:163], v[208:211], v[120:123]
	v_mfma_f32_16x16x32_bf16 v[64:67], v[156:159], v[188:191], v[64:67]
	v_mfma_f32_16x16x32_bf16 v[68:71], v[164:167], v[188:191], v[68:71]
	v_mfma_f32_16x16x32_bf16 v[80:83], v[156:159], v[196:199], v[80:83]
	v_mfma_f32_16x16x32_bf16 v[84:87], v[164:167], v[196:199], v[84:87]
	v_mfma_f32_16x16x32_bf16 v[96:99], v[156:159], v[204:207], v[96:99]
	v_mfma_f32_16x16x32_bf16 v[100:103], v[164:167], v[204:207], v[100:103]
	v_mfma_f32_16x16x32_bf16 v[116:119], v[156:159], v[212:215], v[116:119]
	v_mfma_f32_16x16x32_bf16 v[120:123], v[164:167], v[212:215], v[120:123]
	s_setprio 0
	s_setprio 1
	v_mfma_f32_16x16x32_bf16 v[72:75], v[168:171], v[184:187], v[72:75]
	v_mfma_f32_16x16x32_bf16 v[76:79], v[176:179], v[184:187], v[76:79]
	v_mfma_f32_16x16x32_bf16 v[88:91], v[168:171], v[192:195], v[88:91]
	v_mfma_f32_16x16x32_bf16 v[92:95], v[176:179], v[192:195], v[92:95]
	v_mfma_f32_16x16x32_bf16 v[104:107], v[168:171], v[200:203], v[104:107]
	v_mfma_f32_16x16x32_bf16 v[108:111], v[176:179], v[200:203], v[108:111]
	v_mfma_f32_16x16x32_bf16 v[124:127], v[168:171], v[208:211], v[124:127]
	v_mfma_f32_16x16x32_bf16 v[128:131], v[176:179], v[208:211], v[128:131]
	v_mfma_f32_16x16x32_bf16 v[72:75], v[172:175], v[188:191], v[72:75]
	v_mfma_f32_16x16x32_bf16 v[76:79], v[180:183], v[188:191], v[76:79]
	v_mfma_f32_16x16x32_bf16 v[88:91], v[172:175], v[196:199], v[88:91]
	v_mfma_f32_16x16x32_bf16 v[92:95], v[180:183], v[196:199], v[92:95]
	v_mfma_f32_16x16x32_bf16 v[104:107], v[172:175], v[204:207], v[104:107]
	v_mfma_f32_16x16x32_bf16 v[108:111], v[180:183], v[204:207], v[108:111]
	v_mfma_f32_16x16x32_bf16 v[124:127], v[172:175], v[212:215], v[124:127]
	v_mfma_f32_16x16x32_bf16 v[128:131], v[180:183], v[212:215], v[128:131]
	s_setprio 0
	s_barrier
	s_add_i32 s53, s53, 2
	s_add_u32 s40, s40, 0x100
	s_addc_u32 s41, s41, 0
	s_cmp_gt_u32 s53, 61
	s_cbranch_scc0 .LBB0_974
	s_and_b64 vcc, exec, s[24:25]
	s_cbranch_vccz .LBB0_977
	s_barrier

; __global__ void __launch_bounds__(NWAVES * 64, 2) mk_fwd(Args args) {
	.amdhsa_kernel _Z6mk_fwd4Args
		.amdhsa_group_segment_fixed_size 0
		.amdhsa_private_segment_fixed_size 0
		.amdhsa_kernarg_size 408
		.amdhsa_user_sgpr_count 2
		.amdhsa_user_sgpr_dispatch_ptr 0
		.amdhsa_user_sgpr_queue_ptr 0
		.amdhsa_user_sgpr_kernarg_segment_ptr 1
		.amdhsa_user_sgpr_dispatch_id 0
		.amdhsa_user_sgpr_kernarg_preload_length 0
		.amdhsa_user_sgpr_kernarg_preload_offset 0
		.amdhsa_user_sgpr_private_segment_size 0
		.amdhsa_uses_dynamic_stack 0
		.amdhsa_enable_private_segment 0
		.amdhsa_system_sgpr_workgroup_id_x 1
		.amdhsa_system_sgpr_workgroup_id_y 0
		.amdhsa_system_sgpr_workgroup_id_z 0
		.amdhsa_system_sgpr_workgroup_info 0
		.amdhsa_system_vgpr_workitem_id 2
		.amdhsa_next_free_vgpr 256
		.amdhsa_next_free_sgpr 102
		.amdhsa_accum_offset 256
		.amdhsa_reserve_vcc 1
		.amdhsa_float_round_mode_32 0
		.amdhsa_float_round_mode_16_64 0
		.amdhsa_float_denorm_mode_32 3
		.amdhsa_float_denorm_mode_16_64 3
		.amdhsa_dx10_clamp 1
		.amdhsa_ieee_mode 1
		.amdhsa_fp16_overflow 0
		.amdhsa_tg_split 0
		.amdhsa_exception_fp_ieee_invalid_op 0
		.amdhsa_exception_fp_denorm_src 0
		.amdhsa_exception_fp_ieee_div_zero 0
		.amdhsa_exception_fp_ieee_overflow 0
		.amdhsa_exception_fp_ieee_underflow 0
		.amdhsa_exception_fp_ieee_inexact 0
		.amdhsa_exception_int_div_zero 0
	.end_amdhsa_kernel

; __global__ void __launch_bounds__(NWAVES * 64, 2) mk_fwd(Args args) {
amdhsa.kernels:
  - .agpr_count:     0
    .args:
      - .offset:         0
        .size:           152
        .value_kind:     by_value
      - .offset:         152
        .size:           4
        .value_kind:     hidden_block_count_x
      - .offset:         156
        .size:           4
        .value_kind:     hidden_block_count_y
      - .offset:         160
        .size:           4
        .value_kind:     hidden_block_count_z
      - .offset:         164
        .size:           2
        .value_kind:     hidden_group_size_x
      - .offset:         166
        .size:           2
        .value_kind:     hidden_group_size_y
      - .offset:         168
        .size:           2
        .value_kind:     hidden_group_size_z
      - .offset:         170
        .size:           2
        .value_kind:     hidden_remainder_x
      - .offset:         172
        .size:           2
        .value_kind:     hidden_remainder_y
      - .offset:         174
        .size:           2
        .value_kind:     hidden_remainder_z
      - .offset:         192
        .size:           8
        .value_kind:     hidden_global_offset_x
      - .offset:         200
        .size:           8
        .value_kind:     hidden_global_offset_y
      - .offset:         208
        .size:           8
        .value_kind:     hidden_global_offset_z
      - .offset:         216
        .size:           2
        .value_kind:     hidden_grid_dims
      - .offset:         240
        .size:           8
        .value_kind:     hidden_multigrid_sync_arg
      - .offset:         272
        .size:           4
        .value_kind:     hidden_dynamic_lds_size
    .group_segment_fixed_size: 0
    .kernarg_segment_align: 8
    .kernarg_segment_size: 408
    .language:       OpenCL C
    .language_version:
      - 2
      - 0
    .max_flat_workgroup_size: 512
    .name:           _Z6mk_fwd4Args
    .private_segment_fixed_size: 0
    .sgpr_count:     108
    .sgpr_spill_count: 150
    .symbol:         _Z6mk_fwd4Args.kd
    .uniform_work_group_size: 1
    .uses_dynamic_stack: false
    .vgpr_count:     256
    .vgpr_spill_count: 0
    .wavefront_size: 64
